# adaLN RMSNorm of the next sub-layer fused into all five residual-GEMM epilogues (sibling exchange of row sums); modpass phases only keep the 512 ctx rows, L1 mod2 + its barrier removed
# speedup vs baseline: 1.0172x; 1.0172x over previous
; __device__ __forceinline__ void prologue(const kptr_t kp, LAS float* scr, int gw, int NGW, int lane) {
;     ...
;             const int id = r * 64 + lane, pos = id >> 4, j = id & 15; const int p = pos < 256 ? pos : pos - 256;
;             const float freq = powf(10000.0f, -(float)j / 16.0f); const float ang = (float)p * freq;
.LBB0_5:
	s_or_b64 exec, exec, s[4:5]
	s_mov_b64 s[36:37], s[0:1]
	v_mov_b32_e32 v1, v206
	s_lshl_b32 s33, s2, 3
	v_readfirstlane_b32 s3, v1
	s_ashr_i32 s4, s3, 6
	s_add_i32 s3, s4, s33
	s_lshl_b32 s28, s30, 3
	s_load_dwordx2 s[100:101], s[0:1], 0xb8
	s_lshl_b32 s99, s3, 10
	v_and_b32_e32 v2, 63, v206
	v_lshlrev_b32_e32 v2, 4, v2
	v_add_u32_e32 v2, s99, v2
	v_mov_b32_e32 v4, 0
	v_mov_b32_e32 v5, 0
	v_mov_b32_e32 v6, 0
	v_mov_b32_e32 v7, 0
	s_waitcnt lgkmcnt(0)
	s_add_u32 s100, s100, 0x3120000
	s_addc_u32 s101, s101, 0
	s_cmp_lt_u32 s3, 896
	s_cbranch_scc0 .Lzero_skip
	global_store_dwordx4 v2, v[4:7], s[100:101]
.Lzero_skip:
	s_cmpk_gt_i32 s3, 0x79cf
	s_cbranch_scc1 .LBB0_92
	v_and_b32_e32 v2, 15, v1
	v_cvt_f32_ubyte0_e32 v2, v2
	v_mul_f32_e32 v16, 0xbd800000, v2
	v_mov_b32_e32 v2, 0x461c4000
	v_cmp_eq_f32_e32 vcc, 0, v16
	s_lshl_b32 s4, s4, 14
	s_add_i32 s6, s4, 0
	v_cndmask_b32_e64 v12, v2, 1.0, vcc
	v_frexp_mant_f32_e32 v2, v12
	s_mov_b32 s4, 0x3f2aaaab
	v_cmp_gt_f32_e64 s[4:5], s4, v2
	s_movk_i32 s7, 0x204
	s_mov_b32 s9, 0x42b17218
	v_cndmask_b32_e64 v3, 1.0, 2.0, s[4:5]
	v_mul_f32_e32 v2, v2, v3
	v_add_f32_e32 v5, 1.0, v2
	v_rcp_f32_e32 v10, v5
	v_add_f32_e32 v3, -1.0, v5
	v_sub_f32_e32 v7, v2, v3
	v_add_f32_e32 v3, -1.0, v2
	v_mul_f32_e32 v11, v3, v10
	v_mul_f32_e32 v4, v5, v11
	v_fma_f32 v6, v11, v5, -v4
	v_fmac_f32_e32 v6, v11, v7
	v_add_f32_e32 v2, v4, v6
	v_sub_f32_e32 v5, v3, v2
	v_pk_add_f32 v[8:9], v[2:3], v[4:5] neg_lo:[0,1] neg_hi:[0,1]
	v_mov_b32_e32 v7, v2
	v_pk_add_f32 v[2:3], v[8:9], v[6:7] neg_lo:[0,1] neg_hi:[0,1]
	v_mov_b32_e32 v6, 0x3e91f4c4
	v_add_f32_e32 v2, v2, v3
	v_add_f32_e32 v2, v5, v2
	v_mul_f32_e32 v3, v10, v2
	v_add_f32_e32 v2, v11, v3
	v_sub_f32_e32 v4, v2, v11
	v_sub_f32_e32 v13, v3, v4
	v_mul_f32_e32 v3, v2, v2
	v_fma_f32 v5, v2, v2, -v3
	v_add_f32_e32 v4, v13, v13
	v_fmac_f32_e32 v5, v2, v4
	v_add_f32_e32 v4, v3, v5
	v_fmac_f32_e32 v6, 0x3e76c4e1, v4
	v_fmaak_f32 v6, v4, v6, 0x3ecccdef
	v_sub_f32_e32 v3, v4, v3
	v_sub_f32_e32 v14, v5, v3
	v_mul_f32_e32 v3, v4, v6
	v_fma_f32 v5, v4, v6, -v3
	v_fmac_f32_e32 v5, v14, v6
	v_add_f32_e32 v6, v3, v5
	v_add_f32_e32 v7, 0x3f2aaaaa, v6
	v_sub_f32_e32 v3, v6, v3
	v_sub_f32_e32 v3, v5, v3
	v_add_f32_e32 v5, 0xbf2aaaaa, v7
	v_add_f32_e32 v3, 0x31739010, v3
	v_sub_f32_e32 v5, v6, v5
	v_pk_mul_f32 v[8:9], v[2:3], v[4:5]
	v_pk_add_f32 v[10:11], v[2:3], v[4:5]
	v_fma_f32 v6, v4, v2, -v8
	v_fmac_f32_e32 v6, v4, v13
	v_mov_b32_e32 v9, v11
	v_fmac_f32_e32 v6, v14, v2
	v_pk_add_f32 v[4:5], v[8:9], v[6:7]
	v_ldexp_f32 v14, v13, 1
	v_sub_f32_e32 v3, v4, v8
	v_sub_f32_e32 v3, v6, v3
	v_sub_f32_e32 v6, v7, v5
	v_add_f32_e32 v9, v11, v6
	v_pk_mul_f32 v[6:7], v[4:5], v[4:5] op_sel:[0,1] op_sel_hi:[1,0]
	v_cvt_f64_f32_e32 v[10:11], v12
	v_frexp_exp_i32_f64_e32 v7, v[10:11]
	v_subbrev_co_u32_e64 v7, s[4:5], 0, v7, s[4:5]
	v_cvt_f32_i32_e32 v7, v7
	v_fma_f32 v8, v4, v5, -v6
	v_fmac_f32_e32 v8, v4, v9
	s_mov_b32 s4, 0x3f317218
	v_mul_f32_e32 v4, 0x3f317218, v7
	v_fmac_f32_e32 v8, v3, v5
	v_fma_f32 v3, v7, s4, -v4
	v_fmamk_f32 v10, v7, 0xb102e308, v3
	v_ldexp_f32 v11, v2, 1
	v_add_f32_e32 v5, v6, v8
	v_pk_add_f32 v[2:3], v[4:5], v[10:11]
	v_mov_b32_e32 v12, v5
	v_mov_b32_e32 v13, v3
	v_mov_b32_e32 v7, v11
	v_pk_add_f32 v[6:7], v[12:13], v[6:7] neg_lo:[0,1] neg_hi:[0,1]
	v_mov_b32_e32 v9, v5
	v_pk_add_f32 v[6:7], v[8:9], v[6:7] neg_lo:[0,1] neg_hi:[0,1]
	v_mov_b32_e32 v11, v2
	v_add_f32_e32 v5, v14, v6
	v_add_f32_e32 v5, v5, v7
	v_pk_add_f32 v[6:7], v[2:3], v[4:5] neg_lo:[0,1] neg_hi:[0,1]
	v_pk_add_f32 v[8:9], v[2:3], v[4:5]
	v_mov_b32_e32 v4, v5
	v_mov_b32_e32 v7, v9
	v_pk_add_f32 v[12:13], v[10:11], v[6:7] neg_lo:[0,1] neg_hi:[0,1]
	v_pk_add_f32 v[6:7], v[10:11], v[6:7]
	v_mov_b32_e32 v5, v2
	v_pk_add_f32 v[10:11], v[6:7], v[2:3] op_sel:[1,0] op_sel_hi:[0,1] neg_lo:[0,1] neg_hi:[0,1]
	v_pk_add_f32 v[14:15], v[8:9], v[10:11] op_sel_hi:[1,0] neg_lo:[0,1] neg_hi:[0,1]
	v_mov_b32_e32 v8, v9
	v_mov_b32_e32 v9, v7
	v_pk_mov_b32 v[10:11], v[2:3], v[10:11] op_sel:[1,0]
	v_mov_b32_e32 v14, v12
	v_pk_add_f32 v[8:9], v[8:9], v[10:11] neg_lo:[0,1] neg_hi:[0,1]
	v_mov_b32_e32 v13, v7
	v_pk_add_f32 v[2:3], v[4:5], v[8:9] neg_lo:[0,1] neg_hi:[0,1]
	s_mov_b32 s8, 0x7f800000
	v_pk_add_f32 v[4:5], v[14:15], v[2:3]
	s_load_dwordx2 s[38:39], s[36:37], 0xb8
	v_pk_add_f32 v[8:9], v[4:5], v[4:5] op_sel:[0,1] op_sel_hi:[1,0]
	v_mov_b32_e32 v39, 0x7f800000
	v_pk_add_f32 v[6:7], v[6:7], v[8:9] op_sel:[1,0] op_sel_hi:[0,1]
	v_mov_b32_e32 v5, v6
	v_pk_add_f32 v[10:11], v[4:5], v[12:13] neg_lo:[0,1] neg_hi:[0,1]
	v_mov_b32_e32 v3, v8
	v_sub_f32_e32 v4, v4, v10
	v_pk_add_f32 v[2:3], v[2:3], v[10:11] neg_lo:[0,1] neg_hi:[0,1]
	v_sub_f32_e32 v4, v12, v4
	v_add_f32_e32 v2, v2, v4
	v_add_f32_e32 v2, v2, v3
	v_add_f32_e32 v3, v6, v2
	v_sub_f32_e32 v4, v3, v6
	v_sub_f32_e32 v2, v2, v4
	v_mul_f32_e32 v4, v16, v3
	v_fma_f32 v3, v16, v3, -v4
	v_fmac_f32_e32 v3, v16, v2
	v_add_f32_e32 v2, v4, v3
	v_cmp_class_f32_e64 s[4:5], v4, s7
	v_sub_f32_e32 v5, v2, v4
	v_sub_f32_e32 v3, v3, v5
	v_cndmask_b32_e64 v2, v2, v4, s[4:5]
	v_mov_b32_e32 v4, 0x37000000
	v_cmp_eq_f32_e64 s[4:5], s9, v2
	s_waitcnt lgkmcnt(0)
; #define LAS __attribute__((address_space(3)))
; __device__ __forceinline__ void prologue(const kptr_t kp, LAS float* scr, int gw, int NGW, int lane) {
;     unsigned char* ws = KPTR(unsigned char, 23);
;     for (int it = gw; it < IT_TOTAL; it += NGW) {
;         int r = it;
;         if (r < IT_ADA) {
;             const int l = r / 576, rem = r % 576, cgp = rem / 16, ks = rem % 16, j0 = cgp * 256 + 4 * lane;
;     ...
;             const int id = r * 64 + lane, pos = id >> 4, j = id & 15; const int p = pos < 256 ? pos : pos - 256;
;             const float freq = powf(10000.0f, -(float)j / 16.0f); const float ang = (float)p * freq;
;             float* t = (float*)(ws + CTL_ROPE) + (size_t)id * 2; t[0] = cosf(ang); t[1] = sinf(ang);
	s_add_u32 s42, s38, 0xb8000
	v_and_b32_e32 v33, 63, v1
	v_cndmask_b32_e64 v4, 0, v4, s[4:5]
	v_sub_f32_e32 v5, v2, v4
	s_mov_b32 s4, 0x3fb8aa3b
	v_mul_f32_e32 v6, 0x3fb8aa3b, v5
	v_fma_f32 v7, v5, s4, -v6
	v_rndne_f32_e32 v8, v6
	v_fmamk_f32 v7, v5, 0x32a5705f, v7
	v_sub_f32_e32 v6, v6, v8
	v_add_f32_e32 v6, v6, v7
	v_exp_f32_e32 v6, v6
	v_cvt_i32_f32_e32 v7, v8
	v_cmp_neq_f32_e64 s[4:5], |v2|, s8
	s_addc_u32 s43, s39, 0
	s_add_u32 s44, s38, 0x6300000
	v_cndmask_b32_e64 v2, 0, v3, s[4:5]
	s_mov_b32 s4, 0xc2ce8ed0
	v_ldexp_f32 v3, v6, v7
	v_cmp_ngt_f32_e64 s[4:5], s4, v5
	v_add_f32_e32 v2, v4, v2
	s_addc_u32 s45, s39, 0
	v_cndmask_b32_e64 v3, 0, v3, s[4:5]
	v_cmp_nlt_f32_e64 s[4:5], s9, v5
	v_bfe_u32 v59, v1, 3, 3
	s_add_u32 s29, s38, 0x100000
	v_cndmask_b32_e64 v3, v39, v3, s[4:5]
	v_fma_f32 v2, v3, v2, v3
	v_cmp_class_f32_e64 s[4:5], v3, s7
	v_mov_b32_e32 v31, 0
	v_bfe_u32 v32, v1, 5, 1
	v_cndmask_b32_e64 v2, v2, v3, s[4:5]
	v_cmp_neq_f32_e64 s[4:5], v16, |v16|
	v_and_b32_e32 v34, 31, v1
	v_or_b32_e32 v35, 0xffe3a000, v33
	v_cndmask_b32_e64 v3, v39, 0, s[4:5]
	v_cndmask_b32_e64 v3, v3, 1.0, vcc
	v_cmp_class_f32_e64 s[4:5], v16, s7
	v_or_b32_e32 v37, 0xfff28000, v33
	s_mov_b32 s41, 0
	v_cndmask_b32_e64 v58, |v2|, v3, s[4:5]
	v_lshlrev_b32_e32 v2, 3, v33
	v_and_b32_e32 v38, 56, v2
	v_mul_u32_u24_e32 v1, 0x84, v38
	v_lshlrev_b32_e32 v3, 2, v59
	s_addc_u32 s66, s39, 0
	v_lshl_add_u32 v36, v34, 2, s6
	s_movk_i32 s67, 0x84
	v_add3_u32 v60, s6, v1, v3
	v_or_b32_e32 v61, 8, v59
	v_or_b32_e32 v62, 16, v59
	v_or_b32_e32 v63, 24, v59
	v_lshlrev_b32_e32 v64, 2, v33
	v_mov_b32_e32 v1, v32
	s_brev_b32 s68, 18
	s_mov_b32 s69, 0xfe5163ab
	s_mov_b32 s70, 0x3c439041
	s_mov_b32 s71, 0xdb629599
	s_mov_b32 s72, 0xf534ddc0
	s_mov_b32 s73, 0xfc2757d1
	s_mov_b32 s74, 0x4e441529
	s_mov_b32 s75, 0xa2f9836e
	s_mov_b32 s76, 0x3fc90fda
	s_mov_b32 s77, 0x3f22f983
	s_mov_b32 s78, 0xbfc90fda
	v_mov_b32_e32 v65, 0x3c0881c4
	v_mov_b32_e32 v66, 0xbab64f3b
	s_brev_b32 s79, 1
	s_movk_i32 s80, 0x1f8
	v_lshlrev_b32_e32 v40, 1, v2
	s_mov_b64 s[46:47], 0x2a80000
	s_movk_i32 s81, 0x5800
	s_mov_b64 s[48:49], 0x1f80000
	s_mov_b64 s[50:51], 0x1d80000
	s_mov_b64 s[52:53], 0x1980400
	s_mov_b64 s[54:55], 0x1980000
	s_movk_i32 s83, 0x4800
	s_mov_b64 s[56:57], 0x1080000
	s_mov_b64 s[58:59], 0xb00000
	s_mov_b32 s84, 0x9000
	s_mov_b64 s[60:61], 0x12000
	v_mov_b32_e32 v67, 0x1000
	s_mov_b32 s85, 0xbfb8aa3b
	s_mov_b32 s86, 0x42ce8ed0
	s_mov_b32 s87, 0xc2b17218
	s_mov_b32 s88, 0xfffee000
	s_mov_b32 s89, 0xffff7000
	s_mov_b64 s[62:63], 0x24000
	v_not_b32_e32 v68, 63
	v_not_b32_e32 v69, 31
	v_mov_b32_e32 v70, 0x7fc00000
	v_mov_b32_e32 v72, v31
	v_mov_b32_e32 v73, v31
	v_mov_b32_e32 v74, v31
	v_mov_b32_e32 v75, v31
	s_branch .LBB0_9

;     __device__ __forceinline__ void operator()(const f32x4 (&acc)[2][2][4][2], const Unit& u, int wr, int wc, int fr, int fq) const {
;         const int cond = u.pm < 64 ? 0 : (u.pm < 128 ? 1 : 2);
;         const float* gate = gate_l + cond * 9216;
;         const int col0 = u.pn * BM + wc * 32 + 4 * fq;
;         f32x4 gv[2][2];
; #pragma unroll
;         for (int bj = 0; bj < 2; ++bj)
; #pragma unroll
;             for (int n = 0; n < 2; ++n) gv[bj][n] = *(const f32x4*)(gate + col0 + bj * HALF + n * 16) * coef;
; #pragma unroll
;         for (int ai = 0; ai < 2; ++ai)
; #pragma unroll
;             for (int m = 0; m < 4; ++m) {
;                 const int row = u.pm * BM + ai * HALF + wr * 64 + m * 16 + fr;
;                 const float* s = row < MX_ ? src_main + (size_t)row * D_ : src_ctx + (size_t)(row - MX_) * D_;
;                 float* d = row < MX_ ? dst_main + (size_t)row * D_ : dst_ctx + (size_t)(row - MX_) * D_;
; #pragma unroll
;                 for (int bj = 0; bj < 2; ++bj)
; #pragma unroll
;                     for (int n = 0; n < 2; ++n) { const int off = col0 + bj * HALF + n * 16; const f32x4 xo = *(const f32x4*)(s + off); *(f32x4*)(d + off) = xo + gv[bj][n] * acc[ai][bj][m][n]; }
.LBB0_315:
	s_cmpk_lt_i32 s65, 0x80
	s_cselect_b32 s16, s62, 0x4800
	s_cmp_gt_i32 s65, 63
	s_cselect_b32 s16, s16, 0
	s_lshl_b32 s16, s16, 2
	s_add_u32 s26, s53, s16
	s_addc_u32 s27, s54, 0
	s_load_dwordx2 s[92:93], s[0:1], 0x30
	s_load_dwordx2 s[76:77], s[0:1], 0xb8
	v_lshl_add_u32 v144, s65, 8, v146
	v_lshl_or_b32 v145, s66, 8, v148
	v_lshlrev_b32_e32 v184, 2, v145
	v_lshl_add_u32 v207, v144, 12, v184
	global_load_dwordx4 v[198:201], v184, s[26:27]
	global_load_dwordx4 v[202:205], v184, s[26:27] offset:64
	global_load_dwordx4 v[208:211], v184, s[26:27] offset:512
	global_load_dwordx4 v[214:217], v184, s[26:27] offset:576
	v_add_u32_e32 v213, 0x10000, v207
	v_add_u32_e32 v218, 0x20000, v207
	v_add_u32_e32 v219, 0x30000, v207
	v_add_u32_e32 v250, 0x80000, v207
	v_add_u32_e32 v251, 0x90000, v207
	v_add_u32_e32 v222, 0xa0000, v207
	v_add_u32_e32 v223, 0xb0000, v207
	global_load_dwordx4 v[140:143], v207, s[8:9]
	global_load_dwordx4 v[152:155], v207, s[8:9] offset:64
	global_load_dwordx4 v[156:159], v207, s[8:9] offset:512
	global_load_dwordx4 v[160:163], v207, s[8:9] offset:576
	global_load_dwordx4 v[164:167], v213, s[8:9]
	global_load_dwordx4 v[168:171], v213, s[8:9] offset:64
	global_load_dwordx4 v[172:175], v213, s[8:9] offset:512
	global_load_dwordx4 v[176:179], v213, s[8:9] offset:576
	global_load_dwordx4 v[180:183], v218, s[8:9]
	global_load_dwordx4 v[186:189], v218, s[8:9] offset:64
	global_load_dwordx4 v[190:193], v218, s[8:9] offset:512
	global_load_dwordx4 v[194:197], v218, s[8:9] offset:576
	s_waitcnt vmcnt(12)
	v_pk_mul_f32 v[198:199], v[198:199], 0.5 op_sel_hi:[1,0]
	v_pk_mul_f32 v[200:201], v[200:201], 0.5 op_sel_hi:[1,0]
	v_pk_mul_f32 v[202:203], v[202:203], 0.5 op_sel_hi:[1,0]
	v_pk_mul_f32 v[204:205], v[204:205], 0.5 op_sel_hi:[1,0]
	v_pk_mul_f32 v[208:209], v[208:209], 0.5 op_sel_hi:[1,0]
	v_pk_mul_f32 v[210:211], v[210:211], 0.5 op_sel_hi:[1,0]
	v_pk_mul_f32 v[214:215], v[214:215], 0.5 op_sel_hi:[1,0]
	v_pk_mul_f32 v[216:217], v[216:217], 0.5 op_sel_hi:[1,0]
	s_waitcnt vmcnt(11)
	v_pk_fma_f32 v[124:125], v[124:125], v[198:199], v[140:141]
	v_pk_fma_f32 v[126:127], v[126:127], v[200:201], v[142:143]
	v_mul_f32_e32 v224, v124, v124
	v_fmac_f32_e32 v224, v125, v125
	v_fmac_f32_e32 v224, v126, v126
	v_fmac_f32_e32 v224, v127, v127
	s_waitcnt vmcnt(10)
	v_pk_fma_f32 v[120:121], v[120:121], v[202:203], v[152:153]
	v_pk_fma_f32 v[122:123], v[122:123], v[204:205], v[154:155]
	v_fmac_f32_e32 v224, v120, v120
	v_fmac_f32_e32 v224, v121, v121
	v_fmac_f32_e32 v224, v122, v122
	v_fmac_f32_e32 v224, v123, v123
	s_waitcnt vmcnt(9)
	v_pk_fma_f32 v[116:117], v[116:117], v[208:209], v[156:157]
	v_pk_fma_f32 v[118:119], v[118:119], v[210:211], v[158:159]
	v_fmac_f32_e32 v224, v116, v116
	v_fmac_f32_e32 v224, v117, v117
	v_fmac_f32_e32 v224, v118, v118
	v_fmac_f32_e32 v224, v119, v119
	s_waitcnt vmcnt(8)
	v_pk_fma_f32 v[108:109], v[108:109], v[214:215], v[160:161]
	v_pk_fma_f32 v[110:111], v[110:111], v[216:217], v[162:163]
	v_fmac_f32_e32 v224, v108, v108
	v_fmac_f32_e32 v224, v109, v109
	v_fmac_f32_e32 v224, v110, v110
	v_fmac_f32_e32 v224, v111, v111
	global_store_dwordx4 v207, v[124:127], s[10:11]
	global_store_dwordx4 v207, v[120:123], s[10:11] offset:64
	global_store_dwordx4 v207, v[116:119], s[10:11] offset:512
	global_store_dwordx4 v207, v[108:111], s[10:11] offset:576
	global_load_dwordx4 v[140:143], v219, s[8:9]
	global_load_dwordx4 v[152:155], v219, s[8:9] offset:64
	global_load_dwordx4 v[156:159], v219, s[8:9] offset:512
	global_load_dwordx4 v[160:163], v219, s[8:9] offset:576
	s_waitcnt vmcnt(15)
	v_pk_fma_f32 v[112:113], v[112:113], v[198:199], v[164:165]
	v_pk_fma_f32 v[114:115], v[114:115], v[200:201], v[166:167]
	v_mul_f32_e32 v225, v112, v112
	v_fmac_f32_e32 v225, v113, v113
	v_fmac_f32_e32 v225, v114, v114
	v_fmac_f32_e32 v225, v115, v115
	s_waitcnt vmcnt(14)
	v_pk_fma_f32 v[104:105], v[104:105], v[202:203], v[168:169]
	v_pk_fma_f32 v[106:107], v[106:107], v[204:205], v[170:171]
	v_fmac_f32_e32 v225, v104, v104
	v_fmac_f32_e32 v225, v105, v105
	v_fmac_f32_e32 v225, v106, v106
	v_fmac_f32_e32 v225, v107, v107
	s_waitcnt vmcnt(13)
	v_pk_fma_f32 v[100:101], v[100:101], v[208:209], v[172:173]
	v_pk_fma_f32 v[102:103], v[102:103], v[210:211], v[174:175]
	v_fmac_f32_e32 v225, v100, v100
	v_fmac_f32_e32 v225, v101, v101
	v_fmac_f32_e32 v225, v102, v102
	v_fmac_f32_e32 v225, v103, v103
	s_waitcnt vmcnt(12)
	v_pk_fma_f32 v[92:93], v[92:93], v[214:215], v[176:177]
	v_pk_fma_f32 v[94:95], v[94:95], v[216:217], v[178:179]
	v_fmac_f32_e32 v225, v92, v92
	v_fmac_f32_e32 v225, v93, v93
	v_fmac_f32_e32 v225, v94, v94
	v_fmac_f32_e32 v225, v95, v95
	global_store_dwordx4 v213, v[112:115], s[10:11]
	global_store_dwordx4 v213, v[104:107], s[10:11] offset:64
	global_store_dwordx4 v213, v[100:103], s[10:11] offset:512
	global_store_dwordx4 v213, v[92:95], s[10:11] offset:576
	global_load_dwordx4 v[164:167], v250, s[8:9]
	global_load_dwordx4 v[168:171], v250, s[8:9] offset:64
	global_load_dwordx4 v[172:175], v250, s[8:9] offset:512
	global_load_dwordx4 v[176:179], v250, s[8:9] offset:576
	s_waitcnt vmcnt(19)
	v_pk_fma_f32 v[96:97], v[96:97], v[198:199], v[180:181]
	v_pk_fma_f32 v[98:99], v[98:99], v[200:201], v[182:183]
	v_mul_f32_e32 v226, v96, v96
	v_fmac_f32_e32 v226, v97, v97
	v_fmac_f32_e32 v226, v98, v98
	v_fmac_f32_e32 v226, v99, v99
	s_waitcnt vmcnt(18)
	v_pk_fma_f32 v[88:89], v[88:89], v[202:203], v[186:187]
	v_pk_fma_f32 v[90:91], v[90:91], v[204:205], v[188:189]
	v_fmac_f32_e32 v226, v88, v88
	v_fmac_f32_e32 v226, v89, v89
	v_fmac_f32_e32 v226, v90, v90
	v_fmac_f32_e32 v226, v91, v91
	s_waitcnt vmcnt(17)
;     __device__ __forceinline__ void operator()(const f32x4 (&acc)[2][2][4][2], const Unit& u, int wr, int wc, int fr, int fq) const {
;     ...
;                 const int row = u.pm * BM + ai * HALF + wr * 64 + m * 16 + fr;
;                 const float* s = row < MX_ ? src_main + (size_t)row * D_ : src_ctx + (size_t)(row - MX_) * D_;
;                 float* d = row < MX_ ? dst_main + (size_t)row * D_ : dst_ctx + (size_t)(row - MX_) * D_;
; #pragma unroll
;                 for (int bj = 0; bj < 2; ++bj)
; #pragma unroll
;                     for (int n = 0; n < 2; ++n) { const int off = col0 + bj * HALF + n * 16; const f32x4 xo = *(const f32x4*)(s + off); *(f32x4*)(d + off) = xo + gv[bj][n] * acc[ai][bj][m][n]; }
	v_pk_fma_f32 v[84:85], v[84:85], v[208:209], v[190:191]
	v_pk_fma_f32 v[86:87], v[86:87], v[210:211], v[192:193]
	v_fmac_f32_e32 v226, v84, v84
	v_fmac_f32_e32 v226, v85, v85
	v_fmac_f32_e32 v226, v86, v86
	v_fmac_f32_e32 v226, v87, v87
	s_waitcnt vmcnt(16)
	v_pk_fma_f32 v[76:77], v[76:77], v[214:215], v[194:195]
	v_pk_fma_f32 v[78:79], v[78:79], v[216:217], v[196:197]
	v_fmac_f32_e32 v226, v76, v76
	v_fmac_f32_e32 v226, v77, v77
	v_fmac_f32_e32 v226, v78, v78
	v_fmac_f32_e32 v226, v79, v79
	global_store_dwordx4 v218, v[96:99], s[10:11]
	global_store_dwordx4 v218, v[88:91], s[10:11] offset:64
	global_store_dwordx4 v218, v[84:87], s[10:11] offset:512
	global_store_dwordx4 v218, v[76:79], s[10:11] offset:576
	global_load_dwordx4 v[180:183], v251, s[8:9]
	global_load_dwordx4 v[186:189], v251, s[8:9] offset:64
	global_load_dwordx4 v[190:193], v251, s[8:9] offset:512
	global_load_dwordx4 v[194:197], v251, s[8:9] offset:576
	s_waitcnt vmcnt(19)
	v_pk_fma_f32 v[80:81], v[80:81], v[198:199], v[140:141]
	v_pk_fma_f32 v[82:83], v[82:83], v[200:201], v[142:143]
	v_mul_f32_e32 v227, v80, v80
	v_fmac_f32_e32 v227, v81, v81
	v_fmac_f32_e32 v227, v82, v82
	v_fmac_f32_e32 v227, v83, v83
	s_waitcnt vmcnt(18)
	v_pk_fma_f32 v[72:73], v[72:73], v[202:203], v[152:153]
	v_pk_fma_f32 v[74:75], v[74:75], v[204:205], v[154:155]
	v_fmac_f32_e32 v227, v72, v72
	v_fmac_f32_e32 v227, v73, v73
	v_fmac_f32_e32 v227, v74, v74
	v_fmac_f32_e32 v227, v75, v75
	s_waitcnt vmcnt(17)
	v_pk_fma_f32 v[68:69], v[68:69], v[208:209], v[156:157]
	v_pk_fma_f32 v[70:71], v[70:71], v[210:211], v[158:159]
	v_fmac_f32_e32 v227, v68, v68
	v_fmac_f32_e32 v227, v69, v69
	v_fmac_f32_e32 v227, v70, v70
	v_fmac_f32_e32 v227, v71, v71
	s_waitcnt vmcnt(16)
	v_pk_fma_f32 v[64:65], v[64:65], v[214:215], v[160:161]
	v_pk_fma_f32 v[66:67], v[66:67], v[216:217], v[162:163]
	v_fmac_f32_e32 v227, v64, v64
	v_fmac_f32_e32 v227, v65, v65
	v_fmac_f32_e32 v227, v66, v66
	v_fmac_f32_e32 v227, v67, v67
	global_store_dwordx4 v219, v[80:83], s[10:11]
	global_store_dwordx4 v219, v[72:75], s[10:11] offset:64
	global_store_dwordx4 v219, v[68:71], s[10:11] offset:512
	global_store_dwordx4 v219, v[64:67], s[10:11] offset:576
	global_load_dwordx4 v[140:143], v222, s[8:9]
	global_load_dwordx4 v[152:155], v222, s[8:9] offset:64
	global_load_dwordx4 v[156:159], v222, s[8:9] offset:512
	global_load_dwordx4 v[160:163], v222, s[8:9] offset:576
	s_waitcnt vmcnt(19)
	v_pk_fma_f32 v[60:61], v[60:61], v[198:199], v[164:165]
	v_pk_fma_f32 v[62:63], v[62:63], v[200:201], v[166:167]
	v_mul_f32_e32 v228, v60, v60
	v_fmac_f32_e32 v228, v61, v61
	v_fmac_f32_e32 v228, v62, v62
	v_fmac_f32_e32 v228, v63, v63
	s_waitcnt vmcnt(18)
	v_pk_fma_f32 v[56:57], v[56:57], v[202:203], v[168:169]
	v_pk_fma_f32 v[58:59], v[58:59], v[204:205], v[170:171]
	v_fmac_f32_e32 v228, v56, v56
	v_fmac_f32_e32 v228, v57, v57
	v_fmac_f32_e32 v228, v58, v58
	v_fmac_f32_e32 v228, v59, v59
	s_waitcnt vmcnt(17)
	v_pk_fma_f32 v[52:53], v[52:53], v[208:209], v[172:173]
	v_pk_fma_f32 v[54:55], v[54:55], v[210:211], v[174:175]
	v_fmac_f32_e32 v228, v52, v52
	v_fmac_f32_e32 v228, v53, v53
	v_fmac_f32_e32 v228, v54, v54
	v_fmac_f32_e32 v228, v55, v55
	s_waitcnt vmcnt(16)
	v_pk_fma_f32 v[44:45], v[44:45], v[214:215], v[176:177]
	v_pk_fma_f32 v[46:47], v[46:47], v[216:217], v[178:179]
	v_fmac_f32_e32 v228, v44, v44
	v_fmac_f32_e32 v228, v45, v45
	v_fmac_f32_e32 v228, v46, v46
	v_fmac_f32_e32 v228, v47, v47
	global_store_dwordx4 v250, v[60:63], s[10:11]
	global_store_dwordx4 v250, v[56:59], s[10:11] offset:64
	global_store_dwordx4 v250, v[52:55], s[10:11] offset:512
	global_store_dwordx4 v250, v[44:47], s[10:11] offset:576
	global_load_dwordx4 v[164:167], v223, s[8:9]
	global_load_dwordx4 v[168:171], v223, s[8:9] offset:64
	global_load_dwordx4 v[172:175], v223, s[8:9] offset:512
	global_load_dwordx4 v[176:179], v223, s[8:9] offset:576
	s_waitcnt vmcnt(19)
	v_pk_fma_f32 v[48:49], v[48:49], v[198:199], v[180:181]
	v_pk_fma_f32 v[50:51], v[50:51], v[200:201], v[182:183]
	v_mul_f32_e32 v229, v48, v48
	v_fmac_f32_e32 v229, v49, v49
	v_fmac_f32_e32 v229, v50, v50
	v_fmac_f32_e32 v229, v51, v51
	s_waitcnt vmcnt(18)
	v_pk_fma_f32 v[40:41], v[40:41], v[202:203], v[186:187]
	v_pk_fma_f32 v[42:43], v[42:43], v[204:205], v[188:189]
	v_fmac_f32_e32 v229, v40, v40
	v_fmac_f32_e32 v229, v41, v41
	v_fmac_f32_e32 v229, v42, v42
	v_fmac_f32_e32 v229, v43, v43
	s_waitcnt vmcnt(17)
	v_pk_fma_f32 v[36:37], v[36:37], v[208:209], v[190:191]
	v_pk_fma_f32 v[38:39], v[38:39], v[210:211], v[192:193]
	v_fmac_f32_e32 v229, v36, v36
	v_fmac_f32_e32 v229, v37, v37
	v_fmac_f32_e32 v229, v38, v38
	v_fmac_f32_e32 v229, v39, v39
	s_waitcnt vmcnt(16)
	v_pk_fma_f32 v[28:29], v[28:29], v[214:215], v[194:195]
	v_pk_fma_f32 v[30:31], v[30:31], v[216:217], v[196:197]
	v_fmac_f32_e32 v229, v28, v28
	v_fmac_f32_e32 v229, v29, v29
	v_fmac_f32_e32 v229, v30, v30
	v_fmac_f32_e32 v229, v31, v31
	global_store_dwordx4 v251, v[48:51], s[10:11]
	global_store_dwordx4 v251, v[40:43], s[10:11] offset:64
	global_store_dwordx4 v251, v[36:39], s[10:11] offset:512
	global_store_dwordx4 v251, v[28:31], s[10:11] offset:576
	s_waitcnt vmcnt(15)
;     __device__ __forceinline__ void operator()(const f32x4 (&acc)[2][2][4][2], const Unit& u, int wr, int wc, int fr, int fq) const {
;     ...
;                     for (int n = 0; n < 2; ++n) { const int off = col0 + bj * HALF + n * 16; const f32x4 xo = *(const f32x4*)(s + off); *(f32x4*)(d + off) = xo + gv[bj][n] * acc[ai][bj][m][n]; }
;     __device__ __forceinline__ void operator()(const f32x4 (&acc)[2][2][4][2], const Unit& u, int wr, int wc, int fr, int fq) const {
;     ...
;                         s1 += __shfl_xor(s1, 16); s1 += __shfl_xor(s1, 32); s2 += __shfl_xor(s2, 16); s2 += __shfl_xor(s2, 32);
;                         if (fq == 0) { unsafeAtomicAdd(stats + 2 * row, s1); unsafeAtomicAdd(stats + 2 * row + 1, s2); }
	v_pk_fma_f32 v[32:33], v[32:33], v[198:199], v[140:141]
	v_pk_fma_f32 v[34:35], v[34:35], v[200:201], v[142:143]
	v_mul_f32_e32 v230, v32, v32
	v_fmac_f32_e32 v230, v33, v33
	v_fmac_f32_e32 v230, v34, v34
	v_fmac_f32_e32 v230, v35, v35
	s_waitcnt vmcnt(14)
	v_pk_fma_f32 v[24:25], v[24:25], v[202:203], v[152:153]
	v_pk_fma_f32 v[26:27], v[26:27], v[204:205], v[154:155]
	v_fmac_f32_e32 v230, v24, v24
	v_fmac_f32_e32 v230, v25, v25
	v_fmac_f32_e32 v230, v26, v26
	v_fmac_f32_e32 v230, v27, v27
	s_waitcnt vmcnt(13)
	v_pk_fma_f32 v[20:21], v[20:21], v[208:209], v[156:157]
	v_pk_fma_f32 v[22:23], v[22:23], v[210:211], v[158:159]
	v_fmac_f32_e32 v230, v20, v20
	v_fmac_f32_e32 v230, v21, v21
	v_fmac_f32_e32 v230, v22, v22
	v_fmac_f32_e32 v230, v23, v23
	s_waitcnt vmcnt(12)
	v_pk_fma_f32 v[12:13], v[12:13], v[214:215], v[160:161]
	v_pk_fma_f32 v[14:15], v[14:15], v[216:217], v[162:163]
	v_fmac_f32_e32 v230, v12, v12
	v_fmac_f32_e32 v230, v13, v13
	v_fmac_f32_e32 v230, v14, v14
	v_fmac_f32_e32 v230, v15, v15
	global_store_dwordx4 v222, v[32:35], s[10:11]
	global_store_dwordx4 v222, v[24:27], s[10:11] offset:64
	global_store_dwordx4 v222, v[20:23], s[10:11] offset:512
	global_store_dwordx4 v222, v[12:15], s[10:11] offset:576
	s_waitcnt vmcnt(11)
	v_pk_fma_f32 v[16:17], v[16:17], v[198:199], v[164:165]
	v_pk_fma_f32 v[18:19], v[18:19], v[200:201], v[166:167]
	v_mul_f32_e32 v231, v16, v16
	v_fmac_f32_e32 v231, v17, v17
	v_fmac_f32_e32 v231, v18, v18
	v_fmac_f32_e32 v231, v19, v19
	s_waitcnt vmcnt(10)
	v_pk_fma_f32 v[8:9], v[8:9], v[202:203], v[168:169]
	v_pk_fma_f32 v[10:11], v[10:11], v[204:205], v[170:171]
	v_fmac_f32_e32 v231, v8, v8
	v_fmac_f32_e32 v231, v9, v9
	v_fmac_f32_e32 v231, v10, v10
	v_fmac_f32_e32 v231, v11, v11
	s_waitcnt vmcnt(9)
	v_pk_fma_f32 v[4:5], v[4:5], v[208:209], v[172:173]
	v_pk_fma_f32 v[6:7], v[6:7], v[210:211], v[174:175]
	v_fmac_f32_e32 v231, v4, v4
	v_fmac_f32_e32 v231, v5, v5
	v_fmac_f32_e32 v231, v6, v6
	v_fmac_f32_e32 v231, v7, v7
	s_waitcnt vmcnt(8)
	v_pk_fma_f32 v[0:1], v[0:1], v[214:215], v[176:177]
	v_pk_fma_f32 v[2:3], v[2:3], v[216:217], v[178:179]
	v_fmac_f32_e32 v231, v0, v0
	v_fmac_f32_e32 v231, v1, v1
	v_fmac_f32_e32 v231, v2, v2
	v_fmac_f32_e32 v231, v3, v3
	global_store_dwordx4 v223, v[16:19], s[10:11]
	global_store_dwordx4 v223, v[8:11], s[10:11] offset:64
	global_store_dwordx4 v223, v[4:7], s[10:11] offset:512
	global_store_dwordx4 v223, v[0:3], s[10:11] offset:576
	v_mbcnt_lo_u32_b32 v232, -1, 0
	v_mbcnt_hi_u32_b32 v232, -1, v232
	v_xor_b32_e32 v233, 16, v232
	v_xor_b32_e32 v234, 32, v232
	v_lshlrev_b32_e32 v233, 2, v233
	v_lshlrev_b32_e32 v234, 2, v234
	s_waitcnt lgkmcnt(0)
	ds_bpermute_b32 v140, v233, v224
	ds_bpermute_b32 v141, v233, v225
	ds_bpermute_b32 v142, v233, v226
	ds_bpermute_b32 v143, v233, v227
	ds_bpermute_b32 v152, v233, v228
	ds_bpermute_b32 v153, v233, v229
	ds_bpermute_b32 v154, v233, v230
	ds_bpermute_b32 v155, v233, v231
	s_waitcnt lgkmcnt(7)
	v_add_f32_e32 v224, v224, v140
	s_waitcnt lgkmcnt(6)
	v_add_f32_e32 v225, v225, v141
	s_waitcnt lgkmcnt(5)
	v_add_f32_e32 v226, v226, v142
	s_waitcnt lgkmcnt(4)
	v_add_f32_e32 v227, v227, v143
	s_waitcnt lgkmcnt(3)
	v_add_f32_e32 v228, v228, v152
	s_waitcnt lgkmcnt(2)
	v_add_f32_e32 v229, v229, v153
	s_waitcnt lgkmcnt(1)
	v_add_f32_e32 v230, v230, v154
	s_waitcnt lgkmcnt(0)
	v_add_f32_e32 v231, v231, v155
	ds_bpermute_b32 v140, v234, v224
	ds_bpermute_b32 v141, v234, v225
	ds_bpermute_b32 v142, v234, v226
	ds_bpermute_b32 v143, v234, v227
	ds_bpermute_b32 v152, v234, v228
	ds_bpermute_b32 v153, v234, v229
	ds_bpermute_b32 v154, v234, v230
	ds_bpermute_b32 v155, v234, v231
	s_waitcnt lgkmcnt(7)
	v_add_f32_e32 v224, v224, v140
	s_waitcnt lgkmcnt(6)
	v_add_f32_e32 v225, v225, v141
	s_waitcnt lgkmcnt(5)
	v_add_f32_e32 v226, v226, v142
	s_waitcnt lgkmcnt(4)
	v_add_f32_e32 v227, v227, v143
	s_waitcnt lgkmcnt(3)
	v_add_f32_e32 v228, v228, v152
	s_waitcnt lgkmcnt(2)
	v_add_f32_e32 v229, v229, v153
	s_waitcnt lgkmcnt(1)
	v_add_f32_e32 v230, v230, v154
	s_waitcnt lgkmcnt(0)
	v_add_f32_e32 v231, v231, v155
	v_lshlrev_b32_e32 v235, 2, v144
	s_add_u32 s90, s76, 0x6500000
	s_addc_u32 s91, s77, 0
	s_add_u32 s76, s76, 0x3120000
	s_addc_u32 s77, s77, 0
	s_lshl_b32 s83, s65, 6
	s_add_u32 s78, s76, s83
	s_addc_u32 s79, s77, 0
	s_add_u32 s78, s78, 0x20000
	s_addc_u32 s79, s79, 0
	s_mov_b64 s[80:81], exec
	s_mov_b64 exec, 0xffff
	global_atomic_add_f32 v235, v224, s[76:77]
	global_atomic_add_f32 v235, v225, s[76:77] offset:64
	global_atomic_add_f32 v235, v226, s[76:77] offset:128
	global_atomic_add_f32 v235, v227, s[76:77] offset:192
	global_atomic_add_f32 v235, v228, s[76:77] offset:512
	global_atomic_add_f32 v235, v229, s[76:77] offset:576
	global_atomic_add_f32 v235, v230, s[76:77] offset:640
	global_atomic_add_f32 v235, v231, s[76:77] offset:704
	s_mov_b64 exec, s[80:81]
	s_add_u32 s86, s26, 0x1000
	s_addc_u32 s87, s27, 0
	s_add_u32 s88, s86, 0x1000
	s_addc_u32 s89, s87, 0
	s_add_u32 s92, s92, 0x1000
	s_addc_u32 s93, s93, 0
	s_mov_b32 s84, 0xffff0000
	s_mov_b32 s85, 0xffff0000
	s_waitcnt vmcnt(0)
	s_barrier
	v_readfirstlane_b32 s83, v206
	v_mov_b32_e32 v236, 0
	v_mov_b32_e32 v237, 1
	s_cmp_lg_u32 s83, 0
	s_cbranch_scc1 .Lfma_wait_done
	s_mov_b64 exec, 1
	global_atomic_add v236, v237, s[78:79]
	s_mov_b32 s82, 0

; __device__ __forceinline__ unsigned cvtpk_s(float lo, float hi) { f32x2_t v = {lo, hi}; bf16x2_t b = __builtin_convertvector(v, bf16x2_t); return __builtin_bit_cast(unsigned, b); }
; __device__ __forceinline__ u32x4 quad_swap(unsigned lo0, unsigned lo1, unsigned hi0, unsigned hi1, int fq, int& coloff) {
;     const bool odd = fq & 1;
;     const unsigned s0 = odd ? lo0 : hi0, s1 = odd ? lo1 : hi1;
;     const unsigned r0 = (unsigned)__shfl_xor((int)s0, 16), r1 = (unsigned)__shfl_xor((int)s1, 16);
;     coloff = odd ? 16 + 4 * (fq - 1) : 4 * fq;
;     u32x4 o; o.x = odd ? r0 : lo0; o.y = odd ? r1 : lo1; o.z = odd ? hi0 : r0; o.w = odd ? hi1 : r1; return o;
; }
; __device__ __forceinline__ void modpass(const float* xs_main, const float* xs_ctx, const float* mod_l, const float* g, int i, bf16_t* H, int nrows, int gw, int NGW, int lane) {
;     ...
;         const float rstd = 1.0f / sqrtf(wave_sum(ss) * (1.0f / D) + EPS);
; #pragma unroll
;         for (int j = 0; j < 2; ++j) {
;             const f32x4 o0 = v[j][0] * rstd * gm[j][0] + sh[j][0], o1 = v[j][1] * rstd * gm[j][1] + sh[j][1];
;             u32x4 w; w.x = cvtpk_s(o0[0], o0[1]); w.y = cvtpk_s(o0[2], o0[3]); w.z = cvtpk_s(o1[0], o1[1]); w.w = cvtpk_s(o1[2], o1[3]);
;             *(u32x4*)(H + (size_t)row * D + 8 * lane + 512 * j) = w;
.Lfma_wait_done:
	s_barrier
	global_load_dword v152, v235, s[76:77] sc1
	global_load_dword v153, v235, s[76:77] offset:64 sc1
	global_load_dword v154, v235, s[76:77] offset:128 sc1
	global_load_dword v155, v235, s[76:77] offset:192 sc1
	global_load_dword v156, v235, s[76:77] offset:512 sc1
	global_load_dword v157, v235, s[76:77] offset:576 sc1
	global_load_dword v158, v235, s[76:77] offset:640 sc1
	global_load_dword v159, v235, s[76:77] offset:704 sc1
	global_load_dwordx4 v[198:201], v184, s[86:87]
	global_load_dwordx4 v[202:205], v184, s[86:87] offset:64
	global_load_dwordx4 v[208:211], v184, s[86:87] offset:512
	global_load_dwordx4 v[214:217], v184, s[86:87] offset:576
	global_load_dwordx4 v[160:163], v184, s[88:89]
	global_load_dwordx4 v[164:167], v184, s[88:89] offset:64
	global_load_dwordx4 v[168:171], v184, s[88:89] offset:512
	global_load_dwordx4 v[172:175], v184, s[88:89] offset:576
	global_load_dwordx4 v[176:179], v184, s[92:93]
	global_load_dwordx4 v[180:183], v184, s[92:93] offset:64
	global_load_dwordx4 v[186:189], v184, s[92:93] offset:512
	global_load_dwordx4 v[190:193], v184, s[92:93] offset:576
	v_mov_b32_e32 v232, 12
	v_cndmask_b32_e64 v232, 0, v232, s[84:85]
	v_add_u32_e32 v232, v232, v145
	v_lshlrev_b32_e32 v232, 1, v232
	v_lshl_add_u32 v239, v144, 11, v232
	v_mov_b32_e32 v232, 0x358637bd
	s_waitcnt vmcnt(0)
	v_fmamk_f32 v152, v152, 0x3a800000, v232
	v_fmamk_f32 v153, v153, 0x3a800000, v232
	v_fmamk_f32 v154, v154, 0x3a800000, v232
	v_fmamk_f32 v155, v155, 0x3a800000, v232
	v_fmamk_f32 v156, v156, 0x3a800000, v232
	v_fmamk_f32 v157, v157, 0x3a800000, v232
	v_fmamk_f32 v158, v158, 0x3a800000, v232
	v_fmamk_f32 v159, v159, 0x3a800000, v232
	v_rsq_f32_e32 v152, v152
	v_rsq_f32_e32 v153, v153
	v_rsq_f32_e32 v154, v154
	v_rsq_f32_e32 v155, v155
	v_rsq_f32_e32 v156, v156
	v_rsq_f32_e32 v157, v157
	v_rsq_f32_e32 v158, v158
	v_rsq_f32_e32 v159, v159
	v_pk_add_f32 v[160:161], v[160:161], 1.0 op_sel_hi:[1,0]
	v_pk_mul_f32 v[160:161], v[176:177], v[160:161]
	v_pk_add_f32 v[162:163], v[162:163], 1.0 op_sel_hi:[1,0]
	v_pk_mul_f32 v[162:163], v[178:179], v[162:163]
	v_pk_add_f32 v[164:165], v[164:165], 1.0 op_sel_hi:[1,0]
	v_pk_mul_f32 v[164:165], v[180:181], v[164:165]
	v_pk_add_f32 v[166:167], v[166:167], 1.0 op_sel_hi:[1,0]
	v_pk_mul_f32 v[166:167], v[182:183], v[166:167]
	v_pk_add_f32 v[168:169], v[168:169], 1.0 op_sel_hi:[1,0]
	v_pk_mul_f32 v[168:169], v[186:187], v[168:169]
	v_pk_add_f32 v[170:171], v[170:171], 1.0 op_sel_hi:[1,0]
	v_pk_mul_f32 v[170:171], v[188:189], v[170:171]
	v_pk_add_f32 v[172:173], v[172:173], 1.0 op_sel_hi:[1,0]
	v_pk_mul_f32 v[172:173], v[190:191], v[172:173]
	v_pk_add_f32 v[174:175], v[174:175], 1.0 op_sel_hi:[1,0]
	v_pk_mul_f32 v[174:175], v[192:193], v[174:175]
	v_mul_f32_e32 v124, v124, v152
	v_mul_f32_e32 v125, v125, v152
	v_pk_fma_f32 v[124:125], v[160:161], v[124:125], v[198:199]
	v_mul_f32_e32 v126, v126, v152
	v_mul_f32_e32 v127, v127, v152
	v_pk_fma_f32 v[126:127], v[162:163], v[126:127], v[200:201]
	v_cvt_pk_bf16_f32 v186, v124, v125
	v_cvt_pk_bf16_f32 v187, v126, v127
	v_mul_f32_e32 v120, v120, v152
	v_mul_f32_e32 v121, v121, v152
	v_pk_fma_f32 v[120:121], v[164:165], v[120:121], v[202:203]
	v_mul_f32_e32 v122, v122, v152
	v_mul_f32_e32 v123, v123, v152
	v_pk_fma_f32 v[122:123], v[166:167], v[122:123], v[204:205]
	v_cvt_pk_bf16_f32 v188, v120, v121
	v_cvt_pk_bf16_f32 v189, v122, v123
	v_mul_f32_e32 v116, v116, v152
	v_mul_f32_e32 v117, v117, v152
	v_pk_fma_f32 v[116:117], v[168:169], v[116:117], v[208:209]
	v_mul_f32_e32 v118, v118, v152
	v_mul_f32_e32 v119, v119, v152
	v_pk_fma_f32 v[118:119], v[170:171], v[118:119], v[210:211]
	v_cvt_pk_bf16_f32 v190, v116, v117
	v_cvt_pk_bf16_f32 v191, v118, v119
	v_mul_f32_e32 v108, v108, v152
	v_mul_f32_e32 v109, v109, v152
	v_pk_fma_f32 v[108:109], v[172:173], v[108:109], v[214:215]
	v_mul_f32_e32 v110, v110, v152
	v_mul_f32_e32 v111, v111, v152
	v_pk_fma_f32 v[110:111], v[174:175], v[110:111], v[216:217]
	v_cvt_pk_bf16_f32 v192, v108, v109
	v_cvt_pk_bf16_f32 v193, v110, v111
	v_mov_b32_e32 v232, v239
	v_cndmask_b32_e64 v194, v188, v186, s[84:85]
	v_cndmask_b32_e64 v195, v189, v187, s[84:85]
	ds_bpermute_b32 v196, v233, v194
	ds_bpermute_b32 v197, v233, v195
	s_waitcnt lgkmcnt(0)
	v_cndmask_b32_e64 v176, v186, v196, s[84:85]
	v_cndmask_b32_e64 v177, v187, v197, s[84:85]
	v_cndmask_b32_e64 v178, v196, v188, s[84:85]
	v_cndmask_b32_e64 v179, v197, v189, s[84:85]
	global_store_dwordx4 v232, v[176:179], s[90:91]
	v_cndmask_b32_e64 v194, v192, v190, s[84:85]
	v_cndmask_b32_e64 v195, v193, v191, s[84:85]
	ds_bpermute_b32 v196, v233, v194
	ds_bpermute_b32 v197, v233, v195
	s_waitcnt lgkmcnt(0)
	v_cndmask_b32_e64 v180, v190, v196, s[84:85]
	v_cndmask_b32_e64 v181, v191, v197, s[84:85]
	v_cndmask_b32_e64 v182, v196, v192, s[84:85]
	v_cndmask_b32_e64 v183, v197, v193, s[84:85]
	global_store_dwordx4 v232, v[180:183], s[90:91] offset:256
	v_mul_f32_e32 v112, v112, v153
	v_mul_f32_e32 v113, v113, v153
	v_pk_fma_f32 v[112:113], v[160:161], v[112:113], v[198:199]
	v_mul_f32_e32 v114, v114, v153
	v_mul_f32_e32 v115, v115, v153
	v_pk_fma_f32 v[114:115], v[162:163], v[114:115], v[200:201]
	v_cvt_pk_bf16_f32 v186, v112, v113
	v_cvt_pk_bf16_f32 v187, v114, v115
	v_mul_f32_e32 v104, v104, v153
	v_mul_f32_e32 v105, v105, v153
	v_pk_fma_f32 v[104:105], v[164:165], v[104:105], v[202:203]
	v_mul_f32_e32 v106, v106, v153
	v_mul_f32_e32 v107, v107, v153
	v_pk_fma_f32 v[106:107], v[166:167], v[106:107], v[204:205]
	v_cvt_pk_bf16_f32 v188, v104, v105
	v_cvt_pk_bf16_f32 v189, v106, v107
	v_mul_f32_e32 v100, v100, v153
	v_mul_f32_e32 v101, v101, v153
	v_pk_fma_f32 v[100:101], v[168:169], v[100:101], v[208:209]
	v_mul_f32_e32 v102, v102, v153
	v_mul_f32_e32 v103, v103, v153
	v_pk_fma_f32 v[102:103], v[170:171], v[102:103], v[210:211]
	v_cvt_pk_bf16_f32 v190, v100, v101
	v_cvt_pk_bf16_f32 v191, v102, v103
	v_mul_f32_e32 v92, v92, v153
	v_mul_f32_e32 v93, v93, v153
	v_pk_fma_f32 v[92:93], v[172:173], v[92:93], v[214:215]
	v_mul_f32_e32 v94, v94, v153
	v_mul_f32_e32 v95, v95, v153
	v_pk_fma_f32 v[94:95], v[174:175], v[94:95], v[216:217]
	v_cvt_pk_bf16_f32 v192, v92, v93
	v_cvt_pk_bf16_f32 v193, v94, v95
	v_add_u32_e32 v232, 0x8000, v239
	v_cndmask_b32_e64 v194, v188, v186, s[84:85]
	v_cndmask_b32_e64 v195, v189, v187, s[84:85]
	ds_bpermute_b32 v196, v233, v194
	ds_bpermute_b32 v197, v233, v195
	s_waitcnt lgkmcnt(0)
; __device__ __forceinline__ unsigned cvtpk_s(float lo, float hi) { f32x2_t v = {lo, hi}; bf16x2_t b = __builtin_convertvector(v, bf16x2_t); return __builtin_bit_cast(unsigned, b); }
; __device__ __forceinline__ u32x4 quad_swap(unsigned lo0, unsigned lo1, unsigned hi0, unsigned hi1, int fq, int& coloff) {
;     const bool odd = fq & 1;
;     const unsigned s0 = odd ? lo0 : hi0, s1 = odd ? lo1 : hi1;
;     const unsigned r0 = (unsigned)__shfl_xor((int)s0, 16), r1 = (unsigned)__shfl_xor((int)s1, 16);
;     coloff = odd ? 16 + 4 * (fq - 1) : 4 * fq;
;     u32x4 o; o.x = odd ? r0 : lo0; o.y = odd ? r1 : lo1; o.z = odd ? hi0 : r0; o.w = odd ? hi1 : r1; return o;
; __device__ __forceinline__ void modpass(const float* xs_main, const float* xs_ctx, const float* mod_l, const float* g, int i, bf16_t* H, int nrows, int gw, int NGW, int lane) {
;     ...
;         for (int j = 0; j < 2; ++j) {
;             const f32x4 o0 = v[j][0] * rstd * gm[j][0] + sh[j][0], o1 = v[j][1] * rstd * gm[j][1] + sh[j][1];
;             u32x4 w; w.x = cvtpk_s(o0[0], o0[1]); w.y = cvtpk_s(o0[2], o0[3]); w.z = cvtpk_s(o1[0], o1[1]); w.w = cvtpk_s(o1[2], o1[3]);
;             *(u32x4*)(H + (size_t)row * D + 8 * lane + 512 * j) = w;
	v_cndmask_b32_e64 v176, v186, v196, s[84:85]
	v_cndmask_b32_e64 v177, v187, v197, s[84:85]
	v_cndmask_b32_e64 v178, v196, v188, s[84:85]
	v_cndmask_b32_e64 v179, v197, v189, s[84:85]
	global_store_dwordx4 v232, v[176:179], s[90:91]
	v_cndmask_b32_e64 v194, v192, v190, s[84:85]
	v_cndmask_b32_e64 v195, v193, v191, s[84:85]
	ds_bpermute_b32 v196, v233, v194
	ds_bpermute_b32 v197, v233, v195
	s_waitcnt lgkmcnt(0)
	v_cndmask_b32_e64 v180, v190, v196, s[84:85]
	v_cndmask_b32_e64 v181, v191, v197, s[84:85]
	v_cndmask_b32_e64 v182, v196, v192, s[84:85]
	v_cndmask_b32_e64 v183, v197, v193, s[84:85]
	global_store_dwordx4 v232, v[180:183], s[90:91] offset:256
	v_mul_f32_e32 v96, v96, v154
	v_mul_f32_e32 v97, v97, v154
	v_pk_fma_f32 v[96:97], v[160:161], v[96:97], v[198:199]
	v_mul_f32_e32 v98, v98, v154
	v_mul_f32_e32 v99, v99, v154
	v_pk_fma_f32 v[98:99], v[162:163], v[98:99], v[200:201]
	v_cvt_pk_bf16_f32 v186, v96, v97
	v_cvt_pk_bf16_f32 v187, v98, v99
	v_mul_f32_e32 v88, v88, v154
	v_mul_f32_e32 v89, v89, v154
	v_pk_fma_f32 v[88:89], v[164:165], v[88:89], v[202:203]
	v_mul_f32_e32 v90, v90, v154
	v_mul_f32_e32 v91, v91, v154
	v_pk_fma_f32 v[90:91], v[166:167], v[90:91], v[204:205]
	v_cvt_pk_bf16_f32 v188, v88, v89
	v_cvt_pk_bf16_f32 v189, v90, v91
	v_mul_f32_e32 v84, v84, v154
	v_mul_f32_e32 v85, v85, v154
	v_pk_fma_f32 v[84:85], v[168:169], v[84:85], v[208:209]
	v_mul_f32_e32 v86, v86, v154
	v_mul_f32_e32 v87, v87, v154
	v_pk_fma_f32 v[86:87], v[170:171], v[86:87], v[210:211]
	v_cvt_pk_bf16_f32 v190, v84, v85
	v_cvt_pk_bf16_f32 v191, v86, v87
	v_mul_f32_e32 v76, v76, v154
	v_mul_f32_e32 v77, v77, v154
	v_pk_fma_f32 v[76:77], v[172:173], v[76:77], v[214:215]
	v_mul_f32_e32 v78, v78, v154
	v_mul_f32_e32 v79, v79, v154
	v_pk_fma_f32 v[78:79], v[174:175], v[78:79], v[216:217]
	v_cvt_pk_bf16_f32 v192, v76, v77
	v_cvt_pk_bf16_f32 v193, v78, v79
	v_add_u32_e32 v232, 0x10000, v239
	v_cndmask_b32_e64 v194, v188, v186, s[84:85]
	v_cndmask_b32_e64 v195, v189, v187, s[84:85]
	ds_bpermute_b32 v196, v233, v194
	ds_bpermute_b32 v197, v233, v195
	s_waitcnt lgkmcnt(0)
	v_cndmask_b32_e64 v176, v186, v196, s[84:85]
	v_cndmask_b32_e64 v177, v187, v197, s[84:85]
	v_cndmask_b32_e64 v178, v196, v188, s[84:85]
	v_cndmask_b32_e64 v179, v197, v189, s[84:85]
	global_store_dwordx4 v232, v[176:179], s[90:91]
	v_cndmask_b32_e64 v194, v192, v190, s[84:85]
	v_cndmask_b32_e64 v195, v193, v191, s[84:85]
	ds_bpermute_b32 v196, v233, v194
	ds_bpermute_b32 v197, v233, v195
	s_waitcnt lgkmcnt(0)
	v_cndmask_b32_e64 v180, v190, v196, s[84:85]
	v_cndmask_b32_e64 v181, v191, v197, s[84:85]
	v_cndmask_b32_e64 v182, v196, v192, s[84:85]
	v_cndmask_b32_e64 v183, v197, v193, s[84:85]
	global_store_dwordx4 v232, v[180:183], s[90:91] offset:256
	v_mul_f32_e32 v80, v80, v155
	v_mul_f32_e32 v81, v81, v155
	v_pk_fma_f32 v[80:81], v[160:161], v[80:81], v[198:199]
	v_mul_f32_e32 v82, v82, v155
	v_mul_f32_e32 v83, v83, v155
	v_pk_fma_f32 v[82:83], v[162:163], v[82:83], v[200:201]
	v_cvt_pk_bf16_f32 v186, v80, v81
	v_cvt_pk_bf16_f32 v187, v82, v83
	v_mul_f32_e32 v72, v72, v155
	v_mul_f32_e32 v73, v73, v155
	v_pk_fma_f32 v[72:73], v[164:165], v[72:73], v[202:203]
	v_mul_f32_e32 v74, v74, v155
	v_mul_f32_e32 v75, v75, v155
	v_pk_fma_f32 v[74:75], v[166:167], v[74:75], v[204:205]
	v_cvt_pk_bf16_f32 v188, v72, v73
	v_cvt_pk_bf16_f32 v189, v74, v75
	v_mul_f32_e32 v68, v68, v155
	v_mul_f32_e32 v69, v69, v155
	v_pk_fma_f32 v[68:69], v[168:169], v[68:69], v[208:209]
	v_mul_f32_e32 v70, v70, v155
	v_mul_f32_e32 v71, v71, v155
	v_pk_fma_f32 v[70:71], v[170:171], v[70:71], v[210:211]
	v_cvt_pk_bf16_f32 v190, v68, v69
	v_cvt_pk_bf16_f32 v191, v70, v71
	v_mul_f32_e32 v64, v64, v155
	v_mul_f32_e32 v65, v65, v155
	v_pk_fma_f32 v[64:65], v[172:173], v[64:65], v[214:215]
	v_mul_f32_e32 v66, v66, v155
	v_mul_f32_e32 v67, v67, v155
	v_pk_fma_f32 v[66:67], v[174:175], v[66:67], v[216:217]
	v_cvt_pk_bf16_f32 v192, v64, v65
	v_cvt_pk_bf16_f32 v193, v66, v67
	v_add_u32_e32 v232, 0x18000, v239
	v_cndmask_b32_e64 v194, v188, v186, s[84:85]
	v_cndmask_b32_e64 v195, v189, v187, s[84:85]
	ds_bpermute_b32 v196, v233, v194
	ds_bpermute_b32 v197, v233, v195
	s_waitcnt lgkmcnt(0)
	v_cndmask_b32_e64 v176, v186, v196, s[84:85]
	v_cndmask_b32_e64 v177, v187, v197, s[84:85]
	v_cndmask_b32_e64 v178, v196, v188, s[84:85]
	v_cndmask_b32_e64 v179, v197, v189, s[84:85]
	global_store_dwordx4 v232, v[176:179], s[90:91]
	v_cndmask_b32_e64 v194, v192, v190, s[84:85]
	v_cndmask_b32_e64 v195, v193, v191, s[84:85]
	ds_bpermute_b32 v196, v233, v194
	ds_bpermute_b32 v197, v233, v195
	s_waitcnt lgkmcnt(0)
	v_cndmask_b32_e64 v180, v190, v196, s[84:85]
	v_cndmask_b32_e64 v181, v191, v197, s[84:85]
	v_cndmask_b32_e64 v182, v196, v192, s[84:85]
	v_cndmask_b32_e64 v183, v197, v193, s[84:85]
	global_store_dwordx4 v232, v[180:183], s[90:91] offset:256
	v_mul_f32_e32 v60, v60, v156
	v_mul_f32_e32 v61, v61, v156
	v_pk_fma_f32 v[60:61], v[160:161], v[60:61], v[198:199]
	v_mul_f32_e32 v62, v62, v156
	v_mul_f32_e32 v63, v63, v156
	v_pk_fma_f32 v[62:63], v[162:163], v[62:63], v[200:201]
	v_cvt_pk_bf16_f32 v186, v60, v61
	v_cvt_pk_bf16_f32 v187, v62, v63
	v_mul_f32_e32 v56, v56, v156
	v_mul_f32_e32 v57, v57, v156
	v_pk_fma_f32 v[56:57], v[164:165], v[56:57], v[202:203]
	v_mul_f32_e32 v58, v58, v156
	v_mul_f32_e32 v59, v59, v156
	v_pk_fma_f32 v[58:59], v[166:167], v[58:59], v[204:205]
	v_cvt_pk_bf16_f32 v188, v56, v57
	v_cvt_pk_bf16_f32 v189, v58, v59
	v_mul_f32_e32 v52, v52, v156
	v_mul_f32_e32 v53, v53, v156
	v_pk_fma_f32 v[52:53], v[168:169], v[52:53], v[208:209]
	v_mul_f32_e32 v54, v54, v156
	v_mul_f32_e32 v55, v55, v156
	v_pk_fma_f32 v[54:55], v[170:171], v[54:55], v[210:211]
	v_cvt_pk_bf16_f32 v190, v52, v53
	v_cvt_pk_bf16_f32 v191, v54, v55
	v_mul_f32_e32 v44, v44, v156
	v_mul_f32_e32 v45, v45, v156
	v_pk_fma_f32 v[44:45], v[172:173], v[44:45], v[214:215]
	v_mul_f32_e32 v46, v46, v156
	v_mul_f32_e32 v47, v47, v156
	v_pk_fma_f32 v[46:47], v[174:175], v[46:47], v[216:217]
	v_cvt_pk_bf16_f32 v192, v44, v45
	v_cvt_pk_bf16_f32 v193, v46, v47
	v_add_u32_e32 v232, 0x40000, v239
	v_cndmask_b32_e64 v194, v188, v186, s[84:85]
	v_cndmask_b32_e64 v195, v189, v187, s[84:85]
	ds_bpermute_b32 v196, v233, v194
	ds_bpermute_b32 v197, v233, v195
	s_waitcnt lgkmcnt(0)
; __device__ __forceinline__ unsigned cvtpk_s(float lo, float hi) { f32x2_t v = {lo, hi}; bf16x2_t b = __builtin_convertvector(v, bf16x2_t); return __builtin_bit_cast(unsigned, b); }
; __device__ __forceinline__ u32x4 quad_swap(unsigned lo0, unsigned lo1, unsigned hi0, unsigned hi1, int fq, int& coloff) {
;     const bool odd = fq & 1;
;     const unsigned s0 = odd ? lo0 : hi0, s1 = odd ? lo1 : hi1;
;     const unsigned r0 = (unsigned)__shfl_xor((int)s0, 16), r1 = (unsigned)__shfl_xor((int)s1, 16);
;     coloff = odd ? 16 + 4 * (fq - 1) : 4 * fq;
;     u32x4 o; o.x = odd ? r0 : lo0; o.y = odd ? r1 : lo1; o.z = odd ? hi0 : r0; o.w = odd ? hi1 : r1; return o;
; __device__ __forceinline__ void modpass(const float* xs_main, const float* xs_ctx, const float* mod_l, const float* g, int i, bf16_t* H, int nrows, int gw, int NGW, int lane) {
;     ...
;         for (int j = 0; j < 2; ++j) {
;             const f32x4 o0 = v[j][0] * rstd * gm[j][0] + sh[j][0], o1 = v[j][1] * rstd * gm[j][1] + sh[j][1];
;             u32x4 w; w.x = cvtpk_s(o0[0], o0[1]); w.y = cvtpk_s(o0[2], o0[3]); w.z = cvtpk_s(o1[0], o1[1]); w.w = cvtpk_s(o1[2], o1[3]);
;             *(u32x4*)(H + (size_t)row * D + 8 * lane + 512 * j) = w;
	v_cndmask_b32_e64 v176, v186, v196, s[84:85]
	v_cndmask_b32_e64 v177, v187, v197, s[84:85]
	v_cndmask_b32_e64 v178, v196, v188, s[84:85]
	v_cndmask_b32_e64 v179, v197, v189, s[84:85]
	global_store_dwordx4 v232, v[176:179], s[90:91]
	v_cndmask_b32_e64 v194, v192, v190, s[84:85]
	v_cndmask_b32_e64 v195, v193, v191, s[84:85]
	ds_bpermute_b32 v196, v233, v194
	ds_bpermute_b32 v197, v233, v195
	s_waitcnt lgkmcnt(0)
	v_cndmask_b32_e64 v180, v190, v196, s[84:85]
	v_cndmask_b32_e64 v181, v191, v197, s[84:85]
	v_cndmask_b32_e64 v182, v196, v192, s[84:85]
	v_cndmask_b32_e64 v183, v197, v193, s[84:85]
	global_store_dwordx4 v232, v[180:183], s[90:91] offset:256
	v_mul_f32_e32 v48, v48, v157
	v_mul_f32_e32 v49, v49, v157
	v_pk_fma_f32 v[48:49], v[160:161], v[48:49], v[198:199]
	v_mul_f32_e32 v50, v50, v157
	v_mul_f32_e32 v51, v51, v157
	v_pk_fma_f32 v[50:51], v[162:163], v[50:51], v[200:201]
	v_cvt_pk_bf16_f32 v186, v48, v49
	v_cvt_pk_bf16_f32 v187, v50, v51
	v_mul_f32_e32 v40, v40, v157
	v_mul_f32_e32 v41, v41, v157
	v_pk_fma_f32 v[40:41], v[164:165], v[40:41], v[202:203]
	v_mul_f32_e32 v42, v42, v157
	v_mul_f32_e32 v43, v43, v157
	v_pk_fma_f32 v[42:43], v[166:167], v[42:43], v[204:205]
	v_cvt_pk_bf16_f32 v188, v40, v41
	v_cvt_pk_bf16_f32 v189, v42, v43
	v_mul_f32_e32 v36, v36, v157
	v_mul_f32_e32 v37, v37, v157
	v_pk_fma_f32 v[36:37], v[168:169], v[36:37], v[208:209]
	v_mul_f32_e32 v38, v38, v157
	v_mul_f32_e32 v39, v39, v157
	v_pk_fma_f32 v[38:39], v[170:171], v[38:39], v[210:211]
	v_cvt_pk_bf16_f32 v190, v36, v37
	v_cvt_pk_bf16_f32 v191, v38, v39
	v_mul_f32_e32 v28, v28, v157
	v_mul_f32_e32 v29, v29, v157
	v_pk_fma_f32 v[28:29], v[172:173], v[28:29], v[214:215]
	v_mul_f32_e32 v30, v30, v157
	v_mul_f32_e32 v31, v31, v157
	v_pk_fma_f32 v[30:31], v[174:175], v[30:31], v[216:217]
	v_cvt_pk_bf16_f32 v192, v28, v29
	v_cvt_pk_bf16_f32 v193, v30, v31
	v_add_u32_e32 v232, 0x48000, v239
	v_cndmask_b32_e64 v194, v188, v186, s[84:85]
	v_cndmask_b32_e64 v195, v189, v187, s[84:85]
	ds_bpermute_b32 v196, v233, v194
	ds_bpermute_b32 v197, v233, v195
	s_waitcnt lgkmcnt(0)
	v_cndmask_b32_e64 v176, v186, v196, s[84:85]
	v_cndmask_b32_e64 v177, v187, v197, s[84:85]
	v_cndmask_b32_e64 v178, v196, v188, s[84:85]
	v_cndmask_b32_e64 v179, v197, v189, s[84:85]
	global_store_dwordx4 v232, v[176:179], s[90:91]
	v_cndmask_b32_e64 v194, v192, v190, s[84:85]
	v_cndmask_b32_e64 v195, v193, v191, s[84:85]
	ds_bpermute_b32 v196, v233, v194
	ds_bpermute_b32 v197, v233, v195
	s_waitcnt lgkmcnt(0)
	v_cndmask_b32_e64 v180, v190, v196, s[84:85]
	v_cndmask_b32_e64 v181, v191, v197, s[84:85]
	v_cndmask_b32_e64 v182, v196, v192, s[84:85]
	v_cndmask_b32_e64 v183, v197, v193, s[84:85]
	global_store_dwordx4 v232, v[180:183], s[90:91] offset:256
	v_mul_f32_e32 v32, v32, v158
	v_mul_f32_e32 v33, v33, v158
	v_pk_fma_f32 v[32:33], v[160:161], v[32:33], v[198:199]
	v_mul_f32_e32 v34, v34, v158
	v_mul_f32_e32 v35, v35, v158
	v_pk_fma_f32 v[34:35], v[162:163], v[34:35], v[200:201]
	v_cvt_pk_bf16_f32 v186, v32, v33
	v_cvt_pk_bf16_f32 v187, v34, v35
	v_mul_f32_e32 v24, v24, v158
	v_mul_f32_e32 v25, v25, v158
	v_pk_fma_f32 v[24:25], v[164:165], v[24:25], v[202:203]
	v_mul_f32_e32 v26, v26, v158
	v_mul_f32_e32 v27, v27, v158
	v_pk_fma_f32 v[26:27], v[166:167], v[26:27], v[204:205]
	v_cvt_pk_bf16_f32 v188, v24, v25
	v_cvt_pk_bf16_f32 v189, v26, v27
	v_mul_f32_e32 v20, v20, v158
	v_mul_f32_e32 v21, v21, v158
	v_pk_fma_f32 v[20:21], v[168:169], v[20:21], v[208:209]
	v_mul_f32_e32 v22, v22, v158
	v_mul_f32_e32 v23, v23, v158
	v_pk_fma_f32 v[22:23], v[170:171], v[22:23], v[210:211]
	v_cvt_pk_bf16_f32 v190, v20, v21
	v_cvt_pk_bf16_f32 v191, v22, v23
	v_mul_f32_e32 v12, v12, v158
	v_mul_f32_e32 v13, v13, v158
	v_pk_fma_f32 v[12:13], v[172:173], v[12:13], v[214:215]
	v_mul_f32_e32 v14, v14, v158
	v_mul_f32_e32 v15, v15, v158
	v_pk_fma_f32 v[14:15], v[174:175], v[14:15], v[216:217]
	v_cvt_pk_bf16_f32 v192, v12, v13
	v_cvt_pk_bf16_f32 v193, v14, v15
	v_add_u32_e32 v232, 0x50000, v239
	v_cndmask_b32_e64 v194, v188, v186, s[84:85]
	v_cndmask_b32_e64 v195, v189, v187, s[84:85]
	ds_bpermute_b32 v196, v233, v194
	ds_bpermute_b32 v197, v233, v195
	s_waitcnt lgkmcnt(0)
	v_cndmask_b32_e64 v176, v186, v196, s[84:85]
	v_cndmask_b32_e64 v177, v187, v197, s[84:85]
	v_cndmask_b32_e64 v178, v196, v188, s[84:85]
	v_cndmask_b32_e64 v179, v197, v189, s[84:85]
	global_store_dwordx4 v232, v[176:179], s[90:91]
	v_cndmask_b32_e64 v194, v192, v190, s[84:85]
	v_cndmask_b32_e64 v195, v193, v191, s[84:85]
	ds_bpermute_b32 v196, v233, v194
	ds_bpermute_b32 v197, v233, v195
	s_waitcnt lgkmcnt(0)
	v_cndmask_b32_e64 v180, v190, v196, s[84:85]
	v_cndmask_b32_e64 v181, v191, v197, s[84:85]
	v_cndmask_b32_e64 v182, v196, v192, s[84:85]
	v_cndmask_b32_e64 v183, v197, v193, s[84:85]
	global_store_dwordx4 v232, v[180:183], s[90:91] offset:256
	v_mul_f32_e32 v16, v16, v159
	v_mul_f32_e32 v17, v17, v159
	v_pk_fma_f32 v[16:17], v[160:161], v[16:17], v[198:199]
	v_mul_f32_e32 v18, v18, v159
	v_mul_f32_e32 v19, v19, v159
	v_pk_fma_f32 v[18:19], v[162:163], v[18:19], v[200:201]
	v_cvt_pk_bf16_f32 v186, v16, v17
	v_cvt_pk_bf16_f32 v187, v18, v19
	v_mul_f32_e32 v8, v8, v159
	v_mul_f32_e32 v9, v9, v159
	v_pk_fma_f32 v[8:9], v[164:165], v[8:9], v[202:203]
	v_mul_f32_e32 v10, v10, v159
	v_mul_f32_e32 v11, v11, v159
	v_pk_fma_f32 v[10:11], v[166:167], v[10:11], v[204:205]
	v_cvt_pk_bf16_f32 v188, v8, v9
	v_cvt_pk_bf16_f32 v189, v10, v11
	v_mul_f32_e32 v4, v4, v159
	v_mul_f32_e32 v5, v5, v159
	v_pk_fma_f32 v[4:5], v[168:169], v[4:5], v[208:209]
	v_mul_f32_e32 v6, v6, v159
	v_mul_f32_e32 v7, v7, v159
	v_pk_fma_f32 v[6:7], v[170:171], v[6:7], v[210:211]
	v_cvt_pk_bf16_f32 v190, v4, v5
	v_cvt_pk_bf16_f32 v191, v6, v7
	v_mul_f32_e32 v0, v0, v159
	v_mul_f32_e32 v1, v1, v159
	v_pk_fma_f32 v[0:1], v[172:173], v[0:1], v[214:215]
	v_mul_f32_e32 v2, v2, v159
	v_mul_f32_e32 v3, v3, v159
	v_pk_fma_f32 v[2:3], v[174:175], v[2:3], v[216:217]
	v_cvt_pk_bf16_f32 v192, v0, v1
	v_cvt_pk_bf16_f32 v193, v2, v3
	v_add_u32_e32 v232, 0x58000, v239
	v_cndmask_b32_e64 v194, v188, v186, s[84:85]
	v_cndmask_b32_e64 v195, v189, v187, s[84:85]
	ds_bpermute_b32 v196, v233, v194
	ds_bpermute_b32 v197, v233, v195
	s_waitcnt lgkmcnt(0)
	v_cndmask_b32_e64 v176, v186, v196, s[84:85]
	v_cndmask_b32_e64 v177, v187, v197, s[84:85]
	v_cndmask_b32_e64 v178, v196, v188, s[84:85]
	v_cndmask_b32_e64 v179, v197, v189, s[84:85]
	global_store_dwordx4 v232, v[176:179], s[90:91]
	v_cndmask_b32_e64 v194, v192, v190, s[84:85]
	v_cndmask_b32_e64 v195, v193, v191, s[84:85]
	ds_bpermute_b32 v196, v233, v194
	ds_bpermute_b32 v197, v233, v195
	s_waitcnt lgkmcnt(0)
	v_cndmask_b32_e64 v180, v190, v196, s[84:85]
	v_cndmask_b32_e64 v181, v191, v197, s[84:85]
	v_cndmask_b32_e64 v182, v196, v192, s[84:85]
	v_cndmask_b32_e64 v183, v197, v193, s[84:85]
	global_store_dwordx4 v232, v[180:183], s[90:91] offset:256
	s_and_b64 vcc, exec, s[4:5]
	s_mov_b64 s[4:5], -1
	s_cbranch_vccnz .LBB0_300
	s_andn2_b64 vcc, exec, s[12:13]
	s_cbranch_vccnz .LBB0_299
	s_barrier
	s_branch .LBB0_299

; __device__ __forceinline__ void modpass(const float* xs_main, const float* xs_ctx, const float* mod_l, const float* g, int i, bf16_t* H, int nrows, int gw, int NGW, int lane) {
;     f32x4 gm[2][2], sh[2][2], v[2][2], vn[2][2]; int cur = -1;
;     int row = gw;
;     if (row < nrows) { const float* xr = row < MX ? xs_main + (size_t)row * D : xs_ctx + (size_t)(row - MX) * D;
; #pragma unroll
;         for (int j = 0; j < 2; ++j) { v[j][0] = *(const f32x4*)(xr + 8 * lane + 512 * j); v[j][1] = *(const f32x4*)(xr + 8 * lane + 512 * j + 4); } }
;     for (; row < nrows; row += NGW) {
;         const int nrow = row + NGW;
;         if (nrow < nrows) { const float* xr = nrow < MX ? xs_main + (size_t)nrow * D : xs_ctx + (size_t)(nrow - MX) * D;
; #pragma unroll
;             for (int j = 0; j < 2; ++j) { vn[j][0] = *(const f32x4*)(xr + 8 * lane + 512 * j); vn[j][1] = *(const f32x4*)(xr + 8 * lane + 512 * j + 4); } }
.LBB0_376:
	s_or_b64 exec, exec, s[4:5]
	s_mov_b64 s[6:7], s[0:1]
	v_mov_b32_e32 v2, v206
	s_waitcnt lgkmcnt(0)
	s_barrier
	s_nop 0
	v_readfirstlane_b32 s3, v2
	s_ashr_i32 s3, s3, 6
	s_add_i32 s4, s3, s33
	s_add_i32 s4, s4, 0x8000
	s_cmp_gt_i32 s4, 0x81ff
	s_cbranch_scc1 .LBB0_383
	s_load_dwordx4 s[8:11], s[6:7], 0xb0
	s_load_dwordx2 s[14:15], s[6:7], 0x30
	v_lshlrev_b32_e32 v0, 3, v2
	v_and_b32_e32 v64, 0x1f8, v0
	v_lshlrev_b32_e32 v0, 2, v64
	s_waitcnt lgkmcnt(0)
	s_add_u32 s3, s10, 0x6300000
	s_addc_u32 s12, s11, 0
	s_add_u32 s6, s14, 0x1000
	s_addc_u32 s7, s15, 0
	s_add_i32 s13, s4, 0xffff8000
	s_ashr_i32 s5, s4, 31
	s_cmp_lt_i32 s4, 0x8000
	s_cselect_b32 s15, s5, 0
	s_cselect_b32 s14, s4, s13
	s_cselect_b32 s13, s9, s12
	s_cselect_b32 s16, s8, s3
	s_lshl_b64 s[14:15], s[14:15], 12
	s_add_u32 s14, s16, s14
	s_addc_u32 s15, s13, s15
	global_load_dwordx4 v[12:15], v0, s[14:15] offset:16
	global_load_dwordx4 v[16:19], v0, s[14:15]
	global_load_dwordx4 v[4:7], v0, s[14:15] offset:2064
	global_load_dwordx4 v[8:11], v0, s[14:15] offset:2048
	v_mbcnt_hi_u32_b32 v3, -1, v212
	v_and_b32_e32 v20, 64, v3
	v_add_u32_e32 v20, 64, v20
	v_xor_b32_e32 v21, 1, v3
	v_cmp_lt_i32_e32 vcc, v21, v20
	v_mov_b32_e32 v1, 0
	s_add_u32 s13, s10, 0x3000
	v_cndmask_b32_e32 v21, v3, v21, vcc
	v_lshlrev_b32_e32 v65, 2, v21
	v_xor_b32_e32 v21, 2, v3
	v_cmp_lt_i32_e32 vcc, v21, v20
	v_lshl_add_u64 v[66:67], s[6:7], 0, v[0:1]
	s_addc_u32 s14, s11, 0
	v_cndmask_b32_e32 v21, v3, v21, vcc
	v_lshlrev_b32_e32 v72, 2, v21
	v_xor_b32_e32 v21, 4, v3
	v_cmp_lt_i32_e32 vcc, v21, v20
	s_mov_b32 s22, -1
	v_mov_b32_e32 v78, 0x358637bd
	v_cndmask_b32_e32 v21, v3, v21, vcc
	v_lshlrev_b32_e32 v73, 2, v21
	v_xor_b32_e32 v21, 8, v3
	v_cmp_lt_i32_e32 vcc, v21, v20
	s_mov_b32 s21, 0xf800000
	v_mov_b32_e32 v79, 0x260
	v_cndmask_b32_e32 v21, v3, v21, vcc
	v_lshlrev_b32_e32 v74, 2, v21
	v_xor_b32_e32 v21, 16, v3
	v_cmp_lt_i32_e32 vcc, v21, v20
	v_mov_b32_e32 v22, v1
	v_mov_b32_e32 v23, v1
	v_cndmask_b32_e32 v21, v3, v21, vcc
	v_lshlrev_b32_e32 v75, 2, v21
	v_xor_b32_e32 v21, 32, v3
	v_cmp_lt_i32_e32 vcc, v21, v20
	v_or_b32_e32 v20, 0x200, v64
	v_lshlrev_b32_e32 v0, 2, v20
	v_lshl_add_u64 v[68:69], s[6:7], 0, v[0:1]
	s_lshl_b64 s[6:7], s[4:5], 11
	v_and_b32_e32 v0, 63, v2
	s_add_u32 s6, s10, s6
	v_cndmask_b32_e32 v3, v3, v21, vcc
	v_lshlrev_b32_e32 v0, 4, v0
	s_addc_u32 s7, s11, s7
	v_lshlrev_b32_e32 v76, 2, v3
	v_lshl_add_u64 v[2:3], s[6:7], 0, v[0:1]
	s_mov_b64 s[6:7], 0x6500400
	s_ashr_i32 s29, s28, 31
	s_add_i32 s15, s4, s28
	v_lshl_add_u64 v[70:71], v[2:3], 0, s[6:7]
	s_lshl_b64 s[6:7], s[28:29], 11
	s_ashr_i32 s20, s15, 31
	v_lshlrev_b32_e32 v77, 2, v20
	v_mov_b32_e32 v0, v1
	v_mov_b32_e32 v2, v1
	v_mov_b32_e32 v3, v1
	v_mov_b32_e32 v20, v1
	v_mov_b32_e32 v21, v1
	v_mov_b32_e32 v28, v1
	v_mov_b32_e32 v29, v1
	v_mov_b32_e32 v30, v1
	v_mov_b32_e32 v31, v1
	v_mov_b32_e32 v24, v1
	v_mov_b32_e32 v25, v1
	v_mov_b32_e32 v26, v1
	v_mov_b32_e32 v27, v1
	s_branch .LBB0_379

;     __device__ __forceinline__ void operator()(const f32x4 (&acc)[2][2][4][2], const Unit& u, int wr, int wc, int fr, int fq) const {
;     ...
;         const int col0 = u.pn * BM + wc * 32 + 4 * fq;
;         f32x4 gv[2][2];
; #pragma unroll
;         for (int bj = 0; bj < 2; ++bj)
; #pragma unroll
;             for (int n = 0; n < 2; ++n) gv[bj][n] = *(const f32x4*)(gate + col0 + bj * HALF + n * 16) * coef;
; #pragma unroll
;         for (int ai = 0; ai < 2; ++ai)
; #pragma unroll
;             for (int m = 0; m < 4; ++m) {
;                 const int row = u.pm * BM + ai * HALF + wr * 64 + m * 16 + fr;
;                 const float* s = row < MX_ ? src_main + (size_t)row * D_ : src_ctx + (size_t)(row - MX_) * D_;
;                 float* d = row < MX_ ? dst_main + (size_t)row * D_ : dst_ctx + (size_t)(row - MX_) * D_;
; #pragma unroll
;                 for (int bj = 0; bj < 2; ++bj)
; #pragma unroll
;                     for (int n = 0; n < 2; ++n) { const int off = col0 + bj * HALF + n * 16; const f32x4 xo = *(const f32x4*)(s + off); *(f32x4*)(d + off) = xo + gv[bj][n] * acc[ai][bj][m][n]; }
.LBB0_1126:
	s_cmpk_lt_i32 s40, 0x80
	s_cselect_b32 s7, s69, 0x4800
	s_cmp_gt_i32 s40, 63
	s_cselect_b32 s7, s7, 0
	s_lshl_b32 s7, s7, 2
	s_add_u32 s8, s61, s7
	s_addc_u32 s9, s62, 0
	s_load_dwordx2 s[92:93], s[0:1], 0x30
	s_load_dwordx2 s[76:77], s[0:1], 0xb8
	v_lshl_add_u32 v156, s40, 8, v158
	v_lshl_or_b32 v157, s6, 8, v160
	v_lshlrev_b32_e32 v201, 2, v157
	v_lshl_add_u32 v224, v156, 12, v201
	global_load_dwordx4 v[196:199], v201, s[8:9]
	global_load_dwordx4 v[212:215], v201, s[8:9] offset:64
	global_load_dwordx4 v[216:219], v201, s[8:9] offset:512
	global_load_dwordx4 v[220:223], v201, s[8:9] offset:576
	v_add_u32_e32 v225, 0x10000, v224
	v_add_u32_e32 v226, 0x20000, v224
	v_add_u32_e32 v227, 0x30000, v224
	v_add_u32_e32 v228, 0x80000, v224
	v_add_u32_e32 v229, 0x90000, v224
	v_add_u32_e32 v230, 0xa0000, v224
	v_add_u32_e32 v231, 0xb0000, v224
	global_load_dwordx4 v[128:131], v224, s[12:13]
	global_load_dwordx4 v[132:135], v224, s[12:13] offset:64
	global_load_dwordx4 v[136:139], v224, s[12:13] offset:512
	global_load_dwordx4 v[140:143], v224, s[12:13] offset:576
	global_load_dwordx4 v[164:167], v225, s[12:13]
	global_load_dwordx4 v[168:171], v225, s[12:13] offset:64
	global_load_dwordx4 v[172:175], v225, s[12:13] offset:512
	global_load_dwordx4 v[176:179], v225, s[12:13] offset:576
	global_load_dwordx4 v[180:183], v226, s[12:13]
	global_load_dwordx4 v[184:187], v226, s[12:13] offset:64
	global_load_dwordx4 v[188:191], v226, s[12:13] offset:512
	global_load_dwordx4 v[192:195], v226, s[12:13] offset:576
	s_waitcnt vmcnt(12)
	s_waitcnt vmcnt(11)
	v_pk_fma_f32 v[124:125], v[124:125], v[196:197], v[128:129]
	v_pk_fma_f32 v[126:127], v[126:127], v[198:199], v[130:131]
	v_mul_f32_e32 v232, v124, v124
	v_fmac_f32_e32 v232, v125, v125
	v_fmac_f32_e32 v232, v126, v126
	v_fmac_f32_e32 v232, v127, v127
	s_waitcnt vmcnt(10)
	v_pk_fma_f32 v[120:121], v[120:121], v[212:213], v[132:133]
	v_pk_fma_f32 v[122:123], v[122:123], v[214:215], v[134:135]
	v_fmac_f32_e32 v232, v120, v120
	v_fmac_f32_e32 v232, v121, v121
	v_fmac_f32_e32 v232, v122, v122
	v_fmac_f32_e32 v232, v123, v123
	s_waitcnt vmcnt(9)
	v_pk_fma_f32 v[116:117], v[116:117], v[216:217], v[136:137]
	v_pk_fma_f32 v[118:119], v[118:119], v[218:219], v[138:139]
	v_fmac_f32_e32 v232, v116, v116
	v_fmac_f32_e32 v232, v117, v117
	v_fmac_f32_e32 v232, v118, v118
	v_fmac_f32_e32 v232, v119, v119
	s_waitcnt vmcnt(8)
	v_pk_fma_f32 v[112:113], v[112:113], v[220:221], v[140:141]
	v_pk_fma_f32 v[114:115], v[114:115], v[222:223], v[142:143]
	v_fmac_f32_e32 v232, v112, v112
	v_fmac_f32_e32 v232, v113, v113
	v_fmac_f32_e32 v232, v114, v114
	v_fmac_f32_e32 v232, v115, v115
	global_store_dwordx4 v224, v[124:127], s[12:13]
	global_store_dwordx4 v224, v[120:123], s[12:13] offset:64
	global_store_dwordx4 v224, v[116:119], s[12:13] offset:512
	global_store_dwordx4 v224, v[112:115], s[12:13] offset:576
	global_load_dwordx4 v[128:131], v227, s[12:13]
	global_load_dwordx4 v[132:135], v227, s[12:13] offset:64
	global_load_dwordx4 v[136:139], v227, s[12:13] offset:512
	global_load_dwordx4 v[140:143], v227, s[12:13] offset:576
	s_waitcnt vmcnt(15)
	v_pk_fma_f32 v[108:109], v[108:109], v[196:197], v[164:165]
	v_pk_fma_f32 v[110:111], v[110:111], v[198:199], v[166:167]
	v_mul_f32_e32 v233, v108, v108
	v_fmac_f32_e32 v233, v109, v109
	v_fmac_f32_e32 v233, v110, v110
	v_fmac_f32_e32 v233, v111, v111
	s_waitcnt vmcnt(14)
	v_pk_fma_f32 v[104:105], v[104:105], v[212:213], v[168:169]
	v_pk_fma_f32 v[106:107], v[106:107], v[214:215], v[170:171]
	v_fmac_f32_e32 v233, v104, v104
	v_fmac_f32_e32 v233, v105, v105
	v_fmac_f32_e32 v233, v106, v106
	v_fmac_f32_e32 v233, v107, v107
	s_waitcnt vmcnt(13)
	v_pk_fma_f32 v[100:101], v[100:101], v[216:217], v[172:173]
	v_pk_fma_f32 v[102:103], v[102:103], v[218:219], v[174:175]
	v_fmac_f32_e32 v233, v100, v100
	v_fmac_f32_e32 v233, v101, v101
	v_fmac_f32_e32 v233, v102, v102
	v_fmac_f32_e32 v233, v103, v103
	s_waitcnt vmcnt(12)
	v_pk_fma_f32 v[96:97], v[96:97], v[220:221], v[176:177]
	v_pk_fma_f32 v[98:99], v[98:99], v[222:223], v[178:179]
	v_fmac_f32_e32 v233, v96, v96
	v_fmac_f32_e32 v233, v97, v97
	v_fmac_f32_e32 v233, v98, v98
	v_fmac_f32_e32 v233, v99, v99
	global_store_dwordx4 v225, v[108:111], s[12:13]
	global_store_dwordx4 v225, v[104:107], s[12:13] offset:64
	global_store_dwordx4 v225, v[100:103], s[12:13] offset:512
	global_store_dwordx4 v225, v[96:99], s[12:13] offset:576
	global_load_dwordx4 v[164:167], v228, s[12:13]
	global_load_dwordx4 v[168:171], v228, s[12:13] offset:64
	global_load_dwordx4 v[172:175], v228, s[12:13] offset:512
	global_load_dwordx4 v[176:179], v228, s[12:13] offset:576
	s_waitcnt vmcnt(19)
	v_pk_fma_f32 v[92:93], v[92:93], v[196:197], v[180:181]
	v_pk_fma_f32 v[94:95], v[94:95], v[198:199], v[182:183]
	v_mul_f32_e32 v234, v92, v92
	v_fmac_f32_e32 v234, v93, v93
	v_fmac_f32_e32 v234, v94, v94
	v_fmac_f32_e32 v234, v95, v95
	s_waitcnt vmcnt(18)
	v_pk_fma_f32 v[88:89], v[88:89], v[212:213], v[184:185]
	v_pk_fma_f32 v[90:91], v[90:91], v[214:215], v[186:187]
	v_fmac_f32_e32 v234, v88, v88
	v_fmac_f32_e32 v234, v89, v89
	v_fmac_f32_e32 v234, v90, v90
	v_fmac_f32_e32 v234, v91, v91
	s_waitcnt vmcnt(17)
	v_pk_fma_f32 v[84:85], v[84:85], v[216:217], v[188:189]
	v_pk_fma_f32 v[86:87], v[86:87], v[218:219], v[190:191]
	v_fmac_f32_e32 v234, v84, v84
	v_fmac_f32_e32 v234, v85, v85
	v_fmac_f32_e32 v234, v86, v86
	v_fmac_f32_e32 v234, v87, v87
	s_waitcnt vmcnt(16)
;     __device__ __forceinline__ void operator()(const f32x4 (&acc)[2][2][4][2], const Unit& u, int wr, int wc, int fr, int fq) const {
;     ...
;         for (int ai = 0; ai < 2; ++ai)
; #pragma unroll
;             for (int m = 0; m < 4; ++m) {
;                 const int row = u.pm * BM + ai * HALF + wr * 64 + m * 16 + fr;
;                 const float* s = row < MX_ ? src_main + (size_t)row * D_ : src_ctx + (size_t)(row - MX_) * D_;
;                 float* d = row < MX_ ? dst_main + (size_t)row * D_ : dst_ctx + (size_t)(row - MX_) * D_;
; #pragma unroll
;                 for (int bj = 0; bj < 2; ++bj)
; #pragma unroll
;                     for (int n = 0; n < 2; ++n) { const int off = col0 + bj * HALF + n * 16; const f32x4 xo = *(const f32x4*)(s + off); *(f32x4*)(d + off) = xo + gv[bj][n] * acc[ai][bj][m][n]; }
	v_pk_fma_f32 v[80:81], v[80:81], v[220:221], v[192:193]
	v_pk_fma_f32 v[82:83], v[82:83], v[222:223], v[194:195]
	v_fmac_f32_e32 v234, v80, v80
	v_fmac_f32_e32 v234, v81, v81
	v_fmac_f32_e32 v234, v82, v82
	v_fmac_f32_e32 v234, v83, v83
	global_store_dwordx4 v226, v[92:95], s[12:13]
	global_store_dwordx4 v226, v[88:91], s[12:13] offset:64
	global_store_dwordx4 v226, v[84:87], s[12:13] offset:512
	global_store_dwordx4 v226, v[80:83], s[12:13] offset:576
	global_load_dwordx4 v[180:183], v229, s[12:13]
	global_load_dwordx4 v[184:187], v229, s[12:13] offset:64
	global_load_dwordx4 v[188:191], v229, s[12:13] offset:512
	global_load_dwordx4 v[192:195], v229, s[12:13] offset:576
	s_waitcnt vmcnt(19)
	v_pk_fma_f32 v[76:77], v[76:77], v[196:197], v[128:129]
	v_pk_fma_f32 v[78:79], v[78:79], v[198:199], v[130:131]
	v_mul_f32_e32 v235, v76, v76
	v_fmac_f32_e32 v235, v77, v77
	v_fmac_f32_e32 v235, v78, v78
	v_fmac_f32_e32 v235, v79, v79
	s_waitcnt vmcnt(18)
	v_pk_fma_f32 v[72:73], v[72:73], v[212:213], v[132:133]
	v_pk_fma_f32 v[74:75], v[74:75], v[214:215], v[134:135]
	v_fmac_f32_e32 v235, v72, v72
	v_fmac_f32_e32 v235, v73, v73
	v_fmac_f32_e32 v235, v74, v74
	v_fmac_f32_e32 v235, v75, v75
	s_waitcnt vmcnt(17)
	v_pk_fma_f32 v[68:69], v[68:69], v[216:217], v[136:137]
	v_pk_fma_f32 v[70:71], v[70:71], v[218:219], v[138:139]
	v_fmac_f32_e32 v235, v68, v68
	v_fmac_f32_e32 v235, v69, v69
	v_fmac_f32_e32 v235, v70, v70
	v_fmac_f32_e32 v235, v71, v71
	s_waitcnt vmcnt(16)
	v_pk_fma_f32 v[64:65], v[64:65], v[220:221], v[140:141]
	v_pk_fma_f32 v[66:67], v[66:67], v[222:223], v[142:143]
	v_fmac_f32_e32 v235, v64, v64
	v_fmac_f32_e32 v235, v65, v65
	v_fmac_f32_e32 v235, v66, v66
	v_fmac_f32_e32 v235, v67, v67
	global_store_dwordx4 v227, v[76:79], s[12:13]
	global_store_dwordx4 v227, v[72:75], s[12:13] offset:64
	global_store_dwordx4 v227, v[68:71], s[12:13] offset:512
	global_store_dwordx4 v227, v[64:67], s[12:13] offset:576
	global_load_dwordx4 v[128:131], v230, s[12:13]
	global_load_dwordx4 v[132:135], v230, s[12:13] offset:64
	global_load_dwordx4 v[136:139], v230, s[12:13] offset:512
	global_load_dwordx4 v[140:143], v230, s[12:13] offset:576
	s_waitcnt vmcnt(19)
	v_pk_fma_f32 v[60:61], v[60:61], v[196:197], v[164:165]
	v_pk_fma_f32 v[62:63], v[62:63], v[198:199], v[166:167]
	v_mul_f32_e32 v236, v60, v60
	v_fmac_f32_e32 v236, v61, v61
	v_fmac_f32_e32 v236, v62, v62
	v_fmac_f32_e32 v236, v63, v63
	s_waitcnt vmcnt(18)
	v_pk_fma_f32 v[56:57], v[56:57], v[212:213], v[168:169]
	v_pk_fma_f32 v[58:59], v[58:59], v[214:215], v[170:171]
	v_fmac_f32_e32 v236, v56, v56
	v_fmac_f32_e32 v236, v57, v57
	v_fmac_f32_e32 v236, v58, v58
	v_fmac_f32_e32 v236, v59, v59
	s_waitcnt vmcnt(17)
	v_pk_fma_f32 v[52:53], v[52:53], v[216:217], v[172:173]
	v_pk_fma_f32 v[54:55], v[54:55], v[218:219], v[174:175]
	v_fmac_f32_e32 v236, v52, v52
	v_fmac_f32_e32 v236, v53, v53
	v_fmac_f32_e32 v236, v54, v54
	v_fmac_f32_e32 v236, v55, v55
	s_waitcnt vmcnt(16)
	v_pk_fma_f32 v[48:49], v[48:49], v[220:221], v[176:177]
	v_pk_fma_f32 v[50:51], v[50:51], v[222:223], v[178:179]
	v_fmac_f32_e32 v236, v48, v48
	v_fmac_f32_e32 v236, v49, v49
	v_fmac_f32_e32 v236, v50, v50
	v_fmac_f32_e32 v236, v51, v51
	global_store_dwordx4 v228, v[60:63], s[12:13]
	global_store_dwordx4 v228, v[56:59], s[12:13] offset:64
	global_store_dwordx4 v228, v[52:55], s[12:13] offset:512
	global_store_dwordx4 v228, v[48:51], s[12:13] offset:576
	global_load_dwordx4 v[164:167], v231, s[12:13]
	global_load_dwordx4 v[168:171], v231, s[12:13] offset:64
	global_load_dwordx4 v[172:175], v231, s[12:13] offset:512
	global_load_dwordx4 v[176:179], v231, s[12:13] offset:576
	s_waitcnt vmcnt(19)
	v_pk_fma_f32 v[44:45], v[44:45], v[196:197], v[180:181]
	v_pk_fma_f32 v[46:47], v[46:47], v[198:199], v[182:183]
	v_mul_f32_e32 v237, v44, v44
	v_fmac_f32_e32 v237, v45, v45
	v_fmac_f32_e32 v237, v46, v46
	v_fmac_f32_e32 v237, v47, v47
	s_waitcnt vmcnt(18)
	v_pk_fma_f32 v[40:41], v[40:41], v[212:213], v[184:185]
	v_pk_fma_f32 v[42:43], v[42:43], v[214:215], v[186:187]
	v_fmac_f32_e32 v237, v40, v40
	v_fmac_f32_e32 v237, v41, v41
	v_fmac_f32_e32 v237, v42, v42
	v_fmac_f32_e32 v237, v43, v43
	s_waitcnt vmcnt(17)
	v_pk_fma_f32 v[36:37], v[36:37], v[216:217], v[188:189]
	v_pk_fma_f32 v[38:39], v[38:39], v[218:219], v[190:191]
	v_fmac_f32_e32 v237, v36, v36
	v_fmac_f32_e32 v237, v37, v37
	v_fmac_f32_e32 v237, v38, v38
	v_fmac_f32_e32 v237, v39, v39
	s_waitcnt vmcnt(16)
	v_pk_fma_f32 v[32:33], v[32:33], v[220:221], v[192:193]
	v_pk_fma_f32 v[34:35], v[34:35], v[222:223], v[194:195]
	v_fmac_f32_e32 v237, v32, v32
	v_fmac_f32_e32 v237, v33, v33
	v_fmac_f32_e32 v237, v34, v34
	v_fmac_f32_e32 v237, v35, v35
	global_store_dwordx4 v229, v[44:47], s[12:13]
	global_store_dwordx4 v229, v[40:43], s[12:13] offset:64
	global_store_dwordx4 v229, v[36:39], s[12:13] offset:512
	global_store_dwordx4 v229, v[32:35], s[12:13] offset:576
	s_waitcnt vmcnt(15)
	v_pk_fma_f32 v[28:29], v[28:29], v[196:197], v[128:129]
	v_pk_fma_f32 v[30:31], v[30:31], v[198:199], v[130:131]
	v_mul_f32_e32 v238, v28, v28
	v_fmac_f32_e32 v238, v29, v29
	v_fmac_f32_e32 v238, v30, v30
	v_fmac_f32_e32 v238, v31, v31
	s_waitcnt vmcnt(14)
;     __device__ __forceinline__ void operator()(const f32x4 (&acc)[2][2][4][2], const Unit& u, int wr, int wc, int fr, int fq) const {
;     ...
;         for (int ai = 0; ai < 2; ++ai)
; #pragma unroll
;             for (int m = 0; m < 4; ++m) {
;                 const int row = u.pm * BM + ai * HALF + wr * 64 + m * 16 + fr;
;                 const float* s = row < MX_ ? src_main + (size_t)row * D_ : src_ctx + (size_t)(row - MX_) * D_;
;                 float* d = row < MX_ ? dst_main + (size_t)row * D_ : dst_ctx + (size_t)(row - MX_) * D_;
; #pragma unroll
;                 for (int bj = 0; bj < 2; ++bj)
; #pragma unroll
;                     for (int n = 0; n < 2; ++n) { const int off = col0 + bj * HALF + n * 16; const f32x4 xo = *(const f32x4*)(s + off); *(f32x4*)(d + off) = xo + gv[bj][n] * acc[ai][bj][m][n]; }
;     __device__ __forceinline__ void operator()(const f32x4 (&acc)[2][2][4][2], const Unit& u, int wr, int wc, int fr, int fq) const {
;     ...
;                         s1 += __shfl_xor(s1, 16); s1 += __shfl_xor(s1, 32); s2 += __shfl_xor(s2, 16); s2 += __shfl_xor(s2, 32);
;                         if (fq == 0) { unsafeAtomicAdd(stats + 2 * row, s1); unsafeAtomicAdd(stats + 2 * row + 1, s2); }
	v_pk_fma_f32 v[24:25], v[24:25], v[212:213], v[132:133]
	v_pk_fma_f32 v[26:27], v[26:27], v[214:215], v[134:135]
	v_fmac_f32_e32 v238, v24, v24
	v_fmac_f32_e32 v238, v25, v25
	v_fmac_f32_e32 v238, v26, v26
	v_fmac_f32_e32 v238, v27, v27
	s_waitcnt vmcnt(13)
	v_pk_fma_f32 v[20:21], v[20:21], v[216:217], v[136:137]
	v_pk_fma_f32 v[22:23], v[22:23], v[218:219], v[138:139]
	v_fmac_f32_e32 v238, v20, v20
	v_fmac_f32_e32 v238, v21, v21
	v_fmac_f32_e32 v238, v22, v22
	v_fmac_f32_e32 v238, v23, v23
	s_waitcnt vmcnt(12)
	v_pk_fma_f32 v[16:17], v[16:17], v[220:221], v[140:141]
	v_pk_fma_f32 v[18:19], v[18:19], v[222:223], v[142:143]
	v_fmac_f32_e32 v238, v16, v16
	v_fmac_f32_e32 v238, v17, v17
	v_fmac_f32_e32 v238, v18, v18
	v_fmac_f32_e32 v238, v19, v19
	global_store_dwordx4 v230, v[28:31], s[12:13]
	global_store_dwordx4 v230, v[24:27], s[12:13] offset:64
	global_store_dwordx4 v230, v[20:23], s[12:13] offset:512
	global_store_dwordx4 v230, v[16:19], s[12:13] offset:576
	s_waitcnt vmcnt(11)
	v_pk_fma_f32 v[12:13], v[12:13], v[196:197], v[164:165]
	v_pk_fma_f32 v[14:15], v[14:15], v[198:199], v[166:167]
	v_mul_f32_e32 v239, v12, v12
	v_fmac_f32_e32 v239, v13, v13
	v_fmac_f32_e32 v239, v14, v14
	v_fmac_f32_e32 v239, v15, v15
	s_waitcnt vmcnt(10)
	v_pk_fma_f32 v[8:9], v[8:9], v[212:213], v[168:169]
	v_pk_fma_f32 v[10:11], v[10:11], v[214:215], v[170:171]
	v_fmac_f32_e32 v239, v8, v8
	v_fmac_f32_e32 v239, v9, v9
	v_fmac_f32_e32 v239, v10, v10
	v_fmac_f32_e32 v239, v11, v11
	s_waitcnt vmcnt(9)
	v_pk_fma_f32 v[4:5], v[4:5], v[216:217], v[172:173]
	v_pk_fma_f32 v[6:7], v[6:7], v[218:219], v[174:175]
	v_fmac_f32_e32 v239, v4, v4
	v_fmac_f32_e32 v239, v5, v5
	v_fmac_f32_e32 v239, v6, v6
	v_fmac_f32_e32 v239, v7, v7
	s_waitcnt vmcnt(8)
	v_pk_fma_f32 v[0:1], v[0:1], v[220:221], v[176:177]
	v_pk_fma_f32 v[2:3], v[2:3], v[222:223], v[178:179]
	v_fmac_f32_e32 v239, v0, v0
	v_fmac_f32_e32 v239, v1, v1
	v_fmac_f32_e32 v239, v2, v2
	v_fmac_f32_e32 v239, v3, v3
	global_store_dwordx4 v231, v[12:15], s[12:13]
	global_store_dwordx4 v231, v[8:11], s[12:13] offset:64
	global_store_dwordx4 v231, v[4:7], s[12:13] offset:512
	global_store_dwordx4 v231, v[0:3], s[12:13] offset:576
	v_mbcnt_lo_u32_b32 v240, -1, 0
	v_mbcnt_hi_u32_b32 v240, -1, v240
	v_xor_b32_e32 v241, 16, v240
	v_xor_b32_e32 v242, 32, v240
	v_lshlrev_b32_e32 v241, 2, v241
	v_lshlrev_b32_e32 v242, 2, v242
	s_waitcnt lgkmcnt(0)
	ds_bpermute_b32 v128, v241, v232
	ds_bpermute_b32 v129, v241, v233
	ds_bpermute_b32 v130, v241, v234
	ds_bpermute_b32 v131, v241, v235
	ds_bpermute_b32 v132, v241, v236
	ds_bpermute_b32 v133, v241, v237
	ds_bpermute_b32 v134, v241, v238
	ds_bpermute_b32 v135, v241, v239
	s_waitcnt lgkmcnt(7)
	v_add_f32_e32 v232, v232, v128
	s_waitcnt lgkmcnt(6)
	v_add_f32_e32 v233, v233, v129
	s_waitcnt lgkmcnt(5)
	v_add_f32_e32 v234, v234, v130
	s_waitcnt lgkmcnt(4)
	v_add_f32_e32 v235, v235, v131
	s_waitcnt lgkmcnt(3)
	v_add_f32_e32 v236, v236, v132
	s_waitcnt lgkmcnt(2)
	v_add_f32_e32 v237, v237, v133
	s_waitcnt lgkmcnt(1)
	v_add_f32_e32 v238, v238, v134
	s_waitcnt lgkmcnt(0)
	v_add_f32_e32 v239, v239, v135
	ds_bpermute_b32 v128, v242, v232
	ds_bpermute_b32 v129, v242, v233
	ds_bpermute_b32 v130, v242, v234
	ds_bpermute_b32 v131, v242, v235
	ds_bpermute_b32 v132, v242, v236
	ds_bpermute_b32 v133, v242, v237
	ds_bpermute_b32 v134, v242, v238
	ds_bpermute_b32 v135, v242, v239
	s_waitcnt lgkmcnt(7)
	v_add_f32_e32 v232, v232, v128
	s_waitcnt lgkmcnt(6)
	v_add_f32_e32 v233, v233, v129
	s_waitcnt lgkmcnt(5)
	v_add_f32_e32 v234, v234, v130
	s_waitcnt lgkmcnt(4)
	v_add_f32_e32 v235, v235, v131
	s_waitcnt lgkmcnt(3)
	v_add_f32_e32 v236, v236, v132
	s_waitcnt lgkmcnt(2)
	v_add_f32_e32 v237, v237, v133
	s_waitcnt lgkmcnt(1)
	v_add_f32_e32 v238, v238, v134
	s_waitcnt lgkmcnt(0)
	v_add_f32_e32 v239, v239, v135
	v_lshlrev_b32_e32 v243, 2, v156
	s_add_u32 s90, s76, 0x6500000
	s_addc_u32 s91, s77, 0
	s_add_u32 s76, s76, 0x3142000
	s_addc_u32 s77, s77, 0
	s_lshl_b32 s83, s40, 6
	s_add_u32 s78, s76, s83
	s_addc_u32 s79, s77, 0
	s_add_u32 s78, s78, 0x20000
	s_addc_u32 s79, s79, 0
	s_mov_b64 s[80:81], exec
	s_mov_b64 exec, 0xffff
	global_atomic_add_f32 v243, v232, s[76:77]
	global_atomic_add_f32 v243, v233, s[76:77] offset:64
	global_atomic_add_f32 v243, v234, s[76:77] offset:128
	global_atomic_add_f32 v243, v235, s[76:77] offset:192
	global_atomic_add_f32 v243, v236, s[76:77] offset:512
	global_atomic_add_f32 v243, v237, s[76:77] offset:576
	global_atomic_add_f32 v243, v238, s[76:77] offset:640
	global_atomic_add_f32 v243, v239, s[76:77] offset:704
	s_mov_b64 exec, s[80:81]
	s_add_u32 s86, s8, 0x1000
	s_addc_u32 s87, s9, 0
	s_add_u32 s88, s86, 0x1000
	s_addc_u32 s89, s87, 0
	s_add_u32 s92, s92, 0x2000
	s_addc_u32 s93, s93, 0
	s_mov_b32 s84, 0xffff0000
	s_mov_b32 s85, 0xffff0000
	s_waitcnt vmcnt(0)
	s_barrier
	v_readfirstlane_b32 s83, v206
	v_mov_b32_e32 v244, 0
	v_mov_b32_e32 v245, 1
	s_cmp_lg_u32 s83, 0
	s_cbranch_scc1 .Lfmc_wait_done
	s_mov_b64 exec, 1
	global_atomic_add v244, v245, s[78:79]
	s_mov_b32 s82, 0
.Lfmc_spin:
	global_load_dword v246, v244, s[78:79] sc1
	s_waitcnt vmcnt(0)
	v_readfirstlane_b32 s83, v246
	s_cmp_ge_u32 s83, 4
	s_cbranch_scc1 .Lfmc_spin_done
	s_sleep 1
	s_add_u32 s82, s82, 1
	s_cmp_lt_u32 s82, 0x4000
	s_cbranch_scc1 .Lfmc_spin

; __device__ __forceinline__ unsigned cvtpk_s(float lo, float hi) { f32x2_t v = {lo, hi}; bf16x2_t b = __builtin_convertvector(v, bf16x2_t); return __builtin_bit_cast(unsigned, b); }
; __device__ __forceinline__ u32x4 quad_swap(unsigned lo0, unsigned lo1, unsigned hi0, unsigned hi1, int fq, int& coloff) {
;     const bool odd = fq & 1;
;     const unsigned s0 = odd ? lo0 : hi0, s1 = odd ? lo1 : hi1;
;     const unsigned r0 = (unsigned)__shfl_xor((int)s0, 16), r1 = (unsigned)__shfl_xor((int)s1, 16);
;     coloff = odd ? 16 + 4 * (fq - 1) : 4 * fq;
;     u32x4 o; o.x = odd ? r0 : lo0; o.y = odd ? r1 : lo1; o.z = odd ? hi0 : r0; o.w = odd ? hi1 : r1; return o;
; __device__ __forceinline__ void modpass(const float* xs_main, const float* xs_ctx, const float* mod_l, const float* g, int i, bf16_t* H, int nrows, int gw, int NGW, int lane) {
;     ...
;         if (cond != cur) { cur = cond; const float* shift = mod_l + cond * 9216 + 3 * i * 1024; const float* scale = shift + 1024;
; #pragma unroll
;             for (int j = 0; j < 2; ++j)
; #pragma unroll
;                 for (int q = 0; q < 2; ++q) { const int c = 8 * lane + 512 * j + 4 * q; gm[j][q] = *(const f32x4*)(g + c) * (*(const f32x4*)(scale + c) + 1.0f); sh[j][q] = *(const f32x4*)(shift + c); } }
;         float ss = 0.f;
; #pragma unroll
;         for (int j = 0; j < 2; ++j)
; #pragma unroll
;             for (int q = 0; q < 2; ++q) ss += (v[j][q][0] * v[j][q][0] + v[j][q][1] * v[j][q][1]) + (v[j][q][2] * v[j][q][2] + v[j][q][3] * v[j][q][3]);
;         const float rstd = 1.0f / sqrtf(wave_sum(ss) * (1.0f / D) + EPS);
; #pragma unroll
;         for (int j = 0; j < 2; ++j) {
;             const f32x4 o0 = v[j][0] * rstd * gm[j][0] + sh[j][0], o1 = v[j][1] * rstd * gm[j][1] + sh[j][1];
;             u32x4 w; w.x = cvtpk_s(o0[0], o0[1]); w.y = cvtpk_s(o0[2], o0[3]); w.z = cvtpk_s(o1[0], o1[1]); w.w = cvtpk_s(o1[2], o1[3]);
;             *(u32x4*)(H + (size_t)row * D + 8 * lane + 512 * j) = w;
.Lfmc_wait_done:
	s_barrier
	global_load_dword v132, v243, s[76:77] sc1
	global_load_dword v133, v243, s[76:77] offset:64 sc1
	global_load_dword v134, v243, s[76:77] offset:128 sc1
	global_load_dword v135, v243, s[76:77] offset:192 sc1
	global_load_dword v136, v243, s[76:77] offset:512 sc1
	global_load_dword v137, v243, s[76:77] offset:576 sc1
	global_load_dword v138, v243, s[76:77] offset:640 sc1
	global_load_dword v139, v243, s[76:77] offset:704 sc1
	global_load_dwordx4 v[196:199], v201, s[86:87]
	global_load_dwordx4 v[212:215], v201, s[86:87] offset:64
	global_load_dwordx4 v[216:219], v201, s[86:87] offset:512
	global_load_dwordx4 v[220:223], v201, s[86:87] offset:576
	global_load_dwordx4 v[140:143], v201, s[88:89]
	global_load_dwordx4 v[164:167], v201, s[88:89] offset:64
	global_load_dwordx4 v[168:171], v201, s[88:89] offset:512
	global_load_dwordx4 v[172:175], v201, s[88:89] offset:576
	global_load_dwordx4 v[176:179], v201, s[92:93]
	global_load_dwordx4 v[180:183], v201, s[92:93] offset:64
	global_load_dwordx4 v[184:187], v201, s[92:93] offset:512
	global_load_dwordx4 v[188:191], v201, s[92:93] offset:576
	v_mov_b32_e32 v240, 12
	v_cndmask_b32_e64 v240, 0, v240, s[84:85]
	v_add_u32_e32 v240, v240, v157
	v_lshlrev_b32_e32 v240, 1, v240
	v_lshl_add_u32 v247, v156, 11, v240
	v_mov_b32_e32 v240, 0x358637bd
	s_waitcnt vmcnt(0)
	v_fmamk_f32 v132, v132, 0x3a800000, v240
	v_fmamk_f32 v133, v133, 0x3a800000, v240
	v_fmamk_f32 v134, v134, 0x3a800000, v240
	v_fmamk_f32 v135, v135, 0x3a800000, v240
	v_fmamk_f32 v136, v136, 0x3a800000, v240
	v_fmamk_f32 v137, v137, 0x3a800000, v240
	v_fmamk_f32 v138, v138, 0x3a800000, v240
	v_fmamk_f32 v139, v139, 0x3a800000, v240
	v_rsq_f32_e32 v132, v132
	v_rsq_f32_e32 v133, v133
	v_rsq_f32_e32 v134, v134
	v_rsq_f32_e32 v135, v135
	v_rsq_f32_e32 v136, v136
	v_rsq_f32_e32 v137, v137
	v_rsq_f32_e32 v138, v138
	v_rsq_f32_e32 v139, v139
	v_pk_add_f32 v[140:141], v[140:141], 1.0 op_sel_hi:[1,0]
	v_pk_mul_f32 v[140:141], v[176:177], v[140:141]
	v_pk_add_f32 v[142:143], v[142:143], 1.0 op_sel_hi:[1,0]
	v_pk_mul_f32 v[142:143], v[178:179], v[142:143]
	v_pk_add_f32 v[164:165], v[164:165], 1.0 op_sel_hi:[1,0]
	v_pk_mul_f32 v[164:165], v[180:181], v[164:165]
	v_pk_add_f32 v[166:167], v[166:167], 1.0 op_sel_hi:[1,0]
	v_pk_mul_f32 v[166:167], v[182:183], v[166:167]
	v_pk_add_f32 v[168:169], v[168:169], 1.0 op_sel_hi:[1,0]
	v_pk_mul_f32 v[168:169], v[184:185], v[168:169]
	v_pk_add_f32 v[170:171], v[170:171], 1.0 op_sel_hi:[1,0]
	v_pk_mul_f32 v[170:171], v[186:187], v[170:171]
	v_pk_add_f32 v[172:173], v[172:173], 1.0 op_sel_hi:[1,0]
	v_pk_mul_f32 v[172:173], v[188:189], v[172:173]
	v_pk_add_f32 v[174:175], v[174:175], 1.0 op_sel_hi:[1,0]
	v_pk_mul_f32 v[174:175], v[190:191], v[174:175]
	v_mul_f32_e32 v124, v124, v132
	v_mul_f32_e32 v125, v125, v132
	v_pk_fma_f32 v[124:125], v[140:141], v[124:125], v[196:197]
	v_mul_f32_e32 v126, v126, v132
	v_mul_f32_e32 v127, v127, v132
	v_pk_fma_f32 v[126:127], v[142:143], v[126:127], v[198:199]
	v_cvt_pk_bf16_f32 v184, v124, v125
	v_cvt_pk_bf16_f32 v185, v126, v127
	v_mul_f32_e32 v120, v120, v132
	v_mul_f32_e32 v121, v121, v132
	v_pk_fma_f32 v[120:121], v[164:165], v[120:121], v[212:213]
	v_mul_f32_e32 v122, v122, v132
	v_mul_f32_e32 v123, v123, v132
	v_pk_fma_f32 v[122:123], v[166:167], v[122:123], v[214:215]
	v_cvt_pk_bf16_f32 v186, v120, v121
	v_cvt_pk_bf16_f32 v187, v122, v123
	v_mul_f32_e32 v116, v116, v132
	v_mul_f32_e32 v117, v117, v132
	v_pk_fma_f32 v[116:117], v[168:169], v[116:117], v[216:217]
	v_mul_f32_e32 v118, v118, v132
	v_mul_f32_e32 v119, v119, v132
	v_pk_fma_f32 v[118:119], v[170:171], v[118:119], v[218:219]
	v_cvt_pk_bf16_f32 v188, v116, v117
	v_cvt_pk_bf16_f32 v189, v118, v119
	v_mul_f32_e32 v112, v112, v132
	v_mul_f32_e32 v113, v113, v132
	v_pk_fma_f32 v[112:113], v[172:173], v[112:113], v[220:221]
	v_mul_f32_e32 v114, v114, v132
	v_mul_f32_e32 v115, v115, v132
	v_pk_fma_f32 v[114:115], v[174:175], v[114:115], v[222:223]
	v_cvt_pk_bf16_f32 v190, v112, v113
	v_cvt_pk_bf16_f32 v191, v114, v115
	v_mov_b32_e32 v240, v247
	v_cndmask_b32_e64 v192, v186, v184, s[84:85]
	v_cndmask_b32_e64 v193, v187, v185, s[84:85]
	ds_bpermute_b32 v194, v241, v192
	ds_bpermute_b32 v195, v241, v193
	s_waitcnt lgkmcnt(0)
	v_cndmask_b32_e64 v176, v184, v194, s[84:85]
	v_cndmask_b32_e64 v177, v185, v195, s[84:85]
	v_cndmask_b32_e64 v178, v194, v186, s[84:85]
	v_cndmask_b32_e64 v179, v195, v187, s[84:85]
	global_store_dwordx4 v240, v[176:179], s[90:91]
	v_cndmask_b32_e64 v192, v190, v188, s[84:85]
	v_cndmask_b32_e64 v193, v191, v189, s[84:85]
	ds_bpermute_b32 v194, v241, v192
	ds_bpermute_b32 v195, v241, v193
	s_waitcnt lgkmcnt(0)
	v_cndmask_b32_e64 v180, v188, v194, s[84:85]
	v_cndmask_b32_e64 v181, v189, v195, s[84:85]
	v_cndmask_b32_e64 v182, v194, v190, s[84:85]
	v_cndmask_b32_e64 v183, v195, v191, s[84:85]
	global_store_dwordx4 v240, v[180:183], s[90:91] offset:256
	v_mul_f32_e32 v108, v108, v133
	v_mul_f32_e32 v109, v109, v133
	v_pk_fma_f32 v[108:109], v[140:141], v[108:109], v[196:197]
	v_mul_f32_e32 v110, v110, v133
	v_mul_f32_e32 v111, v111, v133
	v_pk_fma_f32 v[110:111], v[142:143], v[110:111], v[198:199]
	v_cvt_pk_bf16_f32 v184, v108, v109
	v_cvt_pk_bf16_f32 v185, v110, v111
	v_mul_f32_e32 v104, v104, v133
	v_mul_f32_e32 v105, v105, v133
	v_pk_fma_f32 v[104:105], v[164:165], v[104:105], v[212:213]
	v_mul_f32_e32 v106, v106, v133
	v_mul_f32_e32 v107, v107, v133
	v_pk_fma_f32 v[106:107], v[166:167], v[106:107], v[214:215]
	v_cvt_pk_bf16_f32 v186, v104, v105
	v_cvt_pk_bf16_f32 v187, v106, v107
	v_mul_f32_e32 v100, v100, v133
	v_mul_f32_e32 v101, v101, v133
	v_pk_fma_f32 v[100:101], v[168:169], v[100:101], v[216:217]
	v_mul_f32_e32 v102, v102, v133
	v_mul_f32_e32 v103, v103, v133
	v_pk_fma_f32 v[102:103], v[170:171], v[102:103], v[218:219]
	v_cvt_pk_bf16_f32 v188, v100, v101
	v_cvt_pk_bf16_f32 v189, v102, v103
	v_mul_f32_e32 v96, v96, v133
	v_mul_f32_e32 v97, v97, v133
	v_pk_fma_f32 v[96:97], v[172:173], v[96:97], v[220:221]
	v_mul_f32_e32 v98, v98, v133
	v_mul_f32_e32 v99, v99, v133
	v_pk_fma_f32 v[98:99], v[174:175], v[98:99], v[222:223]
	v_cvt_pk_bf16_f32 v190, v96, v97
	v_cvt_pk_bf16_f32 v191, v98, v99
	v_add_u32_e32 v240, 0x8000, v247
	v_cndmask_b32_e64 v192, v186, v184, s[84:85]
	v_cndmask_b32_e64 v193, v187, v185, s[84:85]
	ds_bpermute_b32 v194, v241, v192
	ds_bpermute_b32 v195, v241, v193
	s_waitcnt lgkmcnt(0)
; __device__ __forceinline__ unsigned cvtpk_s(float lo, float hi) { f32x2_t v = {lo, hi}; bf16x2_t b = __builtin_convertvector(v, bf16x2_t); return __builtin_bit_cast(unsigned, b); }
; __device__ __forceinline__ u32x4 quad_swap(unsigned lo0, unsigned lo1, unsigned hi0, unsigned hi1, int fq, int& coloff) {
;     const bool odd = fq & 1;
;     const unsigned s0 = odd ? lo0 : hi0, s1 = odd ? lo1 : hi1;
;     const unsigned r0 = (unsigned)__shfl_xor((int)s0, 16), r1 = (unsigned)__shfl_xor((int)s1, 16);
;     coloff = odd ? 16 + 4 * (fq - 1) : 4 * fq;
;     u32x4 o; o.x = odd ? r0 : lo0; o.y = odd ? r1 : lo1; o.z = odd ? hi0 : r0; o.w = odd ? hi1 : r1; return o;
; __device__ __forceinline__ void modpass(const float* xs_main, const float* xs_ctx, const float* mod_l, const float* g, int i, bf16_t* H, int nrows, int gw, int NGW, int lane) {
;     ...
;         for (int j = 0; j < 2; ++j) {
;             const f32x4 o0 = v[j][0] * rstd * gm[j][0] + sh[j][0], o1 = v[j][1] * rstd * gm[j][1] + sh[j][1];
;             u32x4 w; w.x = cvtpk_s(o0[0], o0[1]); w.y = cvtpk_s(o0[2], o0[3]); w.z = cvtpk_s(o1[0], o1[1]); w.w = cvtpk_s(o1[2], o1[3]);
;             *(u32x4*)(H + (size_t)row * D + 8 * lane + 512 * j) = w;
	v_cndmask_b32_e64 v176, v184, v194, s[84:85]
	v_cndmask_b32_e64 v177, v185, v195, s[84:85]
	v_cndmask_b32_e64 v178, v194, v186, s[84:85]
	v_cndmask_b32_e64 v179, v195, v187, s[84:85]
	global_store_dwordx4 v240, v[176:179], s[90:91]
	v_cndmask_b32_e64 v192, v190, v188, s[84:85]
	v_cndmask_b32_e64 v193, v191, v189, s[84:85]
	ds_bpermute_b32 v194, v241, v192
	ds_bpermute_b32 v195, v241, v193
	s_waitcnt lgkmcnt(0)
	v_cndmask_b32_e64 v180, v188, v194, s[84:85]
	v_cndmask_b32_e64 v181, v189, v195, s[84:85]
	v_cndmask_b32_e64 v182, v194, v190, s[84:85]
	v_cndmask_b32_e64 v183, v195, v191, s[84:85]
	global_store_dwordx4 v240, v[180:183], s[90:91] offset:256
	v_mul_f32_e32 v92, v92, v134
	v_mul_f32_e32 v93, v93, v134
	v_pk_fma_f32 v[92:93], v[140:141], v[92:93], v[196:197]
	v_mul_f32_e32 v94, v94, v134
	v_mul_f32_e32 v95, v95, v134
	v_pk_fma_f32 v[94:95], v[142:143], v[94:95], v[198:199]
	v_cvt_pk_bf16_f32 v184, v92, v93
	v_cvt_pk_bf16_f32 v185, v94, v95
	v_mul_f32_e32 v88, v88, v134
	v_mul_f32_e32 v89, v89, v134
	v_pk_fma_f32 v[88:89], v[164:165], v[88:89], v[212:213]
	v_mul_f32_e32 v90, v90, v134
	v_mul_f32_e32 v91, v91, v134
	v_pk_fma_f32 v[90:91], v[166:167], v[90:91], v[214:215]
	v_cvt_pk_bf16_f32 v186, v88, v89
	v_cvt_pk_bf16_f32 v187, v90, v91
	v_mul_f32_e32 v84, v84, v134
	v_mul_f32_e32 v85, v85, v134
	v_pk_fma_f32 v[84:85], v[168:169], v[84:85], v[216:217]
	v_mul_f32_e32 v86, v86, v134
	v_mul_f32_e32 v87, v87, v134
	v_pk_fma_f32 v[86:87], v[170:171], v[86:87], v[218:219]
	v_cvt_pk_bf16_f32 v188, v84, v85
	v_cvt_pk_bf16_f32 v189, v86, v87
	v_mul_f32_e32 v80, v80, v134
	v_mul_f32_e32 v81, v81, v134
	v_pk_fma_f32 v[80:81], v[172:173], v[80:81], v[220:221]
	v_mul_f32_e32 v82, v82, v134
	v_mul_f32_e32 v83, v83, v134
	v_pk_fma_f32 v[82:83], v[174:175], v[82:83], v[222:223]
	v_cvt_pk_bf16_f32 v190, v80, v81
	v_cvt_pk_bf16_f32 v191, v82, v83
	v_add_u32_e32 v240, 0x10000, v247
	v_cndmask_b32_e64 v192, v186, v184, s[84:85]
	v_cndmask_b32_e64 v193, v187, v185, s[84:85]
	ds_bpermute_b32 v194, v241, v192
	ds_bpermute_b32 v195, v241, v193
	s_waitcnt lgkmcnt(0)
	v_cndmask_b32_e64 v176, v184, v194, s[84:85]
	v_cndmask_b32_e64 v177, v185, v195, s[84:85]
	v_cndmask_b32_e64 v178, v194, v186, s[84:85]
	v_cndmask_b32_e64 v179, v195, v187, s[84:85]
	global_store_dwordx4 v240, v[176:179], s[90:91]
	v_cndmask_b32_e64 v192, v190, v188, s[84:85]
	v_cndmask_b32_e64 v193, v191, v189, s[84:85]
	ds_bpermute_b32 v194, v241, v192
	ds_bpermute_b32 v195, v241, v193
	s_waitcnt lgkmcnt(0)
	v_cndmask_b32_e64 v180, v188, v194, s[84:85]
	v_cndmask_b32_e64 v181, v189, v195, s[84:85]
	v_cndmask_b32_e64 v182, v194, v190, s[84:85]
	v_cndmask_b32_e64 v183, v195, v191, s[84:85]
	global_store_dwordx4 v240, v[180:183], s[90:91] offset:256
	v_mul_f32_e32 v76, v76, v135
	v_mul_f32_e32 v77, v77, v135
	v_pk_fma_f32 v[76:77], v[140:141], v[76:77], v[196:197]
	v_mul_f32_e32 v78, v78, v135
	v_mul_f32_e32 v79, v79, v135
	v_pk_fma_f32 v[78:79], v[142:143], v[78:79], v[198:199]
	v_cvt_pk_bf16_f32 v184, v76, v77
	v_cvt_pk_bf16_f32 v185, v78, v79
	v_mul_f32_e32 v72, v72, v135
	v_mul_f32_e32 v73, v73, v135
	v_pk_fma_f32 v[72:73], v[164:165], v[72:73], v[212:213]
	v_mul_f32_e32 v74, v74, v135
	v_mul_f32_e32 v75, v75, v135
	v_pk_fma_f32 v[74:75], v[166:167], v[74:75], v[214:215]
	v_cvt_pk_bf16_f32 v186, v72, v73
	v_cvt_pk_bf16_f32 v187, v74, v75
	v_mul_f32_e32 v68, v68, v135
	v_mul_f32_e32 v69, v69, v135
	v_pk_fma_f32 v[68:69], v[168:169], v[68:69], v[216:217]
	v_mul_f32_e32 v70, v70, v135
	v_mul_f32_e32 v71, v71, v135
	v_pk_fma_f32 v[70:71], v[170:171], v[70:71], v[218:219]
	v_cvt_pk_bf16_f32 v188, v68, v69
	v_cvt_pk_bf16_f32 v189, v70, v71
	v_mul_f32_e32 v64, v64, v135
	v_mul_f32_e32 v65, v65, v135
	v_pk_fma_f32 v[64:65], v[172:173], v[64:65], v[220:221]
	v_mul_f32_e32 v66, v66, v135
	v_mul_f32_e32 v67, v67, v135
	v_pk_fma_f32 v[66:67], v[174:175], v[66:67], v[222:223]
	v_cvt_pk_bf16_f32 v190, v64, v65
	v_cvt_pk_bf16_f32 v191, v66, v67
	v_add_u32_e32 v240, 0x18000, v247
	v_cndmask_b32_e64 v192, v186, v184, s[84:85]
	v_cndmask_b32_e64 v193, v187, v185, s[84:85]
	ds_bpermute_b32 v194, v241, v192
	ds_bpermute_b32 v195, v241, v193
	s_waitcnt lgkmcnt(0)
	v_cndmask_b32_e64 v176, v184, v194, s[84:85]
	v_cndmask_b32_e64 v177, v185, v195, s[84:85]
	v_cndmask_b32_e64 v178, v194, v186, s[84:85]
	v_cndmask_b32_e64 v179, v195, v187, s[84:85]
	global_store_dwordx4 v240, v[176:179], s[90:91]
	v_cndmask_b32_e64 v192, v190, v188, s[84:85]
	v_cndmask_b32_e64 v193, v191, v189, s[84:85]
	ds_bpermute_b32 v194, v241, v192
	ds_bpermute_b32 v195, v241, v193
	s_waitcnt lgkmcnt(0)
	v_cndmask_b32_e64 v180, v188, v194, s[84:85]
	v_cndmask_b32_e64 v181, v189, v195, s[84:85]
	v_cndmask_b32_e64 v182, v194, v190, s[84:85]
	v_cndmask_b32_e64 v183, v195, v191, s[84:85]
	global_store_dwordx4 v240, v[180:183], s[90:91] offset:256
	v_mul_f32_e32 v60, v60, v136
	v_mul_f32_e32 v61, v61, v136
	v_pk_fma_f32 v[60:61], v[140:141], v[60:61], v[196:197]
	v_mul_f32_e32 v62, v62, v136
	v_mul_f32_e32 v63, v63, v136
	v_pk_fma_f32 v[62:63], v[142:143], v[62:63], v[198:199]
	v_cvt_pk_bf16_f32 v184, v60, v61
	v_cvt_pk_bf16_f32 v185, v62, v63
	v_mul_f32_e32 v56, v56, v136
	v_mul_f32_e32 v57, v57, v136
	v_pk_fma_f32 v[56:57], v[164:165], v[56:57], v[212:213]
	v_mul_f32_e32 v58, v58, v136
	v_mul_f32_e32 v59, v59, v136
	v_pk_fma_f32 v[58:59], v[166:167], v[58:59], v[214:215]
	v_cvt_pk_bf16_f32 v186, v56, v57
	v_cvt_pk_bf16_f32 v187, v58, v59
	v_mul_f32_e32 v52, v52, v136
	v_mul_f32_e32 v53, v53, v136
	v_pk_fma_f32 v[52:53], v[168:169], v[52:53], v[216:217]
	v_mul_f32_e32 v54, v54, v136
	v_mul_f32_e32 v55, v55, v136
	v_pk_fma_f32 v[54:55], v[170:171], v[54:55], v[218:219]
	v_cvt_pk_bf16_f32 v188, v52, v53
	v_cvt_pk_bf16_f32 v189, v54, v55
	v_mul_f32_e32 v48, v48, v136
	v_mul_f32_e32 v49, v49, v136
	v_pk_fma_f32 v[48:49], v[172:173], v[48:49], v[220:221]
	v_mul_f32_e32 v50, v50, v136
	v_mul_f32_e32 v51, v51, v136
	v_pk_fma_f32 v[50:51], v[174:175], v[50:51], v[222:223]
	v_cvt_pk_bf16_f32 v190, v48, v49
	v_cvt_pk_bf16_f32 v191, v50, v51
	v_add_u32_e32 v240, 0x40000, v247
	v_cndmask_b32_e64 v192, v186, v184, s[84:85]
	v_cndmask_b32_e64 v193, v187, v185, s[84:85]
	ds_bpermute_b32 v194, v241, v192
	ds_bpermute_b32 v195, v241, v193
	s_waitcnt lgkmcnt(0)
; __device__ __forceinline__ unsigned cvtpk_s(float lo, float hi) { f32x2_t v = {lo, hi}; bf16x2_t b = __builtin_convertvector(v, bf16x2_t); return __builtin_bit_cast(unsigned, b); }
; __device__ __forceinline__ u32x4 quad_swap(unsigned lo0, unsigned lo1, unsigned hi0, unsigned hi1, int fq, int& coloff) {
;     const bool odd = fq & 1;
;     const unsigned s0 = odd ? lo0 : hi0, s1 = odd ? lo1 : hi1;
;     const unsigned r0 = (unsigned)__shfl_xor((int)s0, 16), r1 = (unsigned)__shfl_xor((int)s1, 16);
;     coloff = odd ? 16 + 4 * (fq - 1) : 4 * fq;
;     u32x4 o; o.x = odd ? r0 : lo0; o.y = odd ? r1 : lo1; o.z = odd ? hi0 : r0; o.w = odd ? hi1 : r1; return o;
; __device__ __forceinline__ void modpass(const float* xs_main, const float* xs_ctx, const float* mod_l, const float* g, int i, bf16_t* H, int nrows, int gw, int NGW, int lane) {
;     ...
;         for (int j = 0; j < 2; ++j) {
;             const f32x4 o0 = v[j][0] * rstd * gm[j][0] + sh[j][0], o1 = v[j][1] * rstd * gm[j][1] + sh[j][1];
;             u32x4 w; w.x = cvtpk_s(o0[0], o0[1]); w.y = cvtpk_s(o0[2], o0[3]); w.z = cvtpk_s(o1[0], o1[1]); w.w = cvtpk_s(o1[2], o1[3]);
;             *(u32x4*)(H + (size_t)row * D + 8 * lane + 512 * j) = w;
	v_cndmask_b32_e64 v176, v184, v194, s[84:85]
	v_cndmask_b32_e64 v177, v185, v195, s[84:85]
	v_cndmask_b32_e64 v178, v194, v186, s[84:85]
	v_cndmask_b32_e64 v179, v195, v187, s[84:85]
	global_store_dwordx4 v240, v[176:179], s[90:91]
	v_cndmask_b32_e64 v192, v190, v188, s[84:85]
	v_cndmask_b32_e64 v193, v191, v189, s[84:85]
	ds_bpermute_b32 v194, v241, v192
	ds_bpermute_b32 v195, v241, v193
	s_waitcnt lgkmcnt(0)
	v_cndmask_b32_e64 v180, v188, v194, s[84:85]
	v_cndmask_b32_e64 v181, v189, v195, s[84:85]
	v_cndmask_b32_e64 v182, v194, v190, s[84:85]
	v_cndmask_b32_e64 v183, v195, v191, s[84:85]
	global_store_dwordx4 v240, v[180:183], s[90:91] offset:256
	v_mul_f32_e32 v44, v44, v137
	v_mul_f32_e32 v45, v45, v137
	v_pk_fma_f32 v[44:45], v[140:141], v[44:45], v[196:197]
	v_mul_f32_e32 v46, v46, v137
	v_mul_f32_e32 v47, v47, v137
	v_pk_fma_f32 v[46:47], v[142:143], v[46:47], v[198:199]
	v_cvt_pk_bf16_f32 v184, v44, v45
	v_cvt_pk_bf16_f32 v185, v46, v47
	v_mul_f32_e32 v40, v40, v137
	v_mul_f32_e32 v41, v41, v137
	v_pk_fma_f32 v[40:41], v[164:165], v[40:41], v[212:213]
	v_mul_f32_e32 v42, v42, v137
	v_mul_f32_e32 v43, v43, v137
	v_pk_fma_f32 v[42:43], v[166:167], v[42:43], v[214:215]
	v_cvt_pk_bf16_f32 v186, v40, v41
	v_cvt_pk_bf16_f32 v187, v42, v43
	v_mul_f32_e32 v36, v36, v137
	v_mul_f32_e32 v37, v37, v137
	v_pk_fma_f32 v[36:37], v[168:169], v[36:37], v[216:217]
	v_mul_f32_e32 v38, v38, v137
	v_mul_f32_e32 v39, v39, v137
	v_pk_fma_f32 v[38:39], v[170:171], v[38:39], v[218:219]
	v_cvt_pk_bf16_f32 v188, v36, v37
	v_cvt_pk_bf16_f32 v189, v38, v39
	v_mul_f32_e32 v32, v32, v137
	v_mul_f32_e32 v33, v33, v137
	v_pk_fma_f32 v[32:33], v[172:173], v[32:33], v[220:221]
	v_mul_f32_e32 v34, v34, v137
	v_mul_f32_e32 v35, v35, v137
	v_pk_fma_f32 v[34:35], v[174:175], v[34:35], v[222:223]
	v_cvt_pk_bf16_f32 v190, v32, v33
	v_cvt_pk_bf16_f32 v191, v34, v35
	v_add_u32_e32 v240, 0x48000, v247
	v_cndmask_b32_e64 v192, v186, v184, s[84:85]
	v_cndmask_b32_e64 v193, v187, v185, s[84:85]
	ds_bpermute_b32 v194, v241, v192
	ds_bpermute_b32 v195, v241, v193
	s_waitcnt lgkmcnt(0)
	v_cndmask_b32_e64 v176, v184, v194, s[84:85]
	v_cndmask_b32_e64 v177, v185, v195, s[84:85]
	v_cndmask_b32_e64 v178, v194, v186, s[84:85]
	v_cndmask_b32_e64 v179, v195, v187, s[84:85]
	global_store_dwordx4 v240, v[176:179], s[90:91]
	v_cndmask_b32_e64 v192, v190, v188, s[84:85]
	v_cndmask_b32_e64 v193, v191, v189, s[84:85]
	ds_bpermute_b32 v194, v241, v192
	ds_bpermute_b32 v195, v241, v193
	s_waitcnt lgkmcnt(0)
	v_cndmask_b32_e64 v180, v188, v194, s[84:85]
	v_cndmask_b32_e64 v181, v189, v195, s[84:85]
	v_cndmask_b32_e64 v182, v194, v190, s[84:85]
	v_cndmask_b32_e64 v183, v195, v191, s[84:85]
	global_store_dwordx4 v240, v[180:183], s[90:91] offset:256
	v_mul_f32_e32 v28, v28, v138
	v_mul_f32_e32 v29, v29, v138
	v_pk_fma_f32 v[28:29], v[140:141], v[28:29], v[196:197]
	v_mul_f32_e32 v30, v30, v138
	v_mul_f32_e32 v31, v31, v138
	v_pk_fma_f32 v[30:31], v[142:143], v[30:31], v[198:199]
	v_cvt_pk_bf16_f32 v184, v28, v29
	v_cvt_pk_bf16_f32 v185, v30, v31
	v_mul_f32_e32 v24, v24, v138
	v_mul_f32_e32 v25, v25, v138
	v_pk_fma_f32 v[24:25], v[164:165], v[24:25], v[212:213]
	v_mul_f32_e32 v26, v26, v138
	v_mul_f32_e32 v27, v27, v138
	v_pk_fma_f32 v[26:27], v[166:167], v[26:27], v[214:215]
	v_cvt_pk_bf16_f32 v186, v24, v25
	v_cvt_pk_bf16_f32 v187, v26, v27
	v_mul_f32_e32 v20, v20, v138
	v_mul_f32_e32 v21, v21, v138
	v_pk_fma_f32 v[20:21], v[168:169], v[20:21], v[216:217]
	v_mul_f32_e32 v22, v22, v138
	v_mul_f32_e32 v23, v23, v138
	v_pk_fma_f32 v[22:23], v[170:171], v[22:23], v[218:219]
	v_cvt_pk_bf16_f32 v188, v20, v21
	v_cvt_pk_bf16_f32 v189, v22, v23
	v_mul_f32_e32 v16, v16, v138
	v_mul_f32_e32 v17, v17, v138
	v_pk_fma_f32 v[16:17], v[172:173], v[16:17], v[220:221]
	v_mul_f32_e32 v18, v18, v138
	v_mul_f32_e32 v19, v19, v138
	v_pk_fma_f32 v[18:19], v[174:175], v[18:19], v[222:223]
	v_cvt_pk_bf16_f32 v190, v16, v17
	v_cvt_pk_bf16_f32 v191, v18, v19
	v_add_u32_e32 v240, 0x50000, v247
	v_cndmask_b32_e64 v192, v186, v184, s[84:85]
	v_cndmask_b32_e64 v193, v187, v185, s[84:85]
	ds_bpermute_b32 v194, v241, v192
	ds_bpermute_b32 v195, v241, v193
	s_waitcnt lgkmcnt(0)
	v_cndmask_b32_e64 v176, v184, v194, s[84:85]
	v_cndmask_b32_e64 v177, v185, v195, s[84:85]
	v_cndmask_b32_e64 v178, v194, v186, s[84:85]
	v_cndmask_b32_e64 v179, v195, v187, s[84:85]
	global_store_dwordx4 v240, v[176:179], s[90:91]
	v_cndmask_b32_e64 v192, v190, v188, s[84:85]
	v_cndmask_b32_e64 v193, v191, v189, s[84:85]
	ds_bpermute_b32 v194, v241, v192
	ds_bpermute_b32 v195, v241, v193
	s_waitcnt lgkmcnt(0)
	v_cndmask_b32_e64 v180, v188, v194, s[84:85]
	v_cndmask_b32_e64 v181, v189, v195, s[84:85]
	v_cndmask_b32_e64 v182, v194, v190, s[84:85]
	v_cndmask_b32_e64 v183, v195, v191, s[84:85]
	global_store_dwordx4 v240, v[180:183], s[90:91] offset:256
	v_mul_f32_e32 v12, v12, v139
	v_mul_f32_e32 v13, v13, v139
	v_pk_fma_f32 v[12:13], v[140:141], v[12:13], v[196:197]
	v_mul_f32_e32 v14, v14, v139
	v_mul_f32_e32 v15, v15, v139
	v_pk_fma_f32 v[14:15], v[142:143], v[14:15], v[198:199]
	v_cvt_pk_bf16_f32 v184, v12, v13
	v_cvt_pk_bf16_f32 v185, v14, v15
	v_mul_f32_e32 v8, v8, v139
	v_mul_f32_e32 v9, v9, v139
	v_pk_fma_f32 v[8:9], v[164:165], v[8:9], v[212:213]
	v_mul_f32_e32 v10, v10, v139
	v_mul_f32_e32 v11, v11, v139
	v_pk_fma_f32 v[10:11], v[166:167], v[10:11], v[214:215]
	v_cvt_pk_bf16_f32 v186, v8, v9
	v_cvt_pk_bf16_f32 v187, v10, v11
	v_mul_f32_e32 v4, v4, v139
	v_mul_f32_e32 v5, v5, v139
	v_pk_fma_f32 v[4:5], v[168:169], v[4:5], v[216:217]
	v_mul_f32_e32 v6, v6, v139
	v_mul_f32_e32 v7, v7, v139
	v_pk_fma_f32 v[6:7], v[170:171], v[6:7], v[218:219]
	v_cvt_pk_bf16_f32 v188, v4, v5
	v_cvt_pk_bf16_f32 v189, v6, v7
	v_mul_f32_e32 v0, v0, v139
	v_mul_f32_e32 v1, v1, v139
	v_pk_fma_f32 v[0:1], v[172:173], v[0:1], v[220:221]
	v_mul_f32_e32 v2, v2, v139
	v_mul_f32_e32 v3, v3, v139
	v_pk_fma_f32 v[2:3], v[174:175], v[2:3], v[222:223]
	v_cvt_pk_bf16_f32 v190, v0, v1
	v_cvt_pk_bf16_f32 v191, v2, v3
	v_add_u32_e32 v240, 0x58000, v247
	v_cndmask_b32_e64 v192, v186, v184, s[84:85]
	v_cndmask_b32_e64 v193, v187, v185, s[84:85]
	ds_bpermute_b32 v194, v241, v192
	ds_bpermute_b32 v195, v241, v193
	s_waitcnt lgkmcnt(0)
	v_cndmask_b32_e64 v176, v184, v194, s[84:85]
	v_cndmask_b32_e64 v177, v185, v195, s[84:85]
	v_cndmask_b32_e64 v178, v194, v186, s[84:85]
	v_cndmask_b32_e64 v179, v195, v187, s[84:85]
	global_store_dwordx4 v240, v[176:179], s[90:91]
	v_cndmask_b32_e64 v192, v190, v188, s[84:85]
	v_cndmask_b32_e64 v193, v191, v189, s[84:85]
	ds_bpermute_b32 v194, v241, v192
	ds_bpermute_b32 v195, v241, v193
	s_waitcnt lgkmcnt(0)
	v_cndmask_b32_e64 v180, v188, v194, s[84:85]
	v_cndmask_b32_e64 v181, v189, v195, s[84:85]
	v_cndmask_b32_e64 v182, v194, v190, s[84:85]
	v_cndmask_b32_e64 v183, v195, v191, s[84:85]
	global_store_dwordx4 v240, v[180:183], s[90:91] offset:256
	s_andn2_b64 vcc, exec, s[10:11]
	s_mov_b64 s[10:11], -1
	s_cbranch_vccnz .LBB0_1115
	s_andn2_b64 vcc, exec, s[14:15]
	s_cbranch_vccnz .LBB0_1114
	s_barrier
	s_branch .LBB0_1114

; __device__ __forceinline__ void modpass(const float* xs_main, const float* xs_ctx, const float* mod_l, const float* g, int i, bf16_t* H, int nrows, int gw, int NGW, int lane) {
;     f32x4 gm[2][2], sh[2][2], v[2][2], vn[2][2]; int cur = -1;
;     int row = gw;
;     if (row < nrows) { const float* xr = row < MX ? xs_main + (size_t)row * D : xs_ctx + (size_t)(row - MX) * D;
; #pragma unroll
;         for (int j = 0; j < 2; ++j) { v[j][0] = *(const f32x4*)(xr + 8 * lane + 512 * j); v[j][1] = *(const f32x4*)(xr + 8 * lane + 512 * j + 4); } }
;     for (; row < nrows; row += NGW) {
;         const int nrow = row + NGW;
;         if (nrow < nrows) { const float* xr = nrow < MX ? xs_main + (size_t)nrow * D : xs_ctx + (size_t)(nrow - MX) * D;
; #pragma unroll
;             for (int j = 0; j < 2; ++j) { vn[j][0] = *(const f32x4*)(xr + 8 * lane + 512 * j); vn[j][1] = *(const f32x4*)(xr + 8 * lane + 512 * j + 4); } }
.LBB0_1187:
	s_or_b64 exec, exec, s[10:11]
	s_mov_b64 s[18:19], s[0:1]
	v_mov_b32_e32 v2, v206
	s_waitcnt lgkmcnt(0)
	s_barrier
	s_nop 0
	v_readfirstlane_b32 s6, v2
	s_ashr_i32 s6, s6, 6
	s_add_i32 s10, s6, s33
	s_add_i32 s10, s10, 0x8000
	s_cmp_gt_i32 s10, 0x81ff
	s_cbranch_scc1 .LBB0_1194
	s_load_dwordx4 s[12:15], s[18:19], 0xb0
	s_load_dwordx2 s[8:9], s[18:19], 0x30
	v_lshlrev_b32_e32 v0, 3, v2
	v_and_b32_e32 v64, 0x1f8, v0
	v_lshlrev_b32_e32 v0, 2, v64
	s_waitcnt lgkmcnt(0)
	s_add_u32 s6, s14, 0x6300000
	s_addc_u32 s7, s15, 0
	s_add_u32 s16, s8, 0x2000
	s_addc_u32 s17, s9, 0
	s_add_i32 s8, s10, 0xffff8000
	s_ashr_i32 s11, s10, 31
	s_cmp_lt_i32 s10, 0x8000
	s_cselect_b32 s9, s11, 0
	s_cselect_b32 s8, s10, s8
	s_cselect_b32 s18, s13, s7
	s_cselect_b32 s19, s12, s6
	s_lshl_b64 s[8:9], s[8:9], 12
	s_add_u32 s8, s19, s8
	s_addc_u32 s9, s18, s9
	global_load_dwordx4 v[12:15], v0, s[8:9] offset:16
	global_load_dwordx4 v[16:19], v0, s[8:9]
	global_load_dwordx4 v[4:7], v0, s[8:9] offset:2064
	global_load_dwordx4 v[8:11], v0, s[8:9] offset:2048
	v_xor_b32_e32 v3, 1, v202
	v_cmp_lt_i32_e32 vcc, v3, v203
	v_mov_b32_e32 v1, 0
	v_or_b32_e32 v20, 0x200, v64
	v_cndmask_b32_e32 v3, v202, v3, vcc
	v_lshlrev_b32_e32 v65, 2, v3
	v_xor_b32_e32 v3, 2, v202
	v_cmp_lt_i32_e32 vcc, v3, v203
	s_add_u32 s8, s14, 0x6000
	v_lshl_add_u64 v[66:67], s[16:17], 0, v[0:1]
	v_cndmask_b32_e32 v3, v202, v3, vcc
	v_lshlrev_b32_e32 v72, 2, v3
	v_xor_b32_e32 v3, 4, v202
	v_cmp_lt_i32_e32 vcc, v3, v203
	v_lshlrev_b32_e32 v0, 2, v20
	s_addc_u32 s9, s15, 0
	v_cndmask_b32_e32 v3, v202, v3, vcc
	v_lshlrev_b32_e32 v73, 2, v3
	v_xor_b32_e32 v3, 8, v202
	v_cmp_lt_i32_e32 vcc, v3, v203
	v_lshl_add_u64 v[68:69], s[16:17], 0, v[0:1]
	s_lshl_b64 s[16:17], s[10:11], 11
	v_cndmask_b32_e32 v3, v202, v3, vcc
	v_cmp_lt_i32_e32 vcc, v204, v203
	v_lshlrev_b32_e32 v74, 2, v3
	v_and_b32_e32 v0, 63, v2
	v_cndmask_b32_e32 v3, v202, v204, vcc
	v_lshlrev_b32_e32 v75, 2, v3
	v_xor_b32_e32 v3, 32, v202
	v_cmp_lt_i32_e32 vcc, v3, v203
	s_add_u32 s14, s14, s16
	v_lshlrev_b32_e32 v0, 4, v0
	v_cndmask_b32_e32 v3, v202, v3, vcc
	s_addc_u32 s15, s15, s17
	v_lshlrev_b32_e32 v76, 2, v3
	v_lshl_add_u64 v[2:3], s[14:15], 0, v[0:1]
	s_mov_b64 s[14:15], 0x6500400
	s_ashr_i32 s29, s28, 31
	s_add_i32 s20, s10, s28
	s_mov_b32 s23, -1
	v_lshl_add_u64 v[70:71], v[2:3], 0, s[14:15]
	s_lshl_b64 s[14:15], s[28:29], 11
	s_ashr_i32 s21, s20, 31
	v_lshlrev_b32_e32 v77, 2, v20
	v_mov_b32_e32 v78, 0x358637bd
	s_mov_b32 s22, 0xf800000
	v_mov_b32_e32 v79, 0x260
	v_mov_b32_e32 v0, v1
	v_mov_b32_e32 v2, v1
	v_mov_b32_e32 v3, v1
	v_mov_b32_e32 v20, v1
	v_mov_b32_e32 v21, v1
	v_mov_b32_e32 v22, v1
	v_mov_b32_e32 v23, v1
	v_mov_b32_e32 v28, v1
	v_mov_b32_e32 v29, v1
	v_mov_b32_e32 v30, v1
	v_mov_b32_e32 v31, v1
	v_mov_b32_e32 v24, v1
	v_mov_b32_e32 v25, v1
	v_mov_b32_e32 v26, v1
	v_mov_b32_e32 v27, v1
	s_branch .LBB0_1190

;     __device__ __forceinline__ void operator()(const f32x4 (&acc)[2][2][4][2], const Unit& u, int wr, int wc, int fr, int fq) const {
;     ...
;         const int col0 = u.pn * BM + wc * 32 + 4 * fq;
;         f32x4 gv[2][2];
; #pragma unroll
;         for (int bj = 0; bj < 2; ++bj)
; #pragma unroll
;             for (int n = 0; n < 2; ++n) gv[bj][n] = *(const f32x4*)(gate + col0 + bj * HALF + n * 16) * coef;
; #pragma unroll
;         for (int ai = 0; ai < 2; ++ai)
; #pragma unroll
;             for (int m = 0; m < 4; ++m) {
;                 const int row = u.pm * BM + ai * HALF + wr * 64 + m * 16 + fr;
;                 const float* s = row < MX_ ? src_main + (size_t)row * D_ : src_ctx + (size_t)(row - MX_) * D_;
;                 float* d = row < MX_ ? dst_main + (size_t)row * D_ : dst_ctx + (size_t)(row - MX_) * D_;
; #pragma unroll
;                 for (int bj = 0; bj < 2; ++bj)
; #pragma unroll
;                     for (int n = 0; n < 2; ++n) { const int off = col0 + bj * HALF + n * 16; const f32x4 xo = *(const f32x4*)(s + off); *(f32x4*)(d + off) = xo + gv[bj][n] * acc[ai][bj][m][n]; }
.LBB0_1346:
	s_cmpk_lt_i32 s6, 0x80
	s_cselect_b32 s8, s64, 0x4800
	s_cmp_gt_i32 s6, 63
	s_cselect_b32 s8, s8, 0
	s_lshl_b32 s8, s8, 2
	s_add_u32 s8, s56, s8
	s_addc_u32 s9, s57, 0
	s_load_dwordx2 s[92:93], s[0:1], 0x30
	s_load_dwordx2 s[76:77], s[0:1], 0xb8
	v_lshl_add_u32 v156, s6, 8, v158
	v_lshl_or_b32 v157, s7, 8, v160
	v_lshlrev_b32_e32 v201, 2, v157
	v_lshl_add_u32 v224, v156, 12, v201
	global_load_dwordx4 v[196:199], v201, s[8:9]
	global_load_dwordx4 v[212:215], v201, s[8:9] offset:64
	global_load_dwordx4 v[216:219], v201, s[8:9] offset:512
	global_load_dwordx4 v[220:223], v201, s[8:9] offset:576
	v_add_u32_e32 v225, 0x10000, v224
	v_add_u32_e32 v226, 0x20000, v224
	v_add_u32_e32 v227, 0x30000, v224
	v_add_u32_e32 v228, 0x80000, v224
	v_add_u32_e32 v229, 0x90000, v224
	v_add_u32_e32 v230, 0xa0000, v224
	v_add_u32_e32 v231, 0xb0000, v224
	global_load_dwordx4 v[140:143], v224, s[16:17]
	global_load_dwordx4 v[144:147], v224, s[16:17] offset:64
	global_load_dwordx4 v[148:151], v224, s[16:17] offset:512
	global_load_dwordx4 v[152:155], v224, s[16:17] offset:576
	global_load_dwordx4 v[164:167], v225, s[16:17]
	global_load_dwordx4 v[168:171], v225, s[16:17] offset:64
	global_load_dwordx4 v[172:175], v225, s[16:17] offset:512
	global_load_dwordx4 v[176:179], v225, s[16:17] offset:576
	global_load_dwordx4 v[180:183], v226, s[16:17]
	global_load_dwordx4 v[184:187], v226, s[16:17] offset:64
	global_load_dwordx4 v[188:191], v226, s[16:17] offset:512
	global_load_dwordx4 v[192:195], v226, s[16:17] offset:576
	s_waitcnt vmcnt(12)
	v_pk_mul_f32 v[196:197], v[196:197], 0.5 op_sel_hi:[1,0]
	v_pk_mul_f32 v[198:199], v[198:199], 0.5 op_sel_hi:[1,0]
	v_pk_mul_f32 v[212:213], v[212:213], 0.5 op_sel_hi:[1,0]
	v_pk_mul_f32 v[214:215], v[214:215], 0.5 op_sel_hi:[1,0]
	v_pk_mul_f32 v[216:217], v[216:217], 0.5 op_sel_hi:[1,0]
	v_pk_mul_f32 v[218:219], v[218:219], 0.5 op_sel_hi:[1,0]
	v_pk_mul_f32 v[220:221], v[220:221], 0.5 op_sel_hi:[1,0]
	v_pk_mul_f32 v[222:223], v[222:223], 0.5 op_sel_hi:[1,0]
	s_waitcnt vmcnt(11)
	v_pk_fma_f32 v[124:125], v[124:125], v[196:197], v[140:141]
	v_pk_fma_f32 v[126:127], v[126:127], v[198:199], v[142:143]
	v_mul_f32_e32 v232, v124, v124
	v_fmac_f32_e32 v232, v125, v125
	v_fmac_f32_e32 v232, v126, v126
	v_fmac_f32_e32 v232, v127, v127
	s_waitcnt vmcnt(10)
	v_pk_fma_f32 v[120:121], v[120:121], v[212:213], v[144:145]
	v_pk_fma_f32 v[122:123], v[122:123], v[214:215], v[146:147]
	v_fmac_f32_e32 v232, v120, v120
	v_fmac_f32_e32 v232, v121, v121
	v_fmac_f32_e32 v232, v122, v122
	v_fmac_f32_e32 v232, v123, v123
	s_waitcnt vmcnt(9)
	v_pk_fma_f32 v[116:117], v[116:117], v[216:217], v[148:149]
	v_pk_fma_f32 v[118:119], v[118:119], v[218:219], v[150:151]
	v_fmac_f32_e32 v232, v116, v116
	v_fmac_f32_e32 v232, v117, v117
	v_fmac_f32_e32 v232, v118, v118
	v_fmac_f32_e32 v232, v119, v119
	s_waitcnt vmcnt(8)
	v_pk_fma_f32 v[112:113], v[112:113], v[220:221], v[152:153]
	v_pk_fma_f32 v[114:115], v[114:115], v[222:223], v[154:155]
	v_fmac_f32_e32 v232, v112, v112
	v_fmac_f32_e32 v232, v113, v113
	v_fmac_f32_e32 v232, v114, v114
	v_fmac_f32_e32 v232, v115, v115
	global_store_dwordx4 v224, v[124:127], s[16:17]
	global_store_dwordx4 v224, v[120:123], s[16:17] offset:64
	global_store_dwordx4 v224, v[116:119], s[16:17] offset:512
	global_store_dwordx4 v224, v[112:115], s[16:17] offset:576
	global_load_dwordx4 v[140:143], v227, s[16:17]
	global_load_dwordx4 v[144:147], v227, s[16:17] offset:64
	global_load_dwordx4 v[148:151], v227, s[16:17] offset:512
	global_load_dwordx4 v[152:155], v227, s[16:17] offset:576
	s_waitcnt vmcnt(15)
	v_pk_fma_f32 v[108:109], v[108:109], v[196:197], v[164:165]
	v_pk_fma_f32 v[110:111], v[110:111], v[198:199], v[166:167]
	v_mul_f32_e32 v233, v108, v108
	v_fmac_f32_e32 v233, v109, v109
	v_fmac_f32_e32 v233, v110, v110
	v_fmac_f32_e32 v233, v111, v111
	s_waitcnt vmcnt(14)
	v_pk_fma_f32 v[104:105], v[104:105], v[212:213], v[168:169]
	v_pk_fma_f32 v[106:107], v[106:107], v[214:215], v[170:171]
	v_fmac_f32_e32 v233, v104, v104
	v_fmac_f32_e32 v233, v105, v105
	v_fmac_f32_e32 v233, v106, v106
	v_fmac_f32_e32 v233, v107, v107
	s_waitcnt vmcnt(13)
	v_pk_fma_f32 v[100:101], v[100:101], v[216:217], v[172:173]
	v_pk_fma_f32 v[102:103], v[102:103], v[218:219], v[174:175]
	v_fmac_f32_e32 v233, v100, v100
	v_fmac_f32_e32 v233, v101, v101
	v_fmac_f32_e32 v233, v102, v102
	v_fmac_f32_e32 v233, v103, v103
	s_waitcnt vmcnt(12)
	v_pk_fma_f32 v[96:97], v[96:97], v[220:221], v[176:177]
	v_pk_fma_f32 v[98:99], v[98:99], v[222:223], v[178:179]
	v_fmac_f32_e32 v233, v96, v96
	v_fmac_f32_e32 v233, v97, v97
	v_fmac_f32_e32 v233, v98, v98
	v_fmac_f32_e32 v233, v99, v99
	global_store_dwordx4 v225, v[108:111], s[16:17]
	global_store_dwordx4 v225, v[104:107], s[16:17] offset:64
	global_store_dwordx4 v225, v[100:103], s[16:17] offset:512
	global_store_dwordx4 v225, v[96:99], s[16:17] offset:576
	global_load_dwordx4 v[164:167], v228, s[16:17]
	global_load_dwordx4 v[168:171], v228, s[16:17] offset:64
	global_load_dwordx4 v[172:175], v228, s[16:17] offset:512
	global_load_dwordx4 v[176:179], v228, s[16:17] offset:576
	s_waitcnt vmcnt(19)
	v_pk_fma_f32 v[92:93], v[92:93], v[196:197], v[180:181]
	v_pk_fma_f32 v[94:95], v[94:95], v[198:199], v[182:183]
	v_mul_f32_e32 v234, v92, v92
	v_fmac_f32_e32 v234, v93, v93
	v_fmac_f32_e32 v234, v94, v94
	v_fmac_f32_e32 v234, v95, v95
	s_waitcnt vmcnt(18)
	v_pk_fma_f32 v[88:89], v[88:89], v[212:213], v[184:185]
	v_pk_fma_f32 v[90:91], v[90:91], v[214:215], v[186:187]
	v_fmac_f32_e32 v234, v88, v88
	v_fmac_f32_e32 v234, v89, v89
	v_fmac_f32_e32 v234, v90, v90
	v_fmac_f32_e32 v234, v91, v91
	s_waitcnt vmcnt(17)
;     __device__ __forceinline__ void operator()(const f32x4 (&acc)[2][2][4][2], const Unit& u, int wr, int wc, int fr, int fq) const {
;     ...
;         for (int ai = 0; ai < 2; ++ai)
; #pragma unroll
;             for (int m = 0; m < 4; ++m) {
;                 const int row = u.pm * BM + ai * HALF + wr * 64 + m * 16 + fr;
;                 const float* s = row < MX_ ? src_main + (size_t)row * D_ : src_ctx + (size_t)(row - MX_) * D_;
;                 float* d = row < MX_ ? dst_main + (size_t)row * D_ : dst_ctx + (size_t)(row - MX_) * D_;
; #pragma unroll
;                 for (int bj = 0; bj < 2; ++bj)
; #pragma unroll
;                     for (int n = 0; n < 2; ++n) { const int off = col0 + bj * HALF + n * 16; const f32x4 xo = *(const f32x4*)(s + off); *(f32x4*)(d + off) = xo + gv[bj][n] * acc[ai][bj][m][n]; }
	v_pk_fma_f32 v[84:85], v[84:85], v[216:217], v[188:189]
	v_pk_fma_f32 v[86:87], v[86:87], v[218:219], v[190:191]
	v_fmac_f32_e32 v234, v84, v84
	v_fmac_f32_e32 v234, v85, v85
	v_fmac_f32_e32 v234, v86, v86
	v_fmac_f32_e32 v234, v87, v87
	s_waitcnt vmcnt(16)
	v_pk_fma_f32 v[80:81], v[80:81], v[220:221], v[192:193]
	v_pk_fma_f32 v[82:83], v[82:83], v[222:223], v[194:195]
	v_fmac_f32_e32 v234, v80, v80
	v_fmac_f32_e32 v234, v81, v81
	v_fmac_f32_e32 v234, v82, v82
	v_fmac_f32_e32 v234, v83, v83
	global_store_dwordx4 v226, v[92:95], s[16:17]
	global_store_dwordx4 v226, v[88:91], s[16:17] offset:64
	global_store_dwordx4 v226, v[84:87], s[16:17] offset:512
	global_store_dwordx4 v226, v[80:83], s[16:17] offset:576
	global_load_dwordx4 v[180:183], v229, s[16:17]
	global_load_dwordx4 v[184:187], v229, s[16:17] offset:64
	global_load_dwordx4 v[188:191], v229, s[16:17] offset:512
	global_load_dwordx4 v[192:195], v229, s[16:17] offset:576
	s_waitcnt vmcnt(19)
	v_pk_fma_f32 v[76:77], v[76:77], v[196:197], v[140:141]
	v_pk_fma_f32 v[78:79], v[78:79], v[198:199], v[142:143]
	v_mul_f32_e32 v235, v76, v76
	v_fmac_f32_e32 v235, v77, v77
	v_fmac_f32_e32 v235, v78, v78
	v_fmac_f32_e32 v235, v79, v79
	s_waitcnt vmcnt(18)
	v_pk_fma_f32 v[72:73], v[72:73], v[212:213], v[144:145]
	v_pk_fma_f32 v[74:75], v[74:75], v[214:215], v[146:147]
	v_fmac_f32_e32 v235, v72, v72
	v_fmac_f32_e32 v235, v73, v73
	v_fmac_f32_e32 v235, v74, v74
	v_fmac_f32_e32 v235, v75, v75
	s_waitcnt vmcnt(17)
	v_pk_fma_f32 v[68:69], v[68:69], v[216:217], v[148:149]
	v_pk_fma_f32 v[70:71], v[70:71], v[218:219], v[150:151]
	v_fmac_f32_e32 v235, v68, v68
	v_fmac_f32_e32 v235, v69, v69
	v_fmac_f32_e32 v235, v70, v70
	v_fmac_f32_e32 v235, v71, v71
	s_waitcnt vmcnt(16)
	v_pk_fma_f32 v[64:65], v[64:65], v[220:221], v[152:153]
	v_pk_fma_f32 v[66:67], v[66:67], v[222:223], v[154:155]
	v_fmac_f32_e32 v235, v64, v64
	v_fmac_f32_e32 v235, v65, v65
	v_fmac_f32_e32 v235, v66, v66
	v_fmac_f32_e32 v235, v67, v67
	global_store_dwordx4 v227, v[76:79], s[16:17]
	global_store_dwordx4 v227, v[72:75], s[16:17] offset:64
	global_store_dwordx4 v227, v[68:71], s[16:17] offset:512
	global_store_dwordx4 v227, v[64:67], s[16:17] offset:576
	global_load_dwordx4 v[140:143], v230, s[16:17]
	global_load_dwordx4 v[144:147], v230, s[16:17] offset:64
	global_load_dwordx4 v[148:151], v230, s[16:17] offset:512
	global_load_dwordx4 v[152:155], v230, s[16:17] offset:576
	s_waitcnt vmcnt(19)
	v_pk_fma_f32 v[60:61], v[60:61], v[196:197], v[164:165]
	v_pk_fma_f32 v[62:63], v[62:63], v[198:199], v[166:167]
	v_mul_f32_e32 v236, v60, v60
	v_fmac_f32_e32 v236, v61, v61
	v_fmac_f32_e32 v236, v62, v62
	v_fmac_f32_e32 v236, v63, v63
	s_waitcnt vmcnt(18)
	v_pk_fma_f32 v[56:57], v[56:57], v[212:213], v[168:169]
	v_pk_fma_f32 v[58:59], v[58:59], v[214:215], v[170:171]
	v_fmac_f32_e32 v236, v56, v56
	v_fmac_f32_e32 v236, v57, v57
	v_fmac_f32_e32 v236, v58, v58
	v_fmac_f32_e32 v236, v59, v59
	s_waitcnt vmcnt(17)
	v_pk_fma_f32 v[52:53], v[52:53], v[216:217], v[172:173]
	v_pk_fma_f32 v[54:55], v[54:55], v[218:219], v[174:175]
	v_fmac_f32_e32 v236, v52, v52
	v_fmac_f32_e32 v236, v53, v53
	v_fmac_f32_e32 v236, v54, v54
	v_fmac_f32_e32 v236, v55, v55
	s_waitcnt vmcnt(16)
	v_pk_fma_f32 v[48:49], v[48:49], v[220:221], v[176:177]
	v_pk_fma_f32 v[50:51], v[50:51], v[222:223], v[178:179]
	v_fmac_f32_e32 v236, v48, v48
	v_fmac_f32_e32 v236, v49, v49
	v_fmac_f32_e32 v236, v50, v50
	v_fmac_f32_e32 v236, v51, v51
	global_store_dwordx4 v228, v[60:63], s[16:17]
	global_store_dwordx4 v228, v[56:59], s[16:17] offset:64
	global_store_dwordx4 v228, v[52:55], s[16:17] offset:512
	global_store_dwordx4 v228, v[48:51], s[16:17] offset:576
	global_load_dwordx4 v[164:167], v231, s[16:17]
	global_load_dwordx4 v[168:171], v231, s[16:17] offset:64
	global_load_dwordx4 v[172:175], v231, s[16:17] offset:512
	global_load_dwordx4 v[176:179], v231, s[16:17] offset:576
	s_waitcnt vmcnt(19)
	v_pk_fma_f32 v[44:45], v[44:45], v[196:197], v[180:181]
	v_pk_fma_f32 v[46:47], v[46:47], v[198:199], v[182:183]
	v_mul_f32_e32 v237, v44, v44
	v_fmac_f32_e32 v237, v45, v45
	v_fmac_f32_e32 v237, v46, v46
	v_fmac_f32_e32 v237, v47, v47
	s_waitcnt vmcnt(18)
	v_pk_fma_f32 v[40:41], v[40:41], v[212:213], v[184:185]
	v_pk_fma_f32 v[42:43], v[42:43], v[214:215], v[186:187]
	v_fmac_f32_e32 v237, v40, v40
	v_fmac_f32_e32 v237, v41, v41
	v_fmac_f32_e32 v237, v42, v42
	v_fmac_f32_e32 v237, v43, v43
	s_waitcnt vmcnt(17)
	v_pk_fma_f32 v[36:37], v[36:37], v[216:217], v[188:189]
	v_pk_fma_f32 v[38:39], v[38:39], v[218:219], v[190:191]
	v_fmac_f32_e32 v237, v36, v36
	v_fmac_f32_e32 v237, v37, v37
	v_fmac_f32_e32 v237, v38, v38
	v_fmac_f32_e32 v237, v39, v39
	s_waitcnt vmcnt(16)
	v_pk_fma_f32 v[32:33], v[32:33], v[220:221], v[192:193]
	v_pk_fma_f32 v[34:35], v[34:35], v[222:223], v[194:195]
	v_fmac_f32_e32 v237, v32, v32
	v_fmac_f32_e32 v237, v33, v33
	v_fmac_f32_e32 v237, v34, v34
	v_fmac_f32_e32 v237, v35, v35
	global_store_dwordx4 v229, v[44:47], s[16:17]
	global_store_dwordx4 v229, v[40:43], s[16:17] offset:64
	global_store_dwordx4 v229, v[36:39], s[16:17] offset:512
	global_store_dwordx4 v229, v[32:35], s[16:17] offset:576
	s_waitcnt vmcnt(15)
;     __device__ __forceinline__ void operator()(const f32x4 (&acc)[2][2][4][2], const Unit& u, int wr, int wc, int fr, int fq) const {
;     ...
;         for (int ai = 0; ai < 2; ++ai)
; #pragma unroll
;             for (int m = 0; m < 4; ++m) {
;                 const int row = u.pm * BM + ai * HALF + wr * 64 + m * 16 + fr;
;                 const float* s = row < MX_ ? src_main + (size_t)row * D_ : src_ctx + (size_t)(row - MX_) * D_;
;                 float* d = row < MX_ ? dst_main + (size_t)row * D_ : dst_ctx + (size_t)(row - MX_) * D_;
; #pragma unroll
;                 for (int bj = 0; bj < 2; ++bj)
; #pragma unroll
;                     for (int n = 0; n < 2; ++n) { const int off = col0 + bj * HALF + n * 16; const f32x4 xo = *(const f32x4*)(s + off); *(f32x4*)(d + off) = xo + gv[bj][n] * acc[ai][bj][m][n]; }
;     __device__ __forceinline__ void operator()(const f32x4 (&acc)[2][2][4][2], const Unit& u, int wr, int wc, int fr, int fq) const {
;     ...
;                         s1 += __shfl_xor(s1, 16); s1 += __shfl_xor(s1, 32); s2 += __shfl_xor(s2, 16); s2 += __shfl_xor(s2, 32);
;                         if (fq == 0) { unsafeAtomicAdd(stats + 2 * row, s1); unsafeAtomicAdd(stats + 2 * row + 1, s2); }
	v_pk_fma_f32 v[28:29], v[28:29], v[196:197], v[140:141]
	v_pk_fma_f32 v[30:31], v[30:31], v[198:199], v[142:143]
	v_mul_f32_e32 v238, v28, v28
	v_fmac_f32_e32 v238, v29, v29
	v_fmac_f32_e32 v238, v30, v30
	v_fmac_f32_e32 v238, v31, v31
	s_waitcnt vmcnt(14)
	v_pk_fma_f32 v[24:25], v[24:25], v[212:213], v[144:145]
	v_pk_fma_f32 v[26:27], v[26:27], v[214:215], v[146:147]
	v_fmac_f32_e32 v238, v24, v24
	v_fmac_f32_e32 v238, v25, v25
	v_fmac_f32_e32 v238, v26, v26
	v_fmac_f32_e32 v238, v27, v27
	s_waitcnt vmcnt(13)
	v_pk_fma_f32 v[20:21], v[20:21], v[216:217], v[148:149]
	v_pk_fma_f32 v[22:23], v[22:23], v[218:219], v[150:151]
	v_fmac_f32_e32 v238, v20, v20
	v_fmac_f32_e32 v238, v21, v21
	v_fmac_f32_e32 v238, v22, v22
	v_fmac_f32_e32 v238, v23, v23
	s_waitcnt vmcnt(12)
	v_pk_fma_f32 v[16:17], v[16:17], v[220:221], v[152:153]
	v_pk_fma_f32 v[18:19], v[18:19], v[222:223], v[154:155]
	v_fmac_f32_e32 v238, v16, v16
	v_fmac_f32_e32 v238, v17, v17
	v_fmac_f32_e32 v238, v18, v18
	v_fmac_f32_e32 v238, v19, v19
	global_store_dwordx4 v230, v[28:31], s[16:17]
	global_store_dwordx4 v230, v[24:27], s[16:17] offset:64
	global_store_dwordx4 v230, v[20:23], s[16:17] offset:512
	global_store_dwordx4 v230, v[16:19], s[16:17] offset:576
	s_waitcnt vmcnt(11)
	v_pk_fma_f32 v[12:13], v[12:13], v[196:197], v[164:165]
	v_pk_fma_f32 v[14:15], v[14:15], v[198:199], v[166:167]
	v_mul_f32_e32 v239, v12, v12
	v_fmac_f32_e32 v239, v13, v13
	v_fmac_f32_e32 v239, v14, v14
	v_fmac_f32_e32 v239, v15, v15
	s_waitcnt vmcnt(10)
	v_pk_fma_f32 v[8:9], v[8:9], v[212:213], v[168:169]
	v_pk_fma_f32 v[10:11], v[10:11], v[214:215], v[170:171]
	v_fmac_f32_e32 v239, v8, v8
	v_fmac_f32_e32 v239, v9, v9
	v_fmac_f32_e32 v239, v10, v10
	v_fmac_f32_e32 v239, v11, v11
	s_waitcnt vmcnt(9)
	v_pk_fma_f32 v[4:5], v[4:5], v[216:217], v[172:173]
	v_pk_fma_f32 v[6:7], v[6:7], v[218:219], v[174:175]
	v_fmac_f32_e32 v239, v4, v4
	v_fmac_f32_e32 v239, v5, v5
	v_fmac_f32_e32 v239, v6, v6
	v_fmac_f32_e32 v239, v7, v7
	s_waitcnt vmcnt(8)
	v_pk_fma_f32 v[0:1], v[0:1], v[220:221], v[176:177]
	v_pk_fma_f32 v[2:3], v[2:3], v[222:223], v[178:179]
	v_fmac_f32_e32 v239, v0, v0
	v_fmac_f32_e32 v239, v1, v1
	v_fmac_f32_e32 v239, v2, v2
	v_fmac_f32_e32 v239, v3, v3
	global_store_dwordx4 v231, v[12:15], s[16:17]
	global_store_dwordx4 v231, v[8:11], s[16:17] offset:64
	global_store_dwordx4 v231, v[4:7], s[16:17] offset:512
	global_store_dwordx4 v231, v[0:3], s[16:17] offset:576
	v_mbcnt_lo_u32_b32 v240, -1, 0
	v_mbcnt_hi_u32_b32 v240, -1, v240
	v_xor_b32_e32 v241, 16, v240
	v_xor_b32_e32 v242, 32, v240
	v_lshlrev_b32_e32 v241, 2, v241
	v_lshlrev_b32_e32 v242, 2, v242
	s_waitcnt lgkmcnt(0)
	ds_bpermute_b32 v140, v241, v232
	ds_bpermute_b32 v141, v241, v233
	ds_bpermute_b32 v142, v241, v234
	ds_bpermute_b32 v143, v241, v235
	ds_bpermute_b32 v144, v241, v236
	ds_bpermute_b32 v145, v241, v237
	ds_bpermute_b32 v146, v241, v238
	ds_bpermute_b32 v147, v241, v239
	s_waitcnt lgkmcnt(7)
	v_add_f32_e32 v232, v232, v140
	s_waitcnt lgkmcnt(6)
	v_add_f32_e32 v233, v233, v141
	s_waitcnt lgkmcnt(5)
	v_add_f32_e32 v234, v234, v142
	s_waitcnt lgkmcnt(4)
	v_add_f32_e32 v235, v235, v143
	s_waitcnt lgkmcnt(3)
	v_add_f32_e32 v236, v236, v144
	s_waitcnt lgkmcnt(2)
	v_add_f32_e32 v237, v237, v145
	s_waitcnt lgkmcnt(1)
	v_add_f32_e32 v238, v238, v146
	s_waitcnt lgkmcnt(0)
	v_add_f32_e32 v239, v239, v147
	ds_bpermute_b32 v140, v242, v232
	ds_bpermute_b32 v141, v242, v233
	ds_bpermute_b32 v142, v242, v234
	ds_bpermute_b32 v143, v242, v235
	ds_bpermute_b32 v144, v242, v236
	ds_bpermute_b32 v145, v242, v237
	ds_bpermute_b32 v146, v242, v238
	ds_bpermute_b32 v147, v242, v239
	s_waitcnt lgkmcnt(7)
	v_add_f32_e32 v232, v232, v140
	s_waitcnt lgkmcnt(6)
	v_add_f32_e32 v233, v233, v141
	s_waitcnt lgkmcnt(5)
	v_add_f32_e32 v234, v234, v142
	s_waitcnt lgkmcnt(4)
	v_add_f32_e32 v235, v235, v143
	s_waitcnt lgkmcnt(3)
	v_add_f32_e32 v236, v236, v144
	s_waitcnt lgkmcnt(2)
	v_add_f32_e32 v237, v237, v145
	s_waitcnt lgkmcnt(1)
	v_add_f32_e32 v238, v238, v146
	s_waitcnt lgkmcnt(0)
	v_add_f32_e32 v239, v239, v147
	v_lshlrev_b32_e32 v243, 2, v156
	s_add_u32 s90, s76, 0x6500000
	s_addc_u32 s91, s77, 0
	s_add_u32 s76, s76, 0x3164000
	s_addc_u32 s77, s77, 0
	s_lshl_b32 s83, s6, 6
	s_add_u32 s78, s76, s83
	s_addc_u32 s79, s77, 0
	s_add_u32 s78, s78, 0x20000
	s_addc_u32 s79, s79, 0
	s_mov_b64 s[80:81], exec
	s_mov_b64 exec, 0xffff
	global_atomic_add_f32 v243, v232, s[76:77]
	global_atomic_add_f32 v243, v233, s[76:77] offset:64
	global_atomic_add_f32 v243, v234, s[76:77] offset:128
	global_atomic_add_f32 v243, v235, s[76:77] offset:192
	global_atomic_add_f32 v243, v236, s[76:77] offset:512
	global_atomic_add_f32 v243, v237, s[76:77] offset:576
	global_atomic_add_f32 v243, v238, s[76:77] offset:640
	global_atomic_add_f32 v243, v239, s[76:77] offset:704
	s_mov_b64 exec, s[80:81]
	s_add_u32 s86, s8, 0x13000
	s_addc_u32 s87, s9, 0
	s_add_u32 s88, s86, 0x1000
	s_addc_u32 s89, s87, 0
	s_add_u32 s92, s92, 0x3000
	s_addc_u32 s93, s93, 0
	s_mov_b32 s84, 0xffff0000
	s_mov_b32 s85, 0xffff0000
	s_waitcnt vmcnt(0)
	s_barrier
	v_readfirstlane_b32 s83, v206
	v_mov_b32_e32 v244, 0
	v_mov_b32_e32 v245, 1
	s_cmp_lg_u32 s83, 0
	s_cbranch_scc1 .Lfmd_wait_done
	s_mov_b64 exec, 1
	global_atomic_add v244, v245, s[78:79]
	s_mov_b32 s82, 0

; __device__ __forceinline__ unsigned cvtpk_s(float lo, float hi) { f32x2_t v = {lo, hi}; bf16x2_t b = __builtin_convertvector(v, bf16x2_t); return __builtin_bit_cast(unsigned, b); }
; __device__ __forceinline__ u32x4 quad_swap(unsigned lo0, unsigned lo1, unsigned hi0, unsigned hi1, int fq, int& coloff) {
;     const bool odd = fq & 1;
;     const unsigned s0 = odd ? lo0 : hi0, s1 = odd ? lo1 : hi1;
;     const unsigned r0 = (unsigned)__shfl_xor((int)s0, 16), r1 = (unsigned)__shfl_xor((int)s1, 16);
;     coloff = odd ? 16 + 4 * (fq - 1) : 4 * fq;
;     u32x4 o; o.x = odd ? r0 : lo0; o.y = odd ? r1 : lo1; o.z = odd ? hi0 : r0; o.w = odd ? hi1 : r1; return o;
; __device__ __forceinline__ void modpass(const float* xs_main, const float* xs_ctx, const float* mod_l, const float* g, int i, bf16_t* H, int nrows, int gw, int NGW, int lane) {
;     ...
;         if (cond != cur) { cur = cond; const float* shift = mod_l + cond * 9216 + 3 * i * 1024; const float* scale = shift + 1024;
; #pragma unroll
;             for (int j = 0; j < 2; ++j)
; #pragma unroll
;                 for (int q = 0; q < 2; ++q) { const int c = 8 * lane + 512 * j + 4 * q; gm[j][q] = *(const f32x4*)(g + c) * (*(const f32x4*)(scale + c) + 1.0f); sh[j][q] = *(const f32x4*)(shift + c); } }
;         float ss = 0.f;
; #pragma unroll
;         for (int j = 0; j < 2; ++j)
; #pragma unroll
;             for (int q = 0; q < 2; ++q) ss += (v[j][q][0] * v[j][q][0] + v[j][q][1] * v[j][q][1]) + (v[j][q][2] * v[j][q][2] + v[j][q][3] * v[j][q][3]);
;         const float rstd = 1.0f / sqrtf(wave_sum(ss) * (1.0f / D) + EPS);
; #pragma unroll
;         for (int j = 0; j < 2; ++j) {
;             const f32x4 o0 = v[j][0] * rstd * gm[j][0] + sh[j][0], o1 = v[j][1] * rstd * gm[j][1] + sh[j][1];
;             u32x4 w; w.x = cvtpk_s(o0[0], o0[1]); w.y = cvtpk_s(o0[2], o0[3]); w.z = cvtpk_s(o1[0], o1[1]); w.w = cvtpk_s(o1[2], o1[3]);
;             *(u32x4*)(H + (size_t)row * D + 8 * lane + 512 * j) = w;
.Lfmd_wait_done:
	s_barrier
	global_load_dword v144, v243, s[76:77] sc1
	global_load_dword v145, v243, s[76:77] offset:64 sc1
	global_load_dword v146, v243, s[76:77] offset:128 sc1
	global_load_dword v147, v243, s[76:77] offset:192 sc1
	global_load_dword v148, v243, s[76:77] offset:512 sc1
	global_load_dword v149, v243, s[76:77] offset:576 sc1
	global_load_dword v150, v243, s[76:77] offset:640 sc1
	global_load_dword v151, v243, s[76:77] offset:704 sc1
	global_load_dwordx4 v[196:199], v201, s[86:87]
	global_load_dwordx4 v[212:215], v201, s[86:87] offset:64
	global_load_dwordx4 v[216:219], v201, s[86:87] offset:512
	global_load_dwordx4 v[220:223], v201, s[86:87] offset:576
	global_load_dwordx4 v[152:155], v201, s[88:89]
	global_load_dwordx4 v[164:167], v201, s[88:89] offset:64
	global_load_dwordx4 v[168:171], v201, s[88:89] offset:512
	global_load_dwordx4 v[172:175], v201, s[88:89] offset:576
	global_load_dwordx4 v[176:179], v201, s[92:93]
	global_load_dwordx4 v[180:183], v201, s[92:93] offset:64
	global_load_dwordx4 v[184:187], v201, s[92:93] offset:512
	global_load_dwordx4 v[188:191], v201, s[92:93] offset:576
	v_mov_b32_e32 v240, 12
	v_cndmask_b32_e64 v240, 0, v240, s[84:85]
	v_add_u32_e32 v240, v240, v157
	v_lshlrev_b32_e32 v240, 1, v240
	v_lshl_add_u32 v247, v156, 11, v240
	v_mov_b32_e32 v240, 0x358637bd
	s_waitcnt vmcnt(0)
	v_fmamk_f32 v144, v144, 0x3a800000, v240
	v_fmamk_f32 v145, v145, 0x3a800000, v240
	v_fmamk_f32 v146, v146, 0x3a800000, v240
	v_fmamk_f32 v147, v147, 0x3a800000, v240
	v_fmamk_f32 v148, v148, 0x3a800000, v240
	v_fmamk_f32 v149, v149, 0x3a800000, v240
	v_fmamk_f32 v150, v150, 0x3a800000, v240
	v_fmamk_f32 v151, v151, 0x3a800000, v240
	v_rsq_f32_e32 v144, v144
	v_rsq_f32_e32 v145, v145
	v_rsq_f32_e32 v146, v146
	v_rsq_f32_e32 v147, v147
	v_rsq_f32_e32 v148, v148
	v_rsq_f32_e32 v149, v149
	v_rsq_f32_e32 v150, v150
	v_rsq_f32_e32 v151, v151
	v_pk_add_f32 v[152:153], v[152:153], 1.0 op_sel_hi:[1,0]
	v_pk_mul_f32 v[152:153], v[176:177], v[152:153]
	v_pk_add_f32 v[154:155], v[154:155], 1.0 op_sel_hi:[1,0]
	v_pk_mul_f32 v[154:155], v[178:179], v[154:155]
	v_pk_add_f32 v[164:165], v[164:165], 1.0 op_sel_hi:[1,0]
	v_pk_mul_f32 v[164:165], v[180:181], v[164:165]
	v_pk_add_f32 v[166:167], v[166:167], 1.0 op_sel_hi:[1,0]
	v_pk_mul_f32 v[166:167], v[182:183], v[166:167]
	v_pk_add_f32 v[168:169], v[168:169], 1.0 op_sel_hi:[1,0]
	v_pk_mul_f32 v[168:169], v[184:185], v[168:169]
	v_pk_add_f32 v[170:171], v[170:171], 1.0 op_sel_hi:[1,0]
	v_pk_mul_f32 v[170:171], v[186:187], v[170:171]
	v_pk_add_f32 v[172:173], v[172:173], 1.0 op_sel_hi:[1,0]
	v_pk_mul_f32 v[172:173], v[188:189], v[172:173]
	v_pk_add_f32 v[174:175], v[174:175], 1.0 op_sel_hi:[1,0]
	v_pk_mul_f32 v[174:175], v[190:191], v[174:175]
	v_mul_f32_e32 v124, v124, v144
	v_mul_f32_e32 v125, v125, v144
	v_pk_fma_f32 v[124:125], v[152:153], v[124:125], v[196:197]
	v_mul_f32_e32 v126, v126, v144
	v_mul_f32_e32 v127, v127, v144
	v_pk_fma_f32 v[126:127], v[154:155], v[126:127], v[198:199]
	v_cvt_pk_bf16_f32 v184, v124, v125
	v_cvt_pk_bf16_f32 v185, v126, v127
	v_mul_f32_e32 v120, v120, v144
	v_mul_f32_e32 v121, v121, v144
	v_pk_fma_f32 v[120:121], v[164:165], v[120:121], v[212:213]
	v_mul_f32_e32 v122, v122, v144
	v_mul_f32_e32 v123, v123, v144
	v_pk_fma_f32 v[122:123], v[166:167], v[122:123], v[214:215]
	v_cvt_pk_bf16_f32 v186, v120, v121
	v_cvt_pk_bf16_f32 v187, v122, v123
	v_mul_f32_e32 v116, v116, v144
	v_mul_f32_e32 v117, v117, v144
	v_pk_fma_f32 v[116:117], v[168:169], v[116:117], v[216:217]
	v_mul_f32_e32 v118, v118, v144
	v_mul_f32_e32 v119, v119, v144
	v_pk_fma_f32 v[118:119], v[170:171], v[118:119], v[218:219]
	v_cvt_pk_bf16_f32 v188, v116, v117
	v_cvt_pk_bf16_f32 v189, v118, v119
	v_mul_f32_e32 v112, v112, v144
	v_mul_f32_e32 v113, v113, v144
	v_pk_fma_f32 v[112:113], v[172:173], v[112:113], v[220:221]
	v_mul_f32_e32 v114, v114, v144
	v_mul_f32_e32 v115, v115, v144
	v_pk_fma_f32 v[114:115], v[174:175], v[114:115], v[222:223]
	v_cvt_pk_bf16_f32 v190, v112, v113
	v_cvt_pk_bf16_f32 v191, v114, v115
	v_mov_b32_e32 v240, v247
	v_cndmask_b32_e64 v192, v186, v184, s[84:85]
	v_cndmask_b32_e64 v193, v187, v185, s[84:85]
	ds_bpermute_b32 v194, v241, v192
	ds_bpermute_b32 v195, v241, v193
	s_waitcnt lgkmcnt(0)
	v_cndmask_b32_e64 v176, v184, v194, s[84:85]
	v_cndmask_b32_e64 v177, v185, v195, s[84:85]
	v_cndmask_b32_e64 v178, v194, v186, s[84:85]
	v_cndmask_b32_e64 v179, v195, v187, s[84:85]
	global_store_dwordx4 v240, v[176:179], s[90:91]
	v_cndmask_b32_e64 v192, v190, v188, s[84:85]
	v_cndmask_b32_e64 v193, v191, v189, s[84:85]
	ds_bpermute_b32 v194, v241, v192
	ds_bpermute_b32 v195, v241, v193
	s_waitcnt lgkmcnt(0)
	v_cndmask_b32_e64 v180, v188, v194, s[84:85]
	v_cndmask_b32_e64 v181, v189, v195, s[84:85]
	v_cndmask_b32_e64 v182, v194, v190, s[84:85]
	v_cndmask_b32_e64 v183, v195, v191, s[84:85]
	global_store_dwordx4 v240, v[180:183], s[90:91] offset:256
	v_mul_f32_e32 v108, v108, v145
	v_mul_f32_e32 v109, v109, v145
	v_pk_fma_f32 v[108:109], v[152:153], v[108:109], v[196:197]
	v_mul_f32_e32 v110, v110, v145
	v_mul_f32_e32 v111, v111, v145
	v_pk_fma_f32 v[110:111], v[154:155], v[110:111], v[198:199]
	v_cvt_pk_bf16_f32 v184, v108, v109
	v_cvt_pk_bf16_f32 v185, v110, v111
	v_mul_f32_e32 v104, v104, v145
	v_mul_f32_e32 v105, v105, v145
	v_pk_fma_f32 v[104:105], v[164:165], v[104:105], v[212:213]
	v_mul_f32_e32 v106, v106, v145
	v_mul_f32_e32 v107, v107, v145
	v_pk_fma_f32 v[106:107], v[166:167], v[106:107], v[214:215]
	v_cvt_pk_bf16_f32 v186, v104, v105
	v_cvt_pk_bf16_f32 v187, v106, v107
	v_mul_f32_e32 v100, v100, v145
	v_mul_f32_e32 v101, v101, v145
	v_pk_fma_f32 v[100:101], v[168:169], v[100:101], v[216:217]
	v_mul_f32_e32 v102, v102, v145
	v_mul_f32_e32 v103, v103, v145
	v_pk_fma_f32 v[102:103], v[170:171], v[102:103], v[218:219]
	v_cvt_pk_bf16_f32 v188, v100, v101
	v_cvt_pk_bf16_f32 v189, v102, v103
	v_mul_f32_e32 v96, v96, v145
	v_mul_f32_e32 v97, v97, v145
	v_pk_fma_f32 v[96:97], v[172:173], v[96:97], v[220:221]
	v_mul_f32_e32 v98, v98, v145
	v_mul_f32_e32 v99, v99, v145
	v_pk_fma_f32 v[98:99], v[174:175], v[98:99], v[222:223]
	v_cvt_pk_bf16_f32 v190, v96, v97
	v_cvt_pk_bf16_f32 v191, v98, v99
	v_add_u32_e32 v240, 0x8000, v247
	v_cndmask_b32_e64 v192, v186, v184, s[84:85]
	v_cndmask_b32_e64 v193, v187, v185, s[84:85]
	ds_bpermute_b32 v194, v241, v192
	ds_bpermute_b32 v195, v241, v193
	s_waitcnt lgkmcnt(0)
; __device__ __forceinline__ unsigned cvtpk_s(float lo, float hi) { f32x2_t v = {lo, hi}; bf16x2_t b = __builtin_convertvector(v, bf16x2_t); return __builtin_bit_cast(unsigned, b); }
; __device__ __forceinline__ u32x4 quad_swap(unsigned lo0, unsigned lo1, unsigned hi0, unsigned hi1, int fq, int& coloff) {
;     const bool odd = fq & 1;
;     const unsigned s0 = odd ? lo0 : hi0, s1 = odd ? lo1 : hi1;
;     const unsigned r0 = (unsigned)__shfl_xor((int)s0, 16), r1 = (unsigned)__shfl_xor((int)s1, 16);
;     coloff = odd ? 16 + 4 * (fq - 1) : 4 * fq;
;     u32x4 o; o.x = odd ? r0 : lo0; o.y = odd ? r1 : lo1; o.z = odd ? hi0 : r0; o.w = odd ? hi1 : r1; return o;
; __device__ __forceinline__ void modpass(const float* xs_main, const float* xs_ctx, const float* mod_l, const float* g, int i, bf16_t* H, int nrows, int gw, int NGW, int lane) {
;     ...
;         for (int j = 0; j < 2; ++j) {
;             const f32x4 o0 = v[j][0] * rstd * gm[j][0] + sh[j][0], o1 = v[j][1] * rstd * gm[j][1] + sh[j][1];
;             u32x4 w; w.x = cvtpk_s(o0[0], o0[1]); w.y = cvtpk_s(o0[2], o0[3]); w.z = cvtpk_s(o1[0], o1[1]); w.w = cvtpk_s(o1[2], o1[3]);
;             *(u32x4*)(H + (size_t)row * D + 8 * lane + 512 * j) = w;
	v_cndmask_b32_e64 v176, v184, v194, s[84:85]
	v_cndmask_b32_e64 v177, v185, v195, s[84:85]
	v_cndmask_b32_e64 v178, v194, v186, s[84:85]
	v_cndmask_b32_e64 v179, v195, v187, s[84:85]
	global_store_dwordx4 v240, v[176:179], s[90:91]
	v_cndmask_b32_e64 v192, v190, v188, s[84:85]
	v_cndmask_b32_e64 v193, v191, v189, s[84:85]
	ds_bpermute_b32 v194, v241, v192
	ds_bpermute_b32 v195, v241, v193
	s_waitcnt lgkmcnt(0)
	v_cndmask_b32_e64 v180, v188, v194, s[84:85]
	v_cndmask_b32_e64 v181, v189, v195, s[84:85]
	v_cndmask_b32_e64 v182, v194, v190, s[84:85]
	v_cndmask_b32_e64 v183, v195, v191, s[84:85]
	global_store_dwordx4 v240, v[180:183], s[90:91] offset:256
	v_mul_f32_e32 v92, v92, v146
	v_mul_f32_e32 v93, v93, v146
	v_pk_fma_f32 v[92:93], v[152:153], v[92:93], v[196:197]
	v_mul_f32_e32 v94, v94, v146
	v_mul_f32_e32 v95, v95, v146
	v_pk_fma_f32 v[94:95], v[154:155], v[94:95], v[198:199]
	v_cvt_pk_bf16_f32 v184, v92, v93
	v_cvt_pk_bf16_f32 v185, v94, v95
	v_mul_f32_e32 v88, v88, v146
	v_mul_f32_e32 v89, v89, v146
	v_pk_fma_f32 v[88:89], v[164:165], v[88:89], v[212:213]
	v_mul_f32_e32 v90, v90, v146
	v_mul_f32_e32 v91, v91, v146
	v_pk_fma_f32 v[90:91], v[166:167], v[90:91], v[214:215]
	v_cvt_pk_bf16_f32 v186, v88, v89
	v_cvt_pk_bf16_f32 v187, v90, v91
	v_mul_f32_e32 v84, v84, v146
	v_mul_f32_e32 v85, v85, v146
	v_pk_fma_f32 v[84:85], v[168:169], v[84:85], v[216:217]
	v_mul_f32_e32 v86, v86, v146
	v_mul_f32_e32 v87, v87, v146
	v_pk_fma_f32 v[86:87], v[170:171], v[86:87], v[218:219]
	v_cvt_pk_bf16_f32 v188, v84, v85
	v_cvt_pk_bf16_f32 v189, v86, v87
	v_mul_f32_e32 v80, v80, v146
	v_mul_f32_e32 v81, v81, v146
	v_pk_fma_f32 v[80:81], v[172:173], v[80:81], v[220:221]
	v_mul_f32_e32 v82, v82, v146
	v_mul_f32_e32 v83, v83, v146
	v_pk_fma_f32 v[82:83], v[174:175], v[82:83], v[222:223]
	v_cvt_pk_bf16_f32 v190, v80, v81
	v_cvt_pk_bf16_f32 v191, v82, v83
	v_add_u32_e32 v240, 0x10000, v247
	v_cndmask_b32_e64 v192, v186, v184, s[84:85]
	v_cndmask_b32_e64 v193, v187, v185, s[84:85]
	ds_bpermute_b32 v194, v241, v192
	ds_bpermute_b32 v195, v241, v193
	s_waitcnt lgkmcnt(0)
	v_cndmask_b32_e64 v176, v184, v194, s[84:85]
	v_cndmask_b32_e64 v177, v185, v195, s[84:85]
	v_cndmask_b32_e64 v178, v194, v186, s[84:85]
	v_cndmask_b32_e64 v179, v195, v187, s[84:85]
	global_store_dwordx4 v240, v[176:179], s[90:91]
	v_cndmask_b32_e64 v192, v190, v188, s[84:85]
	v_cndmask_b32_e64 v193, v191, v189, s[84:85]
	ds_bpermute_b32 v194, v241, v192
	ds_bpermute_b32 v195, v241, v193
	s_waitcnt lgkmcnt(0)
	v_cndmask_b32_e64 v180, v188, v194, s[84:85]
	v_cndmask_b32_e64 v181, v189, v195, s[84:85]
	v_cndmask_b32_e64 v182, v194, v190, s[84:85]
	v_cndmask_b32_e64 v183, v195, v191, s[84:85]
	global_store_dwordx4 v240, v[180:183], s[90:91] offset:256
	v_mul_f32_e32 v76, v76, v147
	v_mul_f32_e32 v77, v77, v147
	v_pk_fma_f32 v[76:77], v[152:153], v[76:77], v[196:197]
	v_mul_f32_e32 v78, v78, v147
	v_mul_f32_e32 v79, v79, v147
	v_pk_fma_f32 v[78:79], v[154:155], v[78:79], v[198:199]
	v_cvt_pk_bf16_f32 v184, v76, v77
	v_cvt_pk_bf16_f32 v185, v78, v79
	v_mul_f32_e32 v72, v72, v147
	v_mul_f32_e32 v73, v73, v147
	v_pk_fma_f32 v[72:73], v[164:165], v[72:73], v[212:213]
	v_mul_f32_e32 v74, v74, v147
	v_mul_f32_e32 v75, v75, v147
	v_pk_fma_f32 v[74:75], v[166:167], v[74:75], v[214:215]
	v_cvt_pk_bf16_f32 v186, v72, v73
	v_cvt_pk_bf16_f32 v187, v74, v75
	v_mul_f32_e32 v68, v68, v147
	v_mul_f32_e32 v69, v69, v147
	v_pk_fma_f32 v[68:69], v[168:169], v[68:69], v[216:217]
	v_mul_f32_e32 v70, v70, v147
	v_mul_f32_e32 v71, v71, v147
	v_pk_fma_f32 v[70:71], v[170:171], v[70:71], v[218:219]
	v_cvt_pk_bf16_f32 v188, v68, v69
	v_cvt_pk_bf16_f32 v189, v70, v71
	v_mul_f32_e32 v64, v64, v147
	v_mul_f32_e32 v65, v65, v147
	v_pk_fma_f32 v[64:65], v[172:173], v[64:65], v[220:221]
	v_mul_f32_e32 v66, v66, v147
	v_mul_f32_e32 v67, v67, v147
	v_pk_fma_f32 v[66:67], v[174:175], v[66:67], v[222:223]
	v_cvt_pk_bf16_f32 v190, v64, v65
	v_cvt_pk_bf16_f32 v191, v66, v67
	v_add_u32_e32 v240, 0x18000, v247
	v_cndmask_b32_e64 v192, v186, v184, s[84:85]
	v_cndmask_b32_e64 v193, v187, v185, s[84:85]
	ds_bpermute_b32 v194, v241, v192
	ds_bpermute_b32 v195, v241, v193
	s_waitcnt lgkmcnt(0)
	v_cndmask_b32_e64 v176, v184, v194, s[84:85]
	v_cndmask_b32_e64 v177, v185, v195, s[84:85]
	v_cndmask_b32_e64 v178, v194, v186, s[84:85]
	v_cndmask_b32_e64 v179, v195, v187, s[84:85]
	global_store_dwordx4 v240, v[176:179], s[90:91]
	v_cndmask_b32_e64 v192, v190, v188, s[84:85]
	v_cndmask_b32_e64 v193, v191, v189, s[84:85]
	ds_bpermute_b32 v194, v241, v192
	ds_bpermute_b32 v195, v241, v193
	s_waitcnt lgkmcnt(0)
	v_cndmask_b32_e64 v180, v188, v194, s[84:85]
	v_cndmask_b32_e64 v181, v189, v195, s[84:85]
	v_cndmask_b32_e64 v182, v194, v190, s[84:85]
	v_cndmask_b32_e64 v183, v195, v191, s[84:85]
	global_store_dwordx4 v240, v[180:183], s[90:91] offset:256
	v_mul_f32_e32 v60, v60, v148
	v_mul_f32_e32 v61, v61, v148
	v_pk_fma_f32 v[60:61], v[152:153], v[60:61], v[196:197]
	v_mul_f32_e32 v62, v62, v148
	v_mul_f32_e32 v63, v63, v148
	v_pk_fma_f32 v[62:63], v[154:155], v[62:63], v[198:199]
	v_cvt_pk_bf16_f32 v184, v60, v61
	v_cvt_pk_bf16_f32 v185, v62, v63
	v_mul_f32_e32 v56, v56, v148
	v_mul_f32_e32 v57, v57, v148
	v_pk_fma_f32 v[56:57], v[164:165], v[56:57], v[212:213]
	v_mul_f32_e32 v58, v58, v148
	v_mul_f32_e32 v59, v59, v148
	v_pk_fma_f32 v[58:59], v[166:167], v[58:59], v[214:215]
	v_cvt_pk_bf16_f32 v186, v56, v57
	v_cvt_pk_bf16_f32 v187, v58, v59
	v_mul_f32_e32 v52, v52, v148
	v_mul_f32_e32 v53, v53, v148
	v_pk_fma_f32 v[52:53], v[168:169], v[52:53], v[216:217]
	v_mul_f32_e32 v54, v54, v148
	v_mul_f32_e32 v55, v55, v148
	v_pk_fma_f32 v[54:55], v[170:171], v[54:55], v[218:219]
	v_cvt_pk_bf16_f32 v188, v52, v53
	v_cvt_pk_bf16_f32 v189, v54, v55
	v_mul_f32_e32 v48, v48, v148
	v_mul_f32_e32 v49, v49, v148
	v_pk_fma_f32 v[48:49], v[172:173], v[48:49], v[220:221]
	v_mul_f32_e32 v50, v50, v148
	v_mul_f32_e32 v51, v51, v148
	v_pk_fma_f32 v[50:51], v[174:175], v[50:51], v[222:223]
	v_cvt_pk_bf16_f32 v190, v48, v49
	v_cvt_pk_bf16_f32 v191, v50, v51
	v_add_u32_e32 v240, 0x40000, v247
	v_cndmask_b32_e64 v192, v186, v184, s[84:85]
	v_cndmask_b32_e64 v193, v187, v185, s[84:85]
	ds_bpermute_b32 v194, v241, v192
	ds_bpermute_b32 v195, v241, v193
	s_waitcnt lgkmcnt(0)
; __device__ __forceinline__ unsigned cvtpk_s(float lo, float hi) { f32x2_t v = {lo, hi}; bf16x2_t b = __builtin_convertvector(v, bf16x2_t); return __builtin_bit_cast(unsigned, b); }
; __device__ __forceinline__ u32x4 quad_swap(unsigned lo0, unsigned lo1, unsigned hi0, unsigned hi1, int fq, int& coloff) {
;     const bool odd = fq & 1;
;     const unsigned s0 = odd ? lo0 : hi0, s1 = odd ? lo1 : hi1;
;     const unsigned r0 = (unsigned)__shfl_xor((int)s0, 16), r1 = (unsigned)__shfl_xor((int)s1, 16);
;     coloff = odd ? 16 + 4 * (fq - 1) : 4 * fq;
;     u32x4 o; o.x = odd ? r0 : lo0; o.y = odd ? r1 : lo1; o.z = odd ? hi0 : r0; o.w = odd ? hi1 : r1; return o;
; __device__ __forceinline__ void modpass(const float* xs_main, const float* xs_ctx, const float* mod_l, const float* g, int i, bf16_t* H, int nrows, int gw, int NGW, int lane) {
;     ...
;         for (int j = 0; j < 2; ++j) {
;             const f32x4 o0 = v[j][0] * rstd * gm[j][0] + sh[j][0], o1 = v[j][1] * rstd * gm[j][1] + sh[j][1];
;             u32x4 w; w.x = cvtpk_s(o0[0], o0[1]); w.y = cvtpk_s(o0[2], o0[3]); w.z = cvtpk_s(o1[0], o1[1]); w.w = cvtpk_s(o1[2], o1[3]);
;             *(u32x4*)(H + (size_t)row * D + 8 * lane + 512 * j) = w;
	v_cndmask_b32_e64 v176, v184, v194, s[84:85]
	v_cndmask_b32_e64 v177, v185, v195, s[84:85]
	v_cndmask_b32_e64 v178, v194, v186, s[84:85]
	v_cndmask_b32_e64 v179, v195, v187, s[84:85]
	global_store_dwordx4 v240, v[176:179], s[90:91]
	v_cndmask_b32_e64 v192, v190, v188, s[84:85]
	v_cndmask_b32_e64 v193, v191, v189, s[84:85]
	ds_bpermute_b32 v194, v241, v192
	ds_bpermute_b32 v195, v241, v193
	s_waitcnt lgkmcnt(0)
	v_cndmask_b32_e64 v180, v188, v194, s[84:85]
	v_cndmask_b32_e64 v181, v189, v195, s[84:85]
	v_cndmask_b32_e64 v182, v194, v190, s[84:85]
	v_cndmask_b32_e64 v183, v195, v191, s[84:85]
	global_store_dwordx4 v240, v[180:183], s[90:91] offset:256
	v_mul_f32_e32 v44, v44, v149
	v_mul_f32_e32 v45, v45, v149
	v_pk_fma_f32 v[44:45], v[152:153], v[44:45], v[196:197]
	v_mul_f32_e32 v46, v46, v149
	v_mul_f32_e32 v47, v47, v149
	v_pk_fma_f32 v[46:47], v[154:155], v[46:47], v[198:199]
	v_cvt_pk_bf16_f32 v184, v44, v45
	v_cvt_pk_bf16_f32 v185, v46, v47
	v_mul_f32_e32 v40, v40, v149
	v_mul_f32_e32 v41, v41, v149
	v_pk_fma_f32 v[40:41], v[164:165], v[40:41], v[212:213]
	v_mul_f32_e32 v42, v42, v149
	v_mul_f32_e32 v43, v43, v149
	v_pk_fma_f32 v[42:43], v[166:167], v[42:43], v[214:215]
	v_cvt_pk_bf16_f32 v186, v40, v41
	v_cvt_pk_bf16_f32 v187, v42, v43
	v_mul_f32_e32 v36, v36, v149
	v_mul_f32_e32 v37, v37, v149
	v_pk_fma_f32 v[36:37], v[168:169], v[36:37], v[216:217]
	v_mul_f32_e32 v38, v38, v149
	v_mul_f32_e32 v39, v39, v149
	v_pk_fma_f32 v[38:39], v[170:171], v[38:39], v[218:219]
	v_cvt_pk_bf16_f32 v188, v36, v37
	v_cvt_pk_bf16_f32 v189, v38, v39
	v_mul_f32_e32 v32, v32, v149
	v_mul_f32_e32 v33, v33, v149
	v_pk_fma_f32 v[32:33], v[172:173], v[32:33], v[220:221]
	v_mul_f32_e32 v34, v34, v149
	v_mul_f32_e32 v35, v35, v149
	v_pk_fma_f32 v[34:35], v[174:175], v[34:35], v[222:223]
	v_cvt_pk_bf16_f32 v190, v32, v33
	v_cvt_pk_bf16_f32 v191, v34, v35
	v_add_u32_e32 v240, 0x48000, v247
	v_cndmask_b32_e64 v192, v186, v184, s[84:85]
	v_cndmask_b32_e64 v193, v187, v185, s[84:85]
	ds_bpermute_b32 v194, v241, v192
	ds_bpermute_b32 v195, v241, v193
	s_waitcnt lgkmcnt(0)
	v_cndmask_b32_e64 v176, v184, v194, s[84:85]
	v_cndmask_b32_e64 v177, v185, v195, s[84:85]
	v_cndmask_b32_e64 v178, v194, v186, s[84:85]
	v_cndmask_b32_e64 v179, v195, v187, s[84:85]
	global_store_dwordx4 v240, v[176:179], s[90:91]
	v_cndmask_b32_e64 v192, v190, v188, s[84:85]
	v_cndmask_b32_e64 v193, v191, v189, s[84:85]
	ds_bpermute_b32 v194, v241, v192
	ds_bpermute_b32 v195, v241, v193
	s_waitcnt lgkmcnt(0)
	v_cndmask_b32_e64 v180, v188, v194, s[84:85]
	v_cndmask_b32_e64 v181, v189, v195, s[84:85]
	v_cndmask_b32_e64 v182, v194, v190, s[84:85]
	v_cndmask_b32_e64 v183, v195, v191, s[84:85]
	global_store_dwordx4 v240, v[180:183], s[90:91] offset:256
	v_mul_f32_e32 v28, v28, v150
	v_mul_f32_e32 v29, v29, v150
	v_pk_fma_f32 v[28:29], v[152:153], v[28:29], v[196:197]
	v_mul_f32_e32 v30, v30, v150
	v_mul_f32_e32 v31, v31, v150
	v_pk_fma_f32 v[30:31], v[154:155], v[30:31], v[198:199]
	v_cvt_pk_bf16_f32 v184, v28, v29
	v_cvt_pk_bf16_f32 v185, v30, v31
	v_mul_f32_e32 v24, v24, v150
	v_mul_f32_e32 v25, v25, v150
	v_pk_fma_f32 v[24:25], v[164:165], v[24:25], v[212:213]
	v_mul_f32_e32 v26, v26, v150
	v_mul_f32_e32 v27, v27, v150
	v_pk_fma_f32 v[26:27], v[166:167], v[26:27], v[214:215]
	v_cvt_pk_bf16_f32 v186, v24, v25
	v_cvt_pk_bf16_f32 v187, v26, v27
	v_mul_f32_e32 v20, v20, v150
	v_mul_f32_e32 v21, v21, v150
	v_pk_fma_f32 v[20:21], v[168:169], v[20:21], v[216:217]
	v_mul_f32_e32 v22, v22, v150
	v_mul_f32_e32 v23, v23, v150
	v_pk_fma_f32 v[22:23], v[170:171], v[22:23], v[218:219]
	v_cvt_pk_bf16_f32 v188, v20, v21
	v_cvt_pk_bf16_f32 v189, v22, v23
	v_mul_f32_e32 v16, v16, v150
	v_mul_f32_e32 v17, v17, v150
	v_pk_fma_f32 v[16:17], v[172:173], v[16:17], v[220:221]
	v_mul_f32_e32 v18, v18, v150
	v_mul_f32_e32 v19, v19, v150
	v_pk_fma_f32 v[18:19], v[174:175], v[18:19], v[222:223]
	v_cvt_pk_bf16_f32 v190, v16, v17
	v_cvt_pk_bf16_f32 v191, v18, v19
	v_add_u32_e32 v240, 0x50000, v247
	v_cndmask_b32_e64 v192, v186, v184, s[84:85]
	v_cndmask_b32_e64 v193, v187, v185, s[84:85]
	ds_bpermute_b32 v194, v241, v192
	ds_bpermute_b32 v195, v241, v193
	s_waitcnt lgkmcnt(0)
	v_cndmask_b32_e64 v176, v184, v194, s[84:85]
	v_cndmask_b32_e64 v177, v185, v195, s[84:85]
	v_cndmask_b32_e64 v178, v194, v186, s[84:85]
	v_cndmask_b32_e64 v179, v195, v187, s[84:85]
	global_store_dwordx4 v240, v[176:179], s[90:91]
	v_cndmask_b32_e64 v192, v190, v188, s[84:85]
	v_cndmask_b32_e64 v193, v191, v189, s[84:85]
	ds_bpermute_b32 v194, v241, v192
	ds_bpermute_b32 v195, v241, v193
	s_waitcnt lgkmcnt(0)
	v_cndmask_b32_e64 v180, v188, v194, s[84:85]
	v_cndmask_b32_e64 v181, v189, v195, s[84:85]
	v_cndmask_b32_e64 v182, v194, v190, s[84:85]
	v_cndmask_b32_e64 v183, v195, v191, s[84:85]
	global_store_dwordx4 v240, v[180:183], s[90:91] offset:256
	v_mul_f32_e32 v12, v12, v151
	v_mul_f32_e32 v13, v13, v151
	v_pk_fma_f32 v[12:13], v[152:153], v[12:13], v[196:197]
	v_mul_f32_e32 v14, v14, v151
	v_mul_f32_e32 v15, v15, v151
	v_pk_fma_f32 v[14:15], v[154:155], v[14:15], v[198:199]
	v_cvt_pk_bf16_f32 v184, v12, v13
	v_cvt_pk_bf16_f32 v185, v14, v15
	v_mul_f32_e32 v8, v8, v151
	v_mul_f32_e32 v9, v9, v151
	v_pk_fma_f32 v[8:9], v[164:165], v[8:9], v[212:213]
	v_mul_f32_e32 v10, v10, v151
	v_mul_f32_e32 v11, v11, v151
	v_pk_fma_f32 v[10:11], v[166:167], v[10:11], v[214:215]
	v_cvt_pk_bf16_f32 v186, v8, v9
	v_cvt_pk_bf16_f32 v187, v10, v11
	v_mul_f32_e32 v4, v4, v151
	v_mul_f32_e32 v5, v5, v151
	v_pk_fma_f32 v[4:5], v[168:169], v[4:5], v[216:217]
	v_mul_f32_e32 v6, v6, v151
	v_mul_f32_e32 v7, v7, v151
	v_pk_fma_f32 v[6:7], v[170:171], v[6:7], v[218:219]
	v_cvt_pk_bf16_f32 v188, v4, v5
	v_cvt_pk_bf16_f32 v189, v6, v7
	v_mul_f32_e32 v0, v0, v151
	v_mul_f32_e32 v1, v1, v151
	v_pk_fma_f32 v[0:1], v[172:173], v[0:1], v[220:221]
	v_mul_f32_e32 v2, v2, v151
	v_mul_f32_e32 v3, v3, v151
	v_pk_fma_f32 v[2:3], v[174:175], v[2:3], v[222:223]
	v_cvt_pk_bf16_f32 v190, v0, v1
	v_cvt_pk_bf16_f32 v191, v2, v3
	v_add_u32_e32 v240, 0x58000, v247
	v_cndmask_b32_e64 v192, v186, v184, s[84:85]
	v_cndmask_b32_e64 v193, v187, v185, s[84:85]
	ds_bpermute_b32 v194, v241, v192
	ds_bpermute_b32 v195, v241, v193
	s_waitcnt lgkmcnt(0)
	v_cndmask_b32_e64 v176, v184, v194, s[84:85]
	v_cndmask_b32_e64 v177, v185, v195, s[84:85]
	v_cndmask_b32_e64 v178, v194, v186, s[84:85]
	v_cndmask_b32_e64 v179, v195, v187, s[84:85]
	global_store_dwordx4 v240, v[176:179], s[90:91]
	v_cndmask_b32_e64 v192, v190, v188, s[84:85]
	v_cndmask_b32_e64 v193, v191, v189, s[84:85]
	ds_bpermute_b32 v194, v241, v192
	ds_bpermute_b32 v195, v241, v193
	s_waitcnt lgkmcnt(0)
	v_cndmask_b32_e64 v180, v188, v194, s[84:85]
	v_cndmask_b32_e64 v181, v189, v195, s[84:85]
	v_cndmask_b32_e64 v182, v194, v190, s[84:85]
	v_cndmask_b32_e64 v183, v195, v191, s[84:85]
	global_store_dwordx4 v240, v[180:183], s[90:91] offset:256
	s_and_b64 vcc, exec, s[12:13]
	s_mov_b64 s[12:13], -1
	s_cbranch_vccnz .LBB0_1331
	s_andn2_b64 vcc, exec, s[18:19]
	s_cbranch_vccnz .LBB0_1330
	s_barrier
	s_branch .LBB0_1330

; __device__ __forceinline__ void modpass(const float* xs_main, const float* xs_ctx, const float* mod_l, const float* g, int i, bf16_t* H, int nrows, int gw, int NGW, int lane) {
;     f32x4 gm[2][2], sh[2][2], v[2][2], vn[2][2]; int cur = -1;
;     int row = gw;
;     if (row < nrows) { const float* xr = row < MX ? xs_main + (size_t)row * D : xs_ctx + (size_t)(row - MX) * D;
; #pragma unroll
;         for (int j = 0; j < 2; ++j) { v[j][0] = *(const f32x4*)(xr + 8 * lane + 512 * j); v[j][1] = *(const f32x4*)(xr + 8 * lane + 512 * j + 4); } }
;     for (; row < nrows; row += NGW) {
;         const int nrow = row + NGW;
;         if (nrow < nrows) { const float* xr = nrow < MX ? xs_main + (size_t)nrow * D : xs_ctx + (size_t)(nrow - MX) * D;
; #pragma unroll
;             for (int j = 0; j < 2; ++j) { vn[j][0] = *(const f32x4*)(xr + 8 * lane + 512 * j); vn[j][1] = *(const f32x4*)(xr + 8 * lane + 512 * j + 4); } }
.LBB0_1407:
	s_or_b64 exec, exec, s[12:13]
	s_mov_b64 s[14:15], s[0:1]
	v_mov_b32_e32 v2, v206
	s_waitcnt lgkmcnt(0)
	s_barrier
	s_nop 0
	v_readfirstlane_b32 s6, v2
	s_ashr_i32 s6, s6, 6
	s_add_i32 s12, s6, s33
	s_add_i32 s12, s12, 0x8000
	s_cmp_gt_i32 s12, 0x81ff
	s_cbranch_scc1 .LBB0_1414
	s_load_dwordx4 s[16:19], s[14:15], 0xb0
	s_load_dwordx2 s[20:21], s[14:15], 0x30
	v_lshlrev_b32_e32 v0, 3, v2
	v_and_b32_e32 v64, 0x1f8, v0
	v_lshlrev_b32_e32 v0, 2, v64
	s_waitcnt lgkmcnt(0)
	s_add_u32 s6, s18, 0x6300000
	s_addc_u32 s7, s19, 0
	s_add_u32 s8, s18, 0x1b000
	s_addc_u32 s9, s19, 0
	s_add_u32 s14, s20, 0x3000
	s_addc_u32 s15, s21, 0
	s_add_i32 s20, s12, 0xffff8000
	s_ashr_i32 s13, s12, 31
	s_cmp_lt_i32 s12, 0x8000
	s_cselect_b32 s21, s13, 0
	s_cselect_b32 s20, s12, s20
	s_cselect_b32 s22, s17, s7
	s_cselect_b32 s23, s16, s6
	s_lshl_b64 s[20:21], s[20:21], 12
	s_add_u32 s20, s23, s20
	s_addc_u32 s21, s22, s21
	global_load_dwordx4 v[12:15], v0, s[20:21] offset:16
	global_load_dwordx4 v[16:19], v0, s[20:21]
	global_load_dwordx4 v[4:7], v0, s[20:21] offset:2064
	global_load_dwordx4 v[8:11], v0, s[20:21] offset:2048
	v_xor_b32_e32 v3, 1, v202
	v_cmp_lt_i32_e32 vcc, v3, v203
	v_mov_b32_e32 v1, 0
	v_or_b32_e32 v20, 0x200, v64
	v_cndmask_b32_e32 v3, v202, v3, vcc
	v_lshlrev_b32_e32 v65, 2, v3
	v_xor_b32_e32 v3, 2, v202
	v_cmp_lt_i32_e32 vcc, v3, v203
	v_lshl_add_u64 v[66:67], s[14:15], 0, v[0:1]
	v_lshlrev_b32_e32 v0, 2, v20
	v_cndmask_b32_e32 v3, v202, v3, vcc
	v_lshlrev_b32_e32 v72, 2, v3
	v_xor_b32_e32 v3, 4, v202
	v_cmp_lt_i32_e32 vcc, v3, v203
	v_lshl_add_u64 v[68:69], s[14:15], 0, v[0:1]
	s_lshl_b64 s[14:15], s[12:13], 11
	v_cndmask_b32_e32 v3, v202, v3, vcc
	v_lshlrev_b32_e32 v73, 2, v3
	v_xor_b32_e32 v3, 8, v202
	v_cmp_lt_i32_e32 vcc, v3, v203
	v_and_b32_e32 v0, 63, v2
	s_add_u32 s14, s18, s14
	v_cndmask_b32_e32 v3, v202, v3, vcc
	v_cmp_lt_i32_e32 vcc, v204, v203
	v_lshlrev_b32_e32 v74, 2, v3
	v_lshlrev_b32_e32 v0, 4, v0
	v_cndmask_b32_e32 v3, v202, v204, vcc
	v_lshlrev_b32_e32 v75, 2, v3
	v_xor_b32_e32 v3, 32, v202
	v_cmp_lt_i32_e32 vcc, v3, v203
	s_addc_u32 s15, s19, s15
	s_ashr_i32 s29, s28, 31
	v_cndmask_b32_e32 v3, v202, v3, vcc
	v_lshlrev_b32_e32 v76, 2, v3
	v_lshl_add_u64 v[2:3], s[14:15], 0, v[0:1]
	s_mov_b64 s[14:15], 0x6500400
	s_add_i32 s20, s12, s28
	s_mov_b32 s23, -1
	v_lshl_add_u64 v[70:71], v[2:3], 0, s[14:15]
	s_lshl_b64 s[14:15], s[28:29], 11
	s_ashr_i32 s21, s20, 31
	v_lshlrev_b32_e32 v77, 2, v20
	v_mov_b32_e32 v78, 0x358637bd
	s_mov_b32 s22, 0xf800000
	v_mov_b32_e32 v79, 0x260
	v_mov_b32_e32 v0, v1
	v_mov_b32_e32 v2, v1
	v_mov_b32_e32 v3, v1
	v_mov_b32_e32 v20, v1
	v_mov_b32_e32 v21, v1
	v_mov_b32_e32 v22, v1
	v_mov_b32_e32 v23, v1
	v_mov_b32_e32 v28, v1
	v_mov_b32_e32 v29, v1
	v_mov_b32_e32 v30, v1
	v_mov_b32_e32 v31, v1
	v_mov_b32_e32 v24, v1
	v_mov_b32_e32 v25, v1
	v_mov_b32_e32 v26, v1
	v_mov_b32_e32 v27, v1
	s_branch .LBB0_1410

;     __device__ __forceinline__ void operator()(const f32x4 (&acc)[2][2][4][2], const Unit& u, int wr, int wc, int fr, int fq) const {
;     ...
;         const int col0 = u.pn * BM + wc * 32 + 4 * fq;
;         f32x4 gv[2][2];
; #pragma unroll
;         for (int bj = 0; bj < 2; ++bj)
; #pragma unroll
;             for (int n = 0; n < 2; ++n) gv[bj][n] = *(const f32x4*)(gate + col0 + bj * HALF + n * 16) * coef;
; #pragma unroll
;         for (int ai = 0; ai < 2; ++ai)
; #pragma unroll
;             for (int m = 0; m < 4; ++m) {
;                 const int row = u.pm * BM + ai * HALF + wr * 64 + m * 16 + fr;
;                 const float* s = row < MX_ ? src_main + (size_t)row * D_ : src_ctx + (size_t)(row - MX_) * D_;
;                 float* d = row < MX_ ? dst_main + (size_t)row * D_ : dst_ctx + (size_t)(row - MX_) * D_;
; #pragma unroll
;                 for (int bj = 0; bj < 2; ++bj)
; #pragma unroll
;                     for (int n = 0; n < 2; ++n) { const int off = col0 + bj * HALF + n * 16; const f32x4 xo = *(const f32x4*)(s + off); *(f32x4*)(d + off) = xo + gv[bj][n] * acc[ai][bj][m][n]; }
.LBB0_1566:
	s_cmpk_lt_i32 s6, 0x80
	s_cselect_b32 s8, s62, 0x4800
	s_cmp_gt_i32 s6, 63
	s_cselect_b32 s8, s8, 0
	s_lshl_b32 s8, s8, 2
	s_add_u32 s8, s54, s8
	s_addc_u32 s9, s55, 0
	s_load_dwordx2 s[92:93], s[0:1], 0x30
	s_load_dwordx2 s[76:77], s[0:1], 0xb8
	v_lshl_add_u32 v156, s6, 8, v158
	v_lshl_or_b32 v157, s7, 8, v160
	v_lshlrev_b32_e32 v201, 2, v157
	v_lshl_add_u32 v224, v156, 12, v201
	global_load_dwordx4 v[196:199], v201, s[8:9]
	global_load_dwordx4 v[212:215], v201, s[8:9] offset:64
	global_load_dwordx4 v[216:219], v201, s[8:9] offset:512
	global_load_dwordx4 v[220:223], v201, s[8:9] offset:576
	v_add_u32_e32 v225, 0x10000, v224
	v_add_u32_e32 v226, 0x20000, v224
	v_add_u32_e32 v227, 0x30000, v224
	v_add_u32_e32 v228, 0x80000, v224
	v_add_u32_e32 v229, 0x90000, v224
	v_add_u32_e32 v230, 0xa0000, v224
	v_add_u32_e32 v231, 0xb0000, v224
	global_load_dwordx4 v[140:143], v224, s[14:15]
	global_load_dwordx4 v[144:147], v224, s[14:15] offset:64
	global_load_dwordx4 v[148:151], v224, s[14:15] offset:512
	global_load_dwordx4 v[152:155], v224, s[14:15] offset:576
	global_load_dwordx4 v[164:167], v225, s[14:15]
	global_load_dwordx4 v[168:171], v225, s[14:15] offset:64
	global_load_dwordx4 v[172:175], v225, s[14:15] offset:512
	global_load_dwordx4 v[176:179], v225, s[14:15] offset:576
	global_load_dwordx4 v[180:183], v226, s[14:15]
	global_load_dwordx4 v[184:187], v226, s[14:15] offset:64
	global_load_dwordx4 v[188:191], v226, s[14:15] offset:512
	global_load_dwordx4 v[192:195], v226, s[14:15] offset:576
	s_waitcnt vmcnt(12)
	v_pk_mul_f32 v[196:197], v[196:197], 0.5 op_sel_hi:[1,0]
	v_pk_mul_f32 v[198:199], v[198:199], 0.5 op_sel_hi:[1,0]
	v_pk_mul_f32 v[212:213], v[212:213], 0.5 op_sel_hi:[1,0]
	v_pk_mul_f32 v[214:215], v[214:215], 0.5 op_sel_hi:[1,0]
	v_pk_mul_f32 v[216:217], v[216:217], 0.5 op_sel_hi:[1,0]
	v_pk_mul_f32 v[218:219], v[218:219], 0.5 op_sel_hi:[1,0]
	v_pk_mul_f32 v[220:221], v[220:221], 0.5 op_sel_hi:[1,0]
	v_pk_mul_f32 v[222:223], v[222:223], 0.5 op_sel_hi:[1,0]
	s_waitcnt vmcnt(11)
	v_pk_fma_f32 v[124:125], v[124:125], v[196:197], v[140:141]
	v_pk_fma_f32 v[126:127], v[126:127], v[198:199], v[142:143]
	v_mul_f32_e32 v232, v124, v124
	v_fmac_f32_e32 v232, v125, v125
	v_fmac_f32_e32 v232, v126, v126
	v_fmac_f32_e32 v232, v127, v127
	s_waitcnt vmcnt(10)
	v_pk_fma_f32 v[120:121], v[120:121], v[212:213], v[144:145]
	v_pk_fma_f32 v[122:123], v[122:123], v[214:215], v[146:147]
	v_fmac_f32_e32 v232, v120, v120
	v_fmac_f32_e32 v232, v121, v121
	v_fmac_f32_e32 v232, v122, v122
	v_fmac_f32_e32 v232, v123, v123
	s_waitcnt vmcnt(9)
	v_pk_fma_f32 v[116:117], v[116:117], v[216:217], v[148:149]
	v_pk_fma_f32 v[118:119], v[118:119], v[218:219], v[150:151]
	v_fmac_f32_e32 v232, v116, v116
	v_fmac_f32_e32 v232, v117, v117
	v_fmac_f32_e32 v232, v118, v118
	v_fmac_f32_e32 v232, v119, v119
	s_waitcnt vmcnt(8)
	v_pk_fma_f32 v[112:113], v[112:113], v[220:221], v[152:153]
	v_pk_fma_f32 v[114:115], v[114:115], v[222:223], v[154:155]
	v_fmac_f32_e32 v232, v112, v112
	v_fmac_f32_e32 v232, v113, v113
	v_fmac_f32_e32 v232, v114, v114
	v_fmac_f32_e32 v232, v115, v115
	global_store_dwordx4 v224, v[124:127], s[14:15]
	global_store_dwordx4 v224, v[120:123], s[14:15] offset:64
	global_store_dwordx4 v224, v[116:119], s[14:15] offset:512
	global_store_dwordx4 v224, v[112:115], s[14:15] offset:576
	global_load_dwordx4 v[140:143], v227, s[14:15]
	global_load_dwordx4 v[144:147], v227, s[14:15] offset:64
	global_load_dwordx4 v[148:151], v227, s[14:15] offset:512
	global_load_dwordx4 v[152:155], v227, s[14:15] offset:576
	s_waitcnt vmcnt(15)
	v_pk_fma_f32 v[108:109], v[108:109], v[196:197], v[164:165]
	v_pk_fma_f32 v[110:111], v[110:111], v[198:199], v[166:167]
	v_mul_f32_e32 v233, v108, v108
	v_fmac_f32_e32 v233, v109, v109
	v_fmac_f32_e32 v233, v110, v110
	v_fmac_f32_e32 v233, v111, v111
	s_waitcnt vmcnt(14)
	v_pk_fma_f32 v[104:105], v[104:105], v[212:213], v[168:169]
	v_pk_fma_f32 v[106:107], v[106:107], v[214:215], v[170:171]
	v_fmac_f32_e32 v233, v104, v104
	v_fmac_f32_e32 v233, v105, v105
	v_fmac_f32_e32 v233, v106, v106
	v_fmac_f32_e32 v233, v107, v107
	s_waitcnt vmcnt(13)
	v_pk_fma_f32 v[100:101], v[100:101], v[216:217], v[172:173]
	v_pk_fma_f32 v[102:103], v[102:103], v[218:219], v[174:175]
	v_fmac_f32_e32 v233, v100, v100
	v_fmac_f32_e32 v233, v101, v101
	v_fmac_f32_e32 v233, v102, v102
	v_fmac_f32_e32 v233, v103, v103
	s_waitcnt vmcnt(12)
	v_pk_fma_f32 v[96:97], v[96:97], v[220:221], v[176:177]
	v_pk_fma_f32 v[98:99], v[98:99], v[222:223], v[178:179]
	v_fmac_f32_e32 v233, v96, v96
	v_fmac_f32_e32 v233, v97, v97
	v_fmac_f32_e32 v233, v98, v98
	v_fmac_f32_e32 v233, v99, v99
	global_store_dwordx4 v225, v[108:111], s[14:15]
	global_store_dwordx4 v225, v[104:107], s[14:15] offset:64
	global_store_dwordx4 v225, v[100:103], s[14:15] offset:512
	global_store_dwordx4 v225, v[96:99], s[14:15] offset:576
	global_load_dwordx4 v[164:167], v228, s[14:15]
	global_load_dwordx4 v[168:171], v228, s[14:15] offset:64
	global_load_dwordx4 v[172:175], v228, s[14:15] offset:512
	global_load_dwordx4 v[176:179], v228, s[14:15] offset:576
	s_waitcnt vmcnt(19)
	v_pk_fma_f32 v[92:93], v[92:93], v[196:197], v[180:181]
	v_pk_fma_f32 v[94:95], v[94:95], v[198:199], v[182:183]
	v_mul_f32_e32 v234, v92, v92
	v_fmac_f32_e32 v234, v93, v93
	v_fmac_f32_e32 v234, v94, v94
	v_fmac_f32_e32 v234, v95, v95
	s_waitcnt vmcnt(18)
	v_pk_fma_f32 v[88:89], v[88:89], v[212:213], v[184:185]
	v_pk_fma_f32 v[90:91], v[90:91], v[214:215], v[186:187]
	v_fmac_f32_e32 v234, v88, v88
	v_fmac_f32_e32 v234, v89, v89
	v_fmac_f32_e32 v234, v90, v90
	v_fmac_f32_e32 v234, v91, v91
	s_waitcnt vmcnt(17)
;     __device__ __forceinline__ void operator()(const f32x4 (&acc)[2][2][4][2], const Unit& u, int wr, int wc, int fr, int fq) const {
;     ...
;         for (int ai = 0; ai < 2; ++ai)
; #pragma unroll
;             for (int m = 0; m < 4; ++m) {
;                 const int row = u.pm * BM + ai * HALF + wr * 64 + m * 16 + fr;
;                 const float* s = row < MX_ ? src_main + (size_t)row * D_ : src_ctx + (size_t)(row - MX_) * D_;
;                 float* d = row < MX_ ? dst_main + (size_t)row * D_ : dst_ctx + (size_t)(row - MX_) * D_;
; #pragma unroll
;                 for (int bj = 0; bj < 2; ++bj)
; #pragma unroll
;                     for (int n = 0; n < 2; ++n) { const int off = col0 + bj * HALF + n * 16; const f32x4 xo = *(const f32x4*)(s + off); *(f32x4*)(d + off) = xo + gv[bj][n] * acc[ai][bj][m][n]; }
	v_pk_fma_f32 v[84:85], v[84:85], v[216:217], v[188:189]
	v_pk_fma_f32 v[86:87], v[86:87], v[218:219], v[190:191]
	v_fmac_f32_e32 v234, v84, v84
	v_fmac_f32_e32 v234, v85, v85
	v_fmac_f32_e32 v234, v86, v86
	v_fmac_f32_e32 v234, v87, v87
	s_waitcnt vmcnt(16)
	v_pk_fma_f32 v[80:81], v[80:81], v[220:221], v[192:193]
	v_pk_fma_f32 v[82:83], v[82:83], v[222:223], v[194:195]
	v_fmac_f32_e32 v234, v80, v80
	v_fmac_f32_e32 v234, v81, v81
	v_fmac_f32_e32 v234, v82, v82
	v_fmac_f32_e32 v234, v83, v83
	global_store_dwordx4 v226, v[92:95], s[14:15]
	global_store_dwordx4 v226, v[88:91], s[14:15] offset:64
	global_store_dwordx4 v226, v[84:87], s[14:15] offset:512
	global_store_dwordx4 v226, v[80:83], s[14:15] offset:576
	global_load_dwordx4 v[180:183], v229, s[14:15]
	global_load_dwordx4 v[184:187], v229, s[14:15] offset:64
	global_load_dwordx4 v[188:191], v229, s[14:15] offset:512
	global_load_dwordx4 v[192:195], v229, s[14:15] offset:576
	s_waitcnt vmcnt(19)
	v_pk_fma_f32 v[76:77], v[76:77], v[196:197], v[140:141]
	v_pk_fma_f32 v[78:79], v[78:79], v[198:199], v[142:143]
	v_mul_f32_e32 v235, v76, v76
	v_fmac_f32_e32 v235, v77, v77
	v_fmac_f32_e32 v235, v78, v78
	v_fmac_f32_e32 v235, v79, v79
	s_waitcnt vmcnt(18)
	v_pk_fma_f32 v[72:73], v[72:73], v[212:213], v[144:145]
	v_pk_fma_f32 v[74:75], v[74:75], v[214:215], v[146:147]
	v_fmac_f32_e32 v235, v72, v72
	v_fmac_f32_e32 v235, v73, v73
	v_fmac_f32_e32 v235, v74, v74
	v_fmac_f32_e32 v235, v75, v75
	s_waitcnt vmcnt(17)
	v_pk_fma_f32 v[68:69], v[68:69], v[216:217], v[148:149]
	v_pk_fma_f32 v[70:71], v[70:71], v[218:219], v[150:151]
	v_fmac_f32_e32 v235, v68, v68
	v_fmac_f32_e32 v235, v69, v69
	v_fmac_f32_e32 v235, v70, v70
	v_fmac_f32_e32 v235, v71, v71
	s_waitcnt vmcnt(16)
	v_pk_fma_f32 v[64:65], v[64:65], v[220:221], v[152:153]
	v_pk_fma_f32 v[66:67], v[66:67], v[222:223], v[154:155]
	v_fmac_f32_e32 v235, v64, v64
	v_fmac_f32_e32 v235, v65, v65
	v_fmac_f32_e32 v235, v66, v66
	v_fmac_f32_e32 v235, v67, v67
	global_store_dwordx4 v227, v[76:79], s[14:15]
	global_store_dwordx4 v227, v[72:75], s[14:15] offset:64
	global_store_dwordx4 v227, v[68:71], s[14:15] offset:512
	global_store_dwordx4 v227, v[64:67], s[14:15] offset:576
	global_load_dwordx4 v[140:143], v230, s[14:15]
	global_load_dwordx4 v[144:147], v230, s[14:15] offset:64
	global_load_dwordx4 v[148:151], v230, s[14:15] offset:512
	global_load_dwordx4 v[152:155], v230, s[14:15] offset:576
	s_waitcnt vmcnt(19)
	v_pk_fma_f32 v[60:61], v[60:61], v[196:197], v[164:165]
	v_pk_fma_f32 v[62:63], v[62:63], v[198:199], v[166:167]
	v_mul_f32_e32 v236, v60, v60
	v_fmac_f32_e32 v236, v61, v61
	v_fmac_f32_e32 v236, v62, v62
	v_fmac_f32_e32 v236, v63, v63
	s_waitcnt vmcnt(18)
	v_pk_fma_f32 v[56:57], v[56:57], v[212:213], v[168:169]
	v_pk_fma_f32 v[58:59], v[58:59], v[214:215], v[170:171]
	v_fmac_f32_e32 v236, v56, v56
	v_fmac_f32_e32 v236, v57, v57
	v_fmac_f32_e32 v236, v58, v58
	v_fmac_f32_e32 v236, v59, v59
	s_waitcnt vmcnt(17)
	v_pk_fma_f32 v[52:53], v[52:53], v[216:217], v[172:173]
	v_pk_fma_f32 v[54:55], v[54:55], v[218:219], v[174:175]
	v_fmac_f32_e32 v236, v52, v52
	v_fmac_f32_e32 v236, v53, v53
	v_fmac_f32_e32 v236, v54, v54
	v_fmac_f32_e32 v236, v55, v55
	s_waitcnt vmcnt(16)
	v_pk_fma_f32 v[48:49], v[48:49], v[220:221], v[176:177]
	v_pk_fma_f32 v[50:51], v[50:51], v[222:223], v[178:179]
	v_fmac_f32_e32 v236, v48, v48
	v_fmac_f32_e32 v236, v49, v49
	v_fmac_f32_e32 v236, v50, v50
	v_fmac_f32_e32 v236, v51, v51
	global_store_dwordx4 v228, v[60:63], s[14:15]
	global_store_dwordx4 v228, v[56:59], s[14:15] offset:64
	global_store_dwordx4 v228, v[52:55], s[14:15] offset:512
	global_store_dwordx4 v228, v[48:51], s[14:15] offset:576
	global_load_dwordx4 v[164:167], v231, s[14:15]
	global_load_dwordx4 v[168:171], v231, s[14:15] offset:64
	global_load_dwordx4 v[172:175], v231, s[14:15] offset:512
	global_load_dwordx4 v[176:179], v231, s[14:15] offset:576
	s_waitcnt vmcnt(19)
	v_pk_fma_f32 v[44:45], v[44:45], v[196:197], v[180:181]
	v_pk_fma_f32 v[46:47], v[46:47], v[198:199], v[182:183]
	v_mul_f32_e32 v237, v44, v44
	v_fmac_f32_e32 v237, v45, v45
	v_fmac_f32_e32 v237, v46, v46
	v_fmac_f32_e32 v237, v47, v47
	s_waitcnt vmcnt(18)
	v_pk_fma_f32 v[40:41], v[40:41], v[212:213], v[184:185]
	v_pk_fma_f32 v[42:43], v[42:43], v[214:215], v[186:187]
	v_fmac_f32_e32 v237, v40, v40
	v_fmac_f32_e32 v237, v41, v41
	v_fmac_f32_e32 v237, v42, v42
	v_fmac_f32_e32 v237, v43, v43
	s_waitcnt vmcnt(17)
	v_pk_fma_f32 v[36:37], v[36:37], v[216:217], v[188:189]
	v_pk_fma_f32 v[38:39], v[38:39], v[218:219], v[190:191]
	v_fmac_f32_e32 v237, v36, v36
	v_fmac_f32_e32 v237, v37, v37
	v_fmac_f32_e32 v237, v38, v38
	v_fmac_f32_e32 v237, v39, v39
	s_waitcnt vmcnt(16)
	v_pk_fma_f32 v[32:33], v[32:33], v[220:221], v[192:193]
	v_pk_fma_f32 v[34:35], v[34:35], v[222:223], v[194:195]
	v_fmac_f32_e32 v237, v32, v32
	v_fmac_f32_e32 v237, v33, v33
	v_fmac_f32_e32 v237, v34, v34
	v_fmac_f32_e32 v237, v35, v35
	global_store_dwordx4 v229, v[44:47], s[14:15]
	global_store_dwordx4 v229, v[40:43], s[14:15] offset:64
	global_store_dwordx4 v229, v[36:39], s[14:15] offset:512
	global_store_dwordx4 v229, v[32:35], s[14:15] offset:576
	s_waitcnt vmcnt(15)
;     __device__ __forceinline__ void operator()(const f32x4 (&acc)[2][2][4][2], const Unit& u, int wr, int wc, int fr, int fq) const {
;     ...
;         for (int ai = 0; ai < 2; ++ai)
; #pragma unroll
;             for (int m = 0; m < 4; ++m) {
;                 const int row = u.pm * BM + ai * HALF + wr * 64 + m * 16 + fr;
;                 const float* s = row < MX_ ? src_main + (size_t)row * D_ : src_ctx + (size_t)(row - MX_) * D_;
;                 float* d = row < MX_ ? dst_main + (size_t)row * D_ : dst_ctx + (size_t)(row - MX_) * D_;
; #pragma unroll
;                 for (int bj = 0; bj < 2; ++bj)
; #pragma unroll
;                     for (int n = 0; n < 2; ++n) { const int off = col0 + bj * HALF + n * 16; const f32x4 xo = *(const f32x4*)(s + off); *(f32x4*)(d + off) = xo + gv[bj][n] * acc[ai][bj][m][n]; }
;     __device__ __forceinline__ void operator()(const f32x4 (&acc)[2][2][4][2], const Unit& u, int wr, int wc, int fr, int fq) const {
;     ...
;                         s1 += __shfl_xor(s1, 16); s1 += __shfl_xor(s1, 32); s2 += __shfl_xor(s2, 16); s2 += __shfl_xor(s2, 32);
;                         if (fq == 0) { unsafeAtomicAdd(stats + 2 * row, s1); unsafeAtomicAdd(stats + 2 * row + 1, s2); }
	v_pk_fma_f32 v[28:29], v[28:29], v[196:197], v[140:141]
	v_pk_fma_f32 v[30:31], v[30:31], v[198:199], v[142:143]
	v_mul_f32_e32 v238, v28, v28
	v_fmac_f32_e32 v238, v29, v29
	v_fmac_f32_e32 v238, v30, v30
	v_fmac_f32_e32 v238, v31, v31
	s_waitcnt vmcnt(14)
	v_pk_fma_f32 v[24:25], v[24:25], v[212:213], v[144:145]
	v_pk_fma_f32 v[26:27], v[26:27], v[214:215], v[146:147]
	v_fmac_f32_e32 v238, v24, v24
	v_fmac_f32_e32 v238, v25, v25
	v_fmac_f32_e32 v238, v26, v26
	v_fmac_f32_e32 v238, v27, v27
	s_waitcnt vmcnt(13)
	v_pk_fma_f32 v[20:21], v[20:21], v[216:217], v[148:149]
	v_pk_fma_f32 v[22:23], v[22:23], v[218:219], v[150:151]
	v_fmac_f32_e32 v238, v20, v20
	v_fmac_f32_e32 v238, v21, v21
	v_fmac_f32_e32 v238, v22, v22
	v_fmac_f32_e32 v238, v23, v23
	s_waitcnt vmcnt(12)
	v_pk_fma_f32 v[16:17], v[16:17], v[220:221], v[152:153]
	v_pk_fma_f32 v[18:19], v[18:19], v[222:223], v[154:155]
	v_fmac_f32_e32 v238, v16, v16
	v_fmac_f32_e32 v238, v17, v17
	v_fmac_f32_e32 v238, v18, v18
	v_fmac_f32_e32 v238, v19, v19
	global_store_dwordx4 v230, v[28:31], s[14:15]
	global_store_dwordx4 v230, v[24:27], s[14:15] offset:64
	global_store_dwordx4 v230, v[20:23], s[14:15] offset:512
	global_store_dwordx4 v230, v[16:19], s[14:15] offset:576
	s_waitcnt vmcnt(11)
	v_pk_fma_f32 v[12:13], v[12:13], v[196:197], v[164:165]
	v_pk_fma_f32 v[14:15], v[14:15], v[198:199], v[166:167]
	v_mul_f32_e32 v239, v12, v12
	v_fmac_f32_e32 v239, v13, v13
	v_fmac_f32_e32 v239, v14, v14
	v_fmac_f32_e32 v239, v15, v15
	s_waitcnt vmcnt(10)
	v_pk_fma_f32 v[8:9], v[8:9], v[212:213], v[168:169]
	v_pk_fma_f32 v[10:11], v[10:11], v[214:215], v[170:171]
	v_fmac_f32_e32 v239, v8, v8
	v_fmac_f32_e32 v239, v9, v9
	v_fmac_f32_e32 v239, v10, v10
	v_fmac_f32_e32 v239, v11, v11
	s_waitcnt vmcnt(9)
	v_pk_fma_f32 v[4:5], v[4:5], v[216:217], v[172:173]
	v_pk_fma_f32 v[6:7], v[6:7], v[218:219], v[174:175]
	v_fmac_f32_e32 v239, v4, v4
	v_fmac_f32_e32 v239, v5, v5
	v_fmac_f32_e32 v239, v6, v6
	v_fmac_f32_e32 v239, v7, v7
	s_waitcnt vmcnt(8)
	v_pk_fma_f32 v[0:1], v[0:1], v[220:221], v[176:177]
	v_pk_fma_f32 v[2:3], v[2:3], v[222:223], v[178:179]
	v_fmac_f32_e32 v239, v0, v0
	v_fmac_f32_e32 v239, v1, v1
	v_fmac_f32_e32 v239, v2, v2
	v_fmac_f32_e32 v239, v3, v3
	global_store_dwordx4 v231, v[12:15], s[14:15]
	global_store_dwordx4 v231, v[8:11], s[14:15] offset:64
	global_store_dwordx4 v231, v[4:7], s[14:15] offset:512
	global_store_dwordx4 v231, v[0:3], s[14:15] offset:576
	v_mbcnt_lo_u32_b32 v240, -1, 0
	v_mbcnt_hi_u32_b32 v240, -1, v240
	v_xor_b32_e32 v241, 16, v240
	v_xor_b32_e32 v242, 32, v240
	v_lshlrev_b32_e32 v241, 2, v241
	v_lshlrev_b32_e32 v242, 2, v242
	s_waitcnt lgkmcnt(0)
	ds_bpermute_b32 v140, v241, v232
	ds_bpermute_b32 v141, v241, v233
	ds_bpermute_b32 v142, v241, v234
	ds_bpermute_b32 v143, v241, v235
	ds_bpermute_b32 v144, v241, v236
	ds_bpermute_b32 v145, v241, v237
	ds_bpermute_b32 v146, v241, v238
	ds_bpermute_b32 v147, v241, v239
	s_waitcnt lgkmcnt(7)
	v_add_f32_e32 v232, v232, v140
	s_waitcnt lgkmcnt(6)
	v_add_f32_e32 v233, v233, v141
	s_waitcnt lgkmcnt(5)
	v_add_f32_e32 v234, v234, v142
	s_waitcnt lgkmcnt(4)
	v_add_f32_e32 v235, v235, v143
	s_waitcnt lgkmcnt(3)
	v_add_f32_e32 v236, v236, v144
	s_waitcnt lgkmcnt(2)
	v_add_f32_e32 v237, v237, v145
	s_waitcnt lgkmcnt(1)
	v_add_f32_e32 v238, v238, v146
	s_waitcnt lgkmcnt(0)
	v_add_f32_e32 v239, v239, v147
	ds_bpermute_b32 v140, v242, v232
	ds_bpermute_b32 v141, v242, v233
	ds_bpermute_b32 v142, v242, v234
	ds_bpermute_b32 v143, v242, v235
	ds_bpermute_b32 v144, v242, v236
	ds_bpermute_b32 v145, v242, v237
	ds_bpermute_b32 v146, v242, v238
	ds_bpermute_b32 v147, v242, v239
	s_waitcnt lgkmcnt(7)
	v_add_f32_e32 v232, v232, v140
	s_waitcnt lgkmcnt(6)
	v_add_f32_e32 v233, v233, v141
	s_waitcnt lgkmcnt(5)
	v_add_f32_e32 v234, v234, v142
	s_waitcnt lgkmcnt(4)
	v_add_f32_e32 v235, v235, v143
	s_waitcnt lgkmcnt(3)
	v_add_f32_e32 v236, v236, v144
	s_waitcnt lgkmcnt(2)
	v_add_f32_e32 v237, v237, v145
	s_waitcnt lgkmcnt(1)
	v_add_f32_e32 v238, v238, v146
	s_waitcnt lgkmcnt(0)
	v_add_f32_e32 v239, v239, v147
	v_lshlrev_b32_e32 v243, 2, v156
	s_add_u32 s90, s76, 0x6500000
	s_addc_u32 s91, s77, 0
	s_add_u32 s76, s76, 0x3186000
	s_addc_u32 s77, s77, 0
	s_lshl_b32 s83, s6, 6
	s_add_u32 s78, s76, s83
	s_addc_u32 s79, s77, 0
	s_add_u32 s78, s78, 0x20000
	s_addc_u32 s79, s79, 0
	s_mov_b64 s[80:81], exec
	s_mov_b64 exec, 0xffff
	global_atomic_add_f32 v243, v232, s[76:77]
	global_atomic_add_f32 v243, v233, s[76:77] offset:64
	global_atomic_add_f32 v243, v234, s[76:77] offset:128
	global_atomic_add_f32 v243, v235, s[76:77] offset:192
	global_atomic_add_f32 v243, v236, s[76:77] offset:512
	global_atomic_add_f32 v243, v237, s[76:77] offset:576
	global_atomic_add_f32 v243, v238, s[76:77] offset:640
	global_atomic_add_f32 v243, v239, s[76:77] offset:704
	s_mov_b64 exec, s[80:81]
	s_add_u32 s86, s8, 0x1000
	s_addc_u32 s87, s9, 0
	s_add_u32 s88, s86, 0x1000
	s_addc_u32 s89, s87, 0
	s_add_u32 s92, s92, 0x4000
	s_addc_u32 s93, s93, 0
	s_mov_b32 s84, 0xffff0000
	s_mov_b32 s85, 0xffff0000
	s_waitcnt vmcnt(0)
	s_barrier
	v_readfirstlane_b32 s83, v206
	v_mov_b32_e32 v244, 0
	v_mov_b32_e32 v245, 1
	s_cmp_lg_u32 s83, 0
	s_cbranch_scc1 .Lfme_wait_done
	s_mov_b64 exec, 1
	global_atomic_add v244, v245, s[78:79]
	s_mov_b32 s82, 0

; __device__ __forceinline__ unsigned cvtpk_s(float lo, float hi) { f32x2_t v = {lo, hi}; bf16x2_t b = __builtin_convertvector(v, bf16x2_t); return __builtin_bit_cast(unsigned, b); }
; __device__ __forceinline__ u32x4 quad_swap(unsigned lo0, unsigned lo1, unsigned hi0, unsigned hi1, int fq, int& coloff) {
;     const bool odd = fq & 1;
;     const unsigned s0 = odd ? lo0 : hi0, s1 = odd ? lo1 : hi1;
;     const unsigned r0 = (unsigned)__shfl_xor((int)s0, 16), r1 = (unsigned)__shfl_xor((int)s1, 16);
;     coloff = odd ? 16 + 4 * (fq - 1) : 4 * fq;
;     u32x4 o; o.x = odd ? r0 : lo0; o.y = odd ? r1 : lo1; o.z = odd ? hi0 : r0; o.w = odd ? hi1 : r1; return o;
; }
; __device__ __forceinline__ void modpass(const float* xs_main, const float* xs_ctx, const float* mod_l, const float* g, int i, bf16_t* H, int nrows, int gw, int NGW, int lane) {
;     ...
;         if (cond != cur) { cur = cond; const float* shift = mod_l + cond * 9216 + 3 * i * 1024; const float* scale = shift + 1024;
; #pragma unroll
;             for (int j = 0; j < 2; ++j)
; #pragma unroll
;                 for (int q = 0; q < 2; ++q) { const int c = 8 * lane + 512 * j + 4 * q; gm[j][q] = *(const f32x4*)(g + c) * (*(const f32x4*)(scale + c) + 1.0f); sh[j][q] = *(const f32x4*)(shift + c); } }
;         float ss = 0.f;
; #pragma unroll
;         for (int j = 0; j < 2; ++j)
; #pragma unroll
;             for (int q = 0; q < 2; ++q) ss += (v[j][q][0] * v[j][q][0] + v[j][q][1] * v[j][q][1]) + (v[j][q][2] * v[j][q][2] + v[j][q][3] * v[j][q][3]);
;         const float rstd = 1.0f / sqrtf(wave_sum(ss) * (1.0f / D) + EPS);
; #pragma unroll
;         for (int j = 0; j < 2; ++j) {
;             const f32x4 o0 = v[j][0] * rstd * gm[j][0] + sh[j][0], o1 = v[j][1] * rstd * gm[j][1] + sh[j][1];
;             u32x4 w; w.x = cvtpk_s(o0[0], o0[1]); w.y = cvtpk_s(o0[2], o0[3]); w.z = cvtpk_s(o1[0], o1[1]); w.w = cvtpk_s(o1[2], o1[3]);
;             *(u32x4*)(H + (size_t)row * D + 8 * lane + 512 * j) = w;
.Lfme_wait_done:
	s_barrier
	global_load_dword v144, v243, s[76:77] sc1
	global_load_dword v145, v243, s[76:77] offset:64 sc1
	global_load_dword v146, v243, s[76:77] offset:128 sc1
	global_load_dword v147, v243, s[76:77] offset:192 sc1
	global_load_dword v148, v243, s[76:77] offset:512 sc1
	global_load_dword v149, v243, s[76:77] offset:576 sc1
	global_load_dword v150, v243, s[76:77] offset:640 sc1
	global_load_dword v151, v243, s[76:77] offset:704 sc1
	global_load_dwordx4 v[196:199], v201, s[86:87]
	global_load_dwordx4 v[212:215], v201, s[86:87] offset:64
	global_load_dwordx4 v[216:219], v201, s[86:87] offset:512
	global_load_dwordx4 v[220:223], v201, s[86:87] offset:576
	global_load_dwordx4 v[152:155], v201, s[88:89]
	global_load_dwordx4 v[164:167], v201, s[88:89] offset:64
	global_load_dwordx4 v[168:171], v201, s[88:89] offset:512
	global_load_dwordx4 v[172:175], v201, s[88:89] offset:576
	global_load_dwordx4 v[176:179], v201, s[92:93]
	global_load_dwordx4 v[180:183], v201, s[92:93] offset:64
	global_load_dwordx4 v[184:187], v201, s[92:93] offset:512
	global_load_dwordx4 v[188:191], v201, s[92:93] offset:576
	v_mov_b32_e32 v240, 12
	v_cndmask_b32_e64 v240, 0, v240, s[84:85]
	v_add_u32_e32 v240, v240, v157
	v_lshlrev_b32_e32 v240, 1, v240
	v_lshl_add_u32 v247, v156, 11, v240
	v_mov_b32_e32 v240, 0x358637bd
	s_waitcnt vmcnt(0)
	v_fmamk_f32 v144, v144, 0x3a800000, v240
	v_fmamk_f32 v145, v145, 0x3a800000, v240
	v_fmamk_f32 v146, v146, 0x3a800000, v240
	v_fmamk_f32 v147, v147, 0x3a800000, v240
	v_fmamk_f32 v148, v148, 0x3a800000, v240
	v_fmamk_f32 v149, v149, 0x3a800000, v240
	v_fmamk_f32 v150, v150, 0x3a800000, v240
	v_fmamk_f32 v151, v151, 0x3a800000, v240
	v_rsq_f32_e32 v144, v144
	v_rsq_f32_e32 v145, v145
	v_rsq_f32_e32 v146, v146
	v_rsq_f32_e32 v147, v147
	v_rsq_f32_e32 v148, v148
	v_rsq_f32_e32 v149, v149
	v_rsq_f32_e32 v150, v150
	v_rsq_f32_e32 v151, v151
	v_pk_add_f32 v[152:153], v[152:153], 1.0 op_sel_hi:[1,0]
	v_pk_mul_f32 v[152:153], v[176:177], v[152:153]
	v_pk_add_f32 v[154:155], v[154:155], 1.0 op_sel_hi:[1,0]
	v_pk_mul_f32 v[154:155], v[178:179], v[154:155]
	v_pk_add_f32 v[164:165], v[164:165], 1.0 op_sel_hi:[1,0]
	v_pk_mul_f32 v[164:165], v[180:181], v[164:165]
	v_pk_add_f32 v[166:167], v[166:167], 1.0 op_sel_hi:[1,0]
	v_pk_mul_f32 v[166:167], v[182:183], v[166:167]
	v_pk_add_f32 v[168:169], v[168:169], 1.0 op_sel_hi:[1,0]
	v_pk_mul_f32 v[168:169], v[184:185], v[168:169]
	v_pk_add_f32 v[170:171], v[170:171], 1.0 op_sel_hi:[1,0]
	v_pk_mul_f32 v[170:171], v[186:187], v[170:171]
	v_pk_add_f32 v[172:173], v[172:173], 1.0 op_sel_hi:[1,0]
	v_pk_mul_f32 v[172:173], v[188:189], v[172:173]
	v_pk_add_f32 v[174:175], v[174:175], 1.0 op_sel_hi:[1,0]
	v_pk_mul_f32 v[174:175], v[190:191], v[174:175]
	v_mul_f32_e32 v124, v124, v144
	v_mul_f32_e32 v125, v125, v144
	v_pk_fma_f32 v[124:125], v[152:153], v[124:125], v[196:197]
	v_mul_f32_e32 v126, v126, v144
	v_mul_f32_e32 v127, v127, v144
	v_pk_fma_f32 v[126:127], v[154:155], v[126:127], v[198:199]
	v_cvt_pk_bf16_f32 v184, v124, v125
	v_cvt_pk_bf16_f32 v185, v126, v127
	v_mul_f32_e32 v120, v120, v144
	v_mul_f32_e32 v121, v121, v144
	v_pk_fma_f32 v[120:121], v[164:165], v[120:121], v[212:213]
	v_mul_f32_e32 v122, v122, v144
	v_mul_f32_e32 v123, v123, v144
	v_pk_fma_f32 v[122:123], v[166:167], v[122:123], v[214:215]
	v_cvt_pk_bf16_f32 v186, v120, v121
	v_cvt_pk_bf16_f32 v187, v122, v123
	v_mul_f32_e32 v116, v116, v144
	v_mul_f32_e32 v117, v117, v144
	v_pk_fma_f32 v[116:117], v[168:169], v[116:117], v[216:217]
	v_mul_f32_e32 v118, v118, v144
	v_mul_f32_e32 v119, v119, v144
	v_pk_fma_f32 v[118:119], v[170:171], v[118:119], v[218:219]
	v_cvt_pk_bf16_f32 v188, v116, v117
	v_cvt_pk_bf16_f32 v189, v118, v119
	v_mul_f32_e32 v112, v112, v144
	v_mul_f32_e32 v113, v113, v144
	v_pk_fma_f32 v[112:113], v[172:173], v[112:113], v[220:221]
	v_mul_f32_e32 v114, v114, v144
	v_mul_f32_e32 v115, v115, v144
	v_pk_fma_f32 v[114:115], v[174:175], v[114:115], v[222:223]
	v_cvt_pk_bf16_f32 v190, v112, v113
	v_cvt_pk_bf16_f32 v191, v114, v115
	v_mov_b32_e32 v240, v247
	v_cndmask_b32_e64 v192, v186, v184, s[84:85]
	v_cndmask_b32_e64 v193, v187, v185, s[84:85]
	ds_bpermute_b32 v194, v241, v192
	ds_bpermute_b32 v195, v241, v193
	s_waitcnt lgkmcnt(0)
	v_cndmask_b32_e64 v176, v184, v194, s[84:85]
	v_cndmask_b32_e64 v177, v185, v195, s[84:85]
	v_cndmask_b32_e64 v178, v194, v186, s[84:85]
	v_cndmask_b32_e64 v179, v195, v187, s[84:85]
	global_store_dwordx4 v240, v[176:179], s[90:91]
	v_cndmask_b32_e64 v192, v190, v188, s[84:85]
	v_cndmask_b32_e64 v193, v191, v189, s[84:85]
	ds_bpermute_b32 v194, v241, v192
	ds_bpermute_b32 v195, v241, v193
	s_waitcnt lgkmcnt(0)
	v_cndmask_b32_e64 v180, v188, v194, s[84:85]
	v_cndmask_b32_e64 v181, v189, v195, s[84:85]
	v_cndmask_b32_e64 v182, v194, v190, s[84:85]
	v_cndmask_b32_e64 v183, v195, v191, s[84:85]
	global_store_dwordx4 v240, v[180:183], s[90:91] offset:256
	v_mul_f32_e32 v108, v108, v145
	v_mul_f32_e32 v109, v109, v145
	v_pk_fma_f32 v[108:109], v[152:153], v[108:109], v[196:197]
	v_mul_f32_e32 v110, v110, v145
	v_mul_f32_e32 v111, v111, v145
	v_pk_fma_f32 v[110:111], v[154:155], v[110:111], v[198:199]
	v_cvt_pk_bf16_f32 v184, v108, v109
	v_cvt_pk_bf16_f32 v185, v110, v111
	v_mul_f32_e32 v104, v104, v145
	v_mul_f32_e32 v105, v105, v145
	v_pk_fma_f32 v[104:105], v[164:165], v[104:105], v[212:213]
	v_mul_f32_e32 v106, v106, v145
	v_mul_f32_e32 v107, v107, v145
	v_pk_fma_f32 v[106:107], v[166:167], v[106:107], v[214:215]
	v_cvt_pk_bf16_f32 v186, v104, v105
	v_cvt_pk_bf16_f32 v187, v106, v107
	v_mul_f32_e32 v100, v100, v145
	v_mul_f32_e32 v101, v101, v145
	v_pk_fma_f32 v[100:101], v[168:169], v[100:101], v[216:217]
	v_mul_f32_e32 v102, v102, v145
	v_mul_f32_e32 v103, v103, v145
	v_pk_fma_f32 v[102:103], v[170:171], v[102:103], v[218:219]
	v_cvt_pk_bf16_f32 v188, v100, v101
	v_cvt_pk_bf16_f32 v189, v102, v103
	v_mul_f32_e32 v96, v96, v145
	v_mul_f32_e32 v97, v97, v145
	v_pk_fma_f32 v[96:97], v[172:173], v[96:97], v[220:221]
	v_mul_f32_e32 v98, v98, v145
	v_mul_f32_e32 v99, v99, v145
	v_pk_fma_f32 v[98:99], v[174:175], v[98:99], v[222:223]
	v_cvt_pk_bf16_f32 v190, v96, v97
	v_cvt_pk_bf16_f32 v191, v98, v99
	v_add_u32_e32 v240, 0x8000, v247
	v_cndmask_b32_e64 v192, v186, v184, s[84:85]
	v_cndmask_b32_e64 v193, v187, v185, s[84:85]
	ds_bpermute_b32 v194, v241, v192
	ds_bpermute_b32 v195, v241, v193
	s_waitcnt lgkmcnt(0)
; __device__ __forceinline__ unsigned cvtpk_s(float lo, float hi) { f32x2_t v = {lo, hi}; bf16x2_t b = __builtin_convertvector(v, bf16x2_t); return __builtin_bit_cast(unsigned, b); }
; __device__ __forceinline__ u32x4 quad_swap(unsigned lo0, unsigned lo1, unsigned hi0, unsigned hi1, int fq, int& coloff) {
;     const bool odd = fq & 1;
;     const unsigned s0 = odd ? lo0 : hi0, s1 = odd ? lo1 : hi1;
;     const unsigned r0 = (unsigned)__shfl_xor((int)s0, 16), r1 = (unsigned)__shfl_xor((int)s1, 16);
;     coloff = odd ? 16 + 4 * (fq - 1) : 4 * fq;
;     u32x4 o; o.x = odd ? r0 : lo0; o.y = odd ? r1 : lo1; o.z = odd ? hi0 : r0; o.w = odd ? hi1 : r1; return o;
; }
; __device__ __forceinline__ void modpass(const float* xs_main, const float* xs_ctx, const float* mod_l, const float* g, int i, bf16_t* H, int nrows, int gw, int NGW, int lane) {
;     ...
;         for (int j = 0; j < 2; ++j) {
;             const f32x4 o0 = v[j][0] * rstd * gm[j][0] + sh[j][0], o1 = v[j][1] * rstd * gm[j][1] + sh[j][1];
;             u32x4 w; w.x = cvtpk_s(o0[0], o0[1]); w.y = cvtpk_s(o0[2], o0[3]); w.z = cvtpk_s(o1[0], o1[1]); w.w = cvtpk_s(o1[2], o1[3]);
;             *(u32x4*)(H + (size_t)row * D + 8 * lane + 512 * j) = w;
	v_cndmask_b32_e64 v176, v184, v194, s[84:85]
	v_cndmask_b32_e64 v177, v185, v195, s[84:85]
	v_cndmask_b32_e64 v178, v194, v186, s[84:85]
	v_cndmask_b32_e64 v179, v195, v187, s[84:85]
	global_store_dwordx4 v240, v[176:179], s[90:91]
	v_cndmask_b32_e64 v192, v190, v188, s[84:85]
	v_cndmask_b32_e64 v193, v191, v189, s[84:85]
	ds_bpermute_b32 v194, v241, v192
	ds_bpermute_b32 v195, v241, v193
	s_waitcnt lgkmcnt(0)
	v_cndmask_b32_e64 v180, v188, v194, s[84:85]
	v_cndmask_b32_e64 v181, v189, v195, s[84:85]
	v_cndmask_b32_e64 v182, v194, v190, s[84:85]
	v_cndmask_b32_e64 v183, v195, v191, s[84:85]
	global_store_dwordx4 v240, v[180:183], s[90:91] offset:256
	v_mul_f32_e32 v92, v92, v146
	v_mul_f32_e32 v93, v93, v146
	v_pk_fma_f32 v[92:93], v[152:153], v[92:93], v[196:197]
	v_mul_f32_e32 v94, v94, v146
	v_mul_f32_e32 v95, v95, v146
	v_pk_fma_f32 v[94:95], v[154:155], v[94:95], v[198:199]
	v_cvt_pk_bf16_f32 v184, v92, v93
	v_cvt_pk_bf16_f32 v185, v94, v95
	v_mul_f32_e32 v88, v88, v146
	v_mul_f32_e32 v89, v89, v146
	v_pk_fma_f32 v[88:89], v[164:165], v[88:89], v[212:213]
	v_mul_f32_e32 v90, v90, v146
	v_mul_f32_e32 v91, v91, v146
	v_pk_fma_f32 v[90:91], v[166:167], v[90:91], v[214:215]
	v_cvt_pk_bf16_f32 v186, v88, v89
	v_cvt_pk_bf16_f32 v187, v90, v91
	v_mul_f32_e32 v84, v84, v146
	v_mul_f32_e32 v85, v85, v146
	v_pk_fma_f32 v[84:85], v[168:169], v[84:85], v[216:217]
	v_mul_f32_e32 v86, v86, v146
	v_mul_f32_e32 v87, v87, v146
	v_pk_fma_f32 v[86:87], v[170:171], v[86:87], v[218:219]
	v_cvt_pk_bf16_f32 v188, v84, v85
	v_cvt_pk_bf16_f32 v189, v86, v87
	v_mul_f32_e32 v80, v80, v146
	v_mul_f32_e32 v81, v81, v146
	v_pk_fma_f32 v[80:81], v[172:173], v[80:81], v[220:221]
	v_mul_f32_e32 v82, v82, v146
	v_mul_f32_e32 v83, v83, v146
	v_pk_fma_f32 v[82:83], v[174:175], v[82:83], v[222:223]
	v_cvt_pk_bf16_f32 v190, v80, v81
	v_cvt_pk_bf16_f32 v191, v82, v83
	v_add_u32_e32 v240, 0x10000, v247
	v_cndmask_b32_e64 v192, v186, v184, s[84:85]
	v_cndmask_b32_e64 v193, v187, v185, s[84:85]
	ds_bpermute_b32 v194, v241, v192
	ds_bpermute_b32 v195, v241, v193
	s_waitcnt lgkmcnt(0)
	v_cndmask_b32_e64 v176, v184, v194, s[84:85]
	v_cndmask_b32_e64 v177, v185, v195, s[84:85]
	v_cndmask_b32_e64 v178, v194, v186, s[84:85]
	v_cndmask_b32_e64 v179, v195, v187, s[84:85]
	global_store_dwordx4 v240, v[176:179], s[90:91]
	v_cndmask_b32_e64 v192, v190, v188, s[84:85]
	v_cndmask_b32_e64 v193, v191, v189, s[84:85]
	ds_bpermute_b32 v194, v241, v192
	ds_bpermute_b32 v195, v241, v193
	s_waitcnt lgkmcnt(0)
	v_cndmask_b32_e64 v180, v188, v194, s[84:85]
	v_cndmask_b32_e64 v181, v189, v195, s[84:85]
	v_cndmask_b32_e64 v182, v194, v190, s[84:85]
	v_cndmask_b32_e64 v183, v195, v191, s[84:85]
	global_store_dwordx4 v240, v[180:183], s[90:91] offset:256
	v_mul_f32_e32 v76, v76, v147
	v_mul_f32_e32 v77, v77, v147
	v_pk_fma_f32 v[76:77], v[152:153], v[76:77], v[196:197]
	v_mul_f32_e32 v78, v78, v147
	v_mul_f32_e32 v79, v79, v147
	v_pk_fma_f32 v[78:79], v[154:155], v[78:79], v[198:199]
	v_cvt_pk_bf16_f32 v184, v76, v77
	v_cvt_pk_bf16_f32 v185, v78, v79
	v_mul_f32_e32 v72, v72, v147
	v_mul_f32_e32 v73, v73, v147
	v_pk_fma_f32 v[72:73], v[164:165], v[72:73], v[212:213]
	v_mul_f32_e32 v74, v74, v147
	v_mul_f32_e32 v75, v75, v147
	v_pk_fma_f32 v[74:75], v[166:167], v[74:75], v[214:215]
	v_cvt_pk_bf16_f32 v186, v72, v73
	v_cvt_pk_bf16_f32 v187, v74, v75
	v_mul_f32_e32 v68, v68, v147
	v_mul_f32_e32 v69, v69, v147
	v_pk_fma_f32 v[68:69], v[168:169], v[68:69], v[216:217]
	v_mul_f32_e32 v70, v70, v147
	v_mul_f32_e32 v71, v71, v147
	v_pk_fma_f32 v[70:71], v[170:171], v[70:71], v[218:219]
	v_cvt_pk_bf16_f32 v188, v68, v69
	v_cvt_pk_bf16_f32 v189, v70, v71
	v_mul_f32_e32 v64, v64, v147
	v_mul_f32_e32 v65, v65, v147
	v_pk_fma_f32 v[64:65], v[172:173], v[64:65], v[220:221]
	v_mul_f32_e32 v66, v66, v147
	v_mul_f32_e32 v67, v67, v147
	v_pk_fma_f32 v[66:67], v[174:175], v[66:67], v[222:223]
	v_cvt_pk_bf16_f32 v190, v64, v65
	v_cvt_pk_bf16_f32 v191, v66, v67
	v_add_u32_e32 v240, 0x18000, v247
	v_cndmask_b32_e64 v192, v186, v184, s[84:85]
	v_cndmask_b32_e64 v193, v187, v185, s[84:85]
	ds_bpermute_b32 v194, v241, v192
	ds_bpermute_b32 v195, v241, v193
	s_waitcnt lgkmcnt(0)
	v_cndmask_b32_e64 v176, v184, v194, s[84:85]
	v_cndmask_b32_e64 v177, v185, v195, s[84:85]
	v_cndmask_b32_e64 v178, v194, v186, s[84:85]
	v_cndmask_b32_e64 v179, v195, v187, s[84:85]
	global_store_dwordx4 v240, v[176:179], s[90:91]
	v_cndmask_b32_e64 v192, v190, v188, s[84:85]
	v_cndmask_b32_e64 v193, v191, v189, s[84:85]
	ds_bpermute_b32 v194, v241, v192
	ds_bpermute_b32 v195, v241, v193
	s_waitcnt lgkmcnt(0)
	v_cndmask_b32_e64 v180, v188, v194, s[84:85]
	v_cndmask_b32_e64 v181, v189, v195, s[84:85]
	v_cndmask_b32_e64 v182, v194, v190, s[84:85]
	v_cndmask_b32_e64 v183, v195, v191, s[84:85]
	global_store_dwordx4 v240, v[180:183], s[90:91] offset:256
	v_mul_f32_e32 v60, v60, v148
	v_mul_f32_e32 v61, v61, v148
	v_pk_fma_f32 v[60:61], v[152:153], v[60:61], v[196:197]
	v_mul_f32_e32 v62, v62, v148
	v_mul_f32_e32 v63, v63, v148
	v_pk_fma_f32 v[62:63], v[154:155], v[62:63], v[198:199]
	v_cvt_pk_bf16_f32 v184, v60, v61
	v_cvt_pk_bf16_f32 v185, v62, v63
	v_mul_f32_e32 v56, v56, v148
	v_mul_f32_e32 v57, v57, v148
	v_pk_fma_f32 v[56:57], v[164:165], v[56:57], v[212:213]
	v_mul_f32_e32 v58, v58, v148
	v_mul_f32_e32 v59, v59, v148
	v_pk_fma_f32 v[58:59], v[166:167], v[58:59], v[214:215]
	v_cvt_pk_bf16_f32 v186, v56, v57
	v_cvt_pk_bf16_f32 v187, v58, v59
	v_mul_f32_e32 v52, v52, v148
	v_mul_f32_e32 v53, v53, v148
	v_pk_fma_f32 v[52:53], v[168:169], v[52:53], v[216:217]
	v_mul_f32_e32 v54, v54, v148
	v_mul_f32_e32 v55, v55, v148
	v_pk_fma_f32 v[54:55], v[170:171], v[54:55], v[218:219]
	v_cvt_pk_bf16_f32 v188, v52, v53
	v_cvt_pk_bf16_f32 v189, v54, v55
	v_mul_f32_e32 v48, v48, v148
	v_mul_f32_e32 v49, v49, v148
	v_pk_fma_f32 v[48:49], v[172:173], v[48:49], v[220:221]
	v_mul_f32_e32 v50, v50, v148
	v_mul_f32_e32 v51, v51, v148
	v_pk_fma_f32 v[50:51], v[174:175], v[50:51], v[222:223]
	v_cvt_pk_bf16_f32 v190, v48, v49
	v_cvt_pk_bf16_f32 v191, v50, v51
	v_add_u32_e32 v240, 0x40000, v247
	v_cndmask_b32_e64 v192, v186, v184, s[84:85]
	v_cndmask_b32_e64 v193, v187, v185, s[84:85]
	ds_bpermute_b32 v194, v241, v192
	ds_bpermute_b32 v195, v241, v193
	s_waitcnt lgkmcnt(0)
; __device__ __forceinline__ unsigned cvtpk_s(float lo, float hi) { f32x2_t v = {lo, hi}; bf16x2_t b = __builtin_convertvector(v, bf16x2_t); return __builtin_bit_cast(unsigned, b); }
; __device__ __forceinline__ u32x4 quad_swap(unsigned lo0, unsigned lo1, unsigned hi0, unsigned hi1, int fq, int& coloff) {
;     const bool odd = fq & 1;
;     const unsigned s0 = odd ? lo0 : hi0, s1 = odd ? lo1 : hi1;
;     const unsigned r0 = (unsigned)__shfl_xor((int)s0, 16), r1 = (unsigned)__shfl_xor((int)s1, 16);
;     coloff = odd ? 16 + 4 * (fq - 1) : 4 * fq;
;     u32x4 o; o.x = odd ? r0 : lo0; o.y = odd ? r1 : lo1; o.z = odd ? hi0 : r0; o.w = odd ? hi1 : r1; return o;
; }
; __device__ __forceinline__ void modpass(const float* xs_main, const float* xs_ctx, const float* mod_l, const float* g, int i, bf16_t* H, int nrows, int gw, int NGW, int lane) {
;     ...
;         for (int j = 0; j < 2; ++j) {
;             const f32x4 o0 = v[j][0] * rstd * gm[j][0] + sh[j][0], o1 = v[j][1] * rstd * gm[j][1] + sh[j][1];
;             u32x4 w; w.x = cvtpk_s(o0[0], o0[1]); w.y = cvtpk_s(o0[2], o0[3]); w.z = cvtpk_s(o1[0], o1[1]); w.w = cvtpk_s(o1[2], o1[3]);
;             *(u32x4*)(H + (size_t)row * D + 8 * lane + 512 * j) = w;
	v_cndmask_b32_e64 v176, v184, v194, s[84:85]
	v_cndmask_b32_e64 v177, v185, v195, s[84:85]
	v_cndmask_b32_e64 v178, v194, v186, s[84:85]
	v_cndmask_b32_e64 v179, v195, v187, s[84:85]
	global_store_dwordx4 v240, v[176:179], s[90:91]
	v_cndmask_b32_e64 v192, v190, v188, s[84:85]
	v_cndmask_b32_e64 v193, v191, v189, s[84:85]
	ds_bpermute_b32 v194, v241, v192
	ds_bpermute_b32 v195, v241, v193
	s_waitcnt lgkmcnt(0)
	v_cndmask_b32_e64 v180, v188, v194, s[84:85]
	v_cndmask_b32_e64 v181, v189, v195, s[84:85]
	v_cndmask_b32_e64 v182, v194, v190, s[84:85]
	v_cndmask_b32_e64 v183, v195, v191, s[84:85]
	global_store_dwordx4 v240, v[180:183], s[90:91] offset:256
	v_mul_f32_e32 v44, v44, v149
	v_mul_f32_e32 v45, v45, v149
	v_pk_fma_f32 v[44:45], v[152:153], v[44:45], v[196:197]
	v_mul_f32_e32 v46, v46, v149
	v_mul_f32_e32 v47, v47, v149
	v_pk_fma_f32 v[46:47], v[154:155], v[46:47], v[198:199]
	v_cvt_pk_bf16_f32 v184, v44, v45
	v_cvt_pk_bf16_f32 v185, v46, v47
	v_mul_f32_e32 v40, v40, v149
	v_mul_f32_e32 v41, v41, v149
	v_pk_fma_f32 v[40:41], v[164:165], v[40:41], v[212:213]
	v_mul_f32_e32 v42, v42, v149
	v_mul_f32_e32 v43, v43, v149
	v_pk_fma_f32 v[42:43], v[166:167], v[42:43], v[214:215]
	v_cvt_pk_bf16_f32 v186, v40, v41
	v_cvt_pk_bf16_f32 v187, v42, v43
	v_mul_f32_e32 v36, v36, v149
	v_mul_f32_e32 v37, v37, v149
	v_pk_fma_f32 v[36:37], v[168:169], v[36:37], v[216:217]
	v_mul_f32_e32 v38, v38, v149
	v_mul_f32_e32 v39, v39, v149
	v_pk_fma_f32 v[38:39], v[170:171], v[38:39], v[218:219]
	v_cvt_pk_bf16_f32 v188, v36, v37
	v_cvt_pk_bf16_f32 v189, v38, v39
	v_mul_f32_e32 v32, v32, v149
	v_mul_f32_e32 v33, v33, v149
	v_pk_fma_f32 v[32:33], v[172:173], v[32:33], v[220:221]
	v_mul_f32_e32 v34, v34, v149
	v_mul_f32_e32 v35, v35, v149
	v_pk_fma_f32 v[34:35], v[174:175], v[34:35], v[222:223]
	v_cvt_pk_bf16_f32 v190, v32, v33
	v_cvt_pk_bf16_f32 v191, v34, v35
	v_add_u32_e32 v240, 0x48000, v247
	v_cndmask_b32_e64 v192, v186, v184, s[84:85]
	v_cndmask_b32_e64 v193, v187, v185, s[84:85]
	ds_bpermute_b32 v194, v241, v192
	ds_bpermute_b32 v195, v241, v193
	s_waitcnt lgkmcnt(0)
	v_cndmask_b32_e64 v176, v184, v194, s[84:85]
	v_cndmask_b32_e64 v177, v185, v195, s[84:85]
	v_cndmask_b32_e64 v178, v194, v186, s[84:85]
	v_cndmask_b32_e64 v179, v195, v187, s[84:85]
	global_store_dwordx4 v240, v[176:179], s[90:91]
	v_cndmask_b32_e64 v192, v190, v188, s[84:85]
	v_cndmask_b32_e64 v193, v191, v189, s[84:85]
	ds_bpermute_b32 v194, v241, v192
	ds_bpermute_b32 v195, v241, v193
	s_waitcnt lgkmcnt(0)
	v_cndmask_b32_e64 v180, v188, v194, s[84:85]
	v_cndmask_b32_e64 v181, v189, v195, s[84:85]
	v_cndmask_b32_e64 v182, v194, v190, s[84:85]
	v_cndmask_b32_e64 v183, v195, v191, s[84:85]
	global_store_dwordx4 v240, v[180:183], s[90:91] offset:256
	v_mul_f32_e32 v28, v28, v150
	v_mul_f32_e32 v29, v29, v150
	v_pk_fma_f32 v[28:29], v[152:153], v[28:29], v[196:197]
	v_mul_f32_e32 v30, v30, v150
	v_mul_f32_e32 v31, v31, v150
	v_pk_fma_f32 v[30:31], v[154:155], v[30:31], v[198:199]
	v_cvt_pk_bf16_f32 v184, v28, v29
	v_cvt_pk_bf16_f32 v185, v30, v31
	v_mul_f32_e32 v24, v24, v150
	v_mul_f32_e32 v25, v25, v150
	v_pk_fma_f32 v[24:25], v[164:165], v[24:25], v[212:213]
	v_mul_f32_e32 v26, v26, v150
	v_mul_f32_e32 v27, v27, v150
	v_pk_fma_f32 v[26:27], v[166:167], v[26:27], v[214:215]
	v_cvt_pk_bf16_f32 v186, v24, v25
	v_cvt_pk_bf16_f32 v187, v26, v27
	v_mul_f32_e32 v20, v20, v150
	v_mul_f32_e32 v21, v21, v150
	v_pk_fma_f32 v[20:21], v[168:169], v[20:21], v[216:217]
	v_mul_f32_e32 v22, v22, v150
	v_mul_f32_e32 v23, v23, v150
	v_pk_fma_f32 v[22:23], v[170:171], v[22:23], v[218:219]
	v_cvt_pk_bf16_f32 v188, v20, v21
	v_cvt_pk_bf16_f32 v189, v22, v23
	v_mul_f32_e32 v16, v16, v150
	v_mul_f32_e32 v17, v17, v150
	v_pk_fma_f32 v[16:17], v[172:173], v[16:17], v[220:221]
	v_mul_f32_e32 v18, v18, v150
	v_mul_f32_e32 v19, v19, v150
	v_pk_fma_f32 v[18:19], v[174:175], v[18:19], v[222:223]
	v_cvt_pk_bf16_f32 v190, v16, v17
	v_cvt_pk_bf16_f32 v191, v18, v19
	v_add_u32_e32 v240, 0x50000, v247
	v_cndmask_b32_e64 v192, v186, v184, s[84:85]
	v_cndmask_b32_e64 v193, v187, v185, s[84:85]
	ds_bpermute_b32 v194, v241, v192
	ds_bpermute_b32 v195, v241, v193
	s_waitcnt lgkmcnt(0)
	v_cndmask_b32_e64 v176, v184, v194, s[84:85]
	v_cndmask_b32_e64 v177, v185, v195, s[84:85]
	v_cndmask_b32_e64 v178, v194, v186, s[84:85]
	v_cndmask_b32_e64 v179, v195, v187, s[84:85]
	global_store_dwordx4 v240, v[176:179], s[90:91]
	v_cndmask_b32_e64 v192, v190, v188, s[84:85]
	v_cndmask_b32_e64 v193, v191, v189, s[84:85]
	ds_bpermute_b32 v194, v241, v192
	ds_bpermute_b32 v195, v241, v193
	s_waitcnt lgkmcnt(0)
	v_cndmask_b32_e64 v180, v188, v194, s[84:85]
	v_cndmask_b32_e64 v181, v189, v195, s[84:85]
	v_cndmask_b32_e64 v182, v194, v190, s[84:85]
	v_cndmask_b32_e64 v183, v195, v191, s[84:85]
	global_store_dwordx4 v240, v[180:183], s[90:91] offset:256
	v_mul_f32_e32 v12, v12, v151
	v_mul_f32_e32 v13, v13, v151
	v_pk_fma_f32 v[12:13], v[152:153], v[12:13], v[196:197]
	v_mul_f32_e32 v14, v14, v151
	v_mul_f32_e32 v15, v15, v151
	v_pk_fma_f32 v[14:15], v[154:155], v[14:15], v[198:199]
	v_cvt_pk_bf16_f32 v184, v12, v13
	v_cvt_pk_bf16_f32 v185, v14, v15
	v_mul_f32_e32 v8, v8, v151
	v_mul_f32_e32 v9, v9, v151
	v_pk_fma_f32 v[8:9], v[164:165], v[8:9], v[212:213]
	v_mul_f32_e32 v10, v10, v151
	v_mul_f32_e32 v11, v11, v151
	v_pk_fma_f32 v[10:11], v[166:167], v[10:11], v[214:215]
	v_cvt_pk_bf16_f32 v186, v8, v9
	v_cvt_pk_bf16_f32 v187, v10, v11
	v_mul_f32_e32 v4, v4, v151
	v_mul_f32_e32 v5, v5, v151
	v_pk_fma_f32 v[4:5], v[168:169], v[4:5], v[216:217]
	v_mul_f32_e32 v6, v6, v151
	v_mul_f32_e32 v7, v7, v151
	v_pk_fma_f32 v[6:7], v[170:171], v[6:7], v[218:219]
	v_cvt_pk_bf16_f32 v188, v4, v5
	v_cvt_pk_bf16_f32 v189, v6, v7
	v_mul_f32_e32 v0, v0, v151
	v_mul_f32_e32 v1, v1, v151
	v_pk_fma_f32 v[0:1], v[172:173], v[0:1], v[220:221]
	v_mul_f32_e32 v2, v2, v151
	v_mul_f32_e32 v3, v3, v151
	v_pk_fma_f32 v[2:3], v[174:175], v[2:3], v[222:223]
	v_cvt_pk_bf16_f32 v190, v0, v1
	v_cvt_pk_bf16_f32 v191, v2, v3
	v_add_u32_e32 v240, 0x58000, v247
	v_cndmask_b32_e64 v192, v186, v184, s[84:85]
	v_cndmask_b32_e64 v193, v187, v185, s[84:85]
	ds_bpermute_b32 v194, v241, v192
	ds_bpermute_b32 v195, v241, v193
	s_waitcnt lgkmcnt(0)
	v_cndmask_b32_e64 v176, v184, v194, s[84:85]
	v_cndmask_b32_e64 v177, v185, v195, s[84:85]
	v_cndmask_b32_e64 v178, v194, v186, s[84:85]
	v_cndmask_b32_e64 v179, v195, v187, s[84:85]
	global_store_dwordx4 v240, v[176:179], s[90:91]
	v_cndmask_b32_e64 v192, v190, v188, s[84:85]
	v_cndmask_b32_e64 v193, v191, v189, s[84:85]
	ds_bpermute_b32 v194, v241, v192
	ds_bpermute_b32 v195, v241, v193
	s_waitcnt lgkmcnt(0)
	v_cndmask_b32_e64 v180, v188, v194, s[84:85]
	v_cndmask_b32_e64 v181, v189, v195, s[84:85]
	v_cndmask_b32_e64 v182, v194, v190, s[84:85]
	v_cndmask_b32_e64 v183, v195, v191, s[84:85]
	global_store_dwordx4 v240, v[180:183], s[90:91] offset:256
	s_and_b64 vcc, exec, s[10:11]
	s_mov_b64 s[10:11], -1
	s_cbranch_vccnz .LBB0_1551
	s_andn2_b64 vcc, exec, s[16:17]
	s_cbranch_vccnz .LBB0_1550
	s_barrier
	s_branch .LBB0_1550

; __device__ __forceinline__ void modpass(const float* xs_main, const float* xs_ctx, const float* mod_l, const float* g, int i, bf16_t* H, int nrows, int gw, int NGW, int lane) {
;     f32x4 gm[2][2], sh[2][2], v[2][2], vn[2][2]; int cur = -1;
;     int row = gw;
;     if (row < nrows) { const float* xr = row < MX ? xs_main + (size_t)row * D : xs_ctx + (size_t)(row - MX) * D;
; #pragma unroll
;         for (int j = 0; j < 2; ++j) { v[j][0] = *(const f32x4*)(xr + 8 * lane + 512 * j); v[j][1] = *(const f32x4*)(xr + 8 * lane + 512 * j + 4); } }
;     for (; row < nrows; row += NGW) {
;         const int nrow = row + NGW;
;         if (nrow < nrows) { const float* xr = nrow < MX ? xs_main + (size_t)nrow * D : xs_ctx + (size_t)(nrow - MX) * D;
; #pragma unroll
;             for (int j = 0; j < 2; ++j) { vn[j][0] = *(const f32x4*)(xr + 8 * lane + 512 * j); vn[j][1] = *(const f32x4*)(xr + 8 * lane + 512 * j + 4); } }
.LBB0_1627:
	s_or_b64 exec, exec, s[10:11]
	s_mov_b64 s[16:17], s[0:1]
	v_mov_b32_e32 v2, v206
	s_waitcnt lgkmcnt(0)
	s_barrier
	s_nop 0
	v_readfirstlane_b32 s6, v2
	s_ashr_i32 s6, s6, 6
	s_add_i32 s10, s6, s33
	s_add_i32 s10, s10, 0x8000
	s_cmp_gt_i32 s10, 0x81ff
	s_cbranch_scc1 .LBB0_1634
	s_load_dwordx4 s[12:15], s[16:17], 0xb0
	s_load_dwordx2 s[8:9], s[16:17], 0x30
	v_lshlrev_b32_e32 v0, 3, v2
	v_and_b32_e32 v64, 0x1f8, v0
	v_lshlrev_b32_e32 v0, 2, v64
	s_waitcnt lgkmcnt(0)
	s_add_u32 s6, s14, 0x6300000
	s_addc_u32 s7, s15, 0
	s_add_u32 s16, s8, 0x4000
	s_addc_u32 s17, s9, 0
	s_add_i32 s8, s10, 0xffff8000
	s_ashr_i32 s11, s10, 31
	s_cmp_lt_i32 s10, 0x8000
	s_cselect_b32 s9, s11, 0
	s_cselect_b32 s8, s10, s8
	s_cselect_b32 s18, s13, s7
	s_cselect_b32 s19, s12, s6
	s_lshl_b64 s[8:9], s[8:9], 12
	s_add_u32 s8, s19, s8
	s_addc_u32 s9, s18, s9
	global_load_dwordx4 v[12:15], v0, s[8:9] offset:16
	global_load_dwordx4 v[16:19], v0, s[8:9]
	global_load_dwordx4 v[4:7], v0, s[8:9] offset:2064
	global_load_dwordx4 v[8:11], v0, s[8:9] offset:2048
	v_xor_b32_e32 v3, 1, v202
	v_cmp_lt_i32_e32 vcc, v3, v203
	v_mov_b32_e32 v1, 0
	v_or_b32_e32 v20, 0x200, v64
	v_cndmask_b32_e32 v3, v202, v3, vcc
	v_lshlrev_b32_e32 v65, 2, v3
	v_xor_b32_e32 v3, 2, v202
	v_cmp_lt_i32_e32 vcc, v3, v203
	s_add_u32 s8, s14, 0x1e000
	v_lshl_add_u64 v[66:67], s[16:17], 0, v[0:1]
	v_cndmask_b32_e32 v3, v202, v3, vcc
	v_lshlrev_b32_e32 v72, 2, v3
	v_xor_b32_e32 v3, 4, v202
	v_cmp_lt_i32_e32 vcc, v3, v203
	v_lshlrev_b32_e32 v0, 2, v20
	s_addc_u32 s9, s15, 0
	v_cndmask_b32_e32 v3, v202, v3, vcc
	v_lshlrev_b32_e32 v73, 2, v3
	v_xor_b32_e32 v3, 8, v202
	v_cmp_lt_i32_e32 vcc, v3, v203
	v_lshl_add_u64 v[68:69], s[16:17], 0, v[0:1]
	s_lshl_b64 s[16:17], s[10:11], 11
	v_cndmask_b32_e32 v3, v202, v3, vcc
	v_cmp_lt_i32_e32 vcc, v204, v203
	v_lshlrev_b32_e32 v74, 2, v3
	v_and_b32_e32 v0, 63, v2
	v_cndmask_b32_e32 v3, v202, v204, vcc
	v_lshlrev_b32_e32 v75, 2, v3
	v_xor_b32_e32 v3, 32, v202
	v_cmp_lt_i32_e32 vcc, v3, v203
	s_add_u32 s14, s14, s16
	v_lshlrev_b32_e32 v0, 4, v0
	v_cndmask_b32_e32 v3, v202, v3, vcc
	s_addc_u32 s15, s15, s17
	v_lshlrev_b32_e32 v76, 2, v3
	v_lshl_add_u64 v[2:3], s[14:15], 0, v[0:1]
	s_mov_b64 s[14:15], 0x6500400
	s_ashr_i32 s29, s28, 31
	s_add_i32 s18, s10, s28
	s_mov_b32 s21, -1
	v_lshl_add_u64 v[70:71], v[2:3], 0, s[14:15]
	s_lshl_b64 s[14:15], s[28:29], 11
	s_ashr_i32 s19, s18, 31
	v_lshlrev_b32_e32 v77, 2, v20
	v_mov_b32_e32 v78, 0x358637bd
	s_mov_b32 s20, 0xf800000
	v_mov_b32_e32 v79, 0x260
	v_mov_b32_e32 v0, v1
	v_mov_b32_e32 v2, v1
	v_mov_b32_e32 v3, v1
	v_mov_b32_e32 v20, v1
	v_mov_b32_e32 v21, v1
	v_mov_b32_e32 v22, v1
	v_mov_b32_e32 v23, v1
	v_mov_b32_e32 v28, v1
	v_mov_b32_e32 v29, v1
	v_mov_b32_e32 v30, v1
	v_mov_b32_e32 v31, v1
	v_mov_b32_e32 v24, v1
	v_mov_b32_e32 v25, v1
	v_mov_b32_e32 v26, v1
	v_mov_b32_e32 v27, v1
	s_branch .LBB0_1630

;     __device__ __forceinline__ void operator()(const f32x4 (&acc)[2][2][4][2], const Unit& u, int wr, int wc, int fr, int fq) const {
;     ...
;         for (int ai = 0; ai < 2; ++ai)
; #pragma unroll
;             for (int m = 0; m < 4; ++m) {
;                 const int row = u.pm * BM + ai * HALF + wr * 64 + m * 16 + fr;
;                 const float* s = row < MX_ ? src_main + (size_t)row * D_ : src_ctx + (size_t)(row - MX_) * D_;
;                 float* d = row < MX_ ? dst_main + (size_t)row * D_ : dst_ctx + (size_t)(row - MX_) * D_;
; #pragma unroll
;                 for (int bj = 0; bj < 2; ++bj)
; #pragma unroll
;                     for (int n = 0; n < 2; ++n) { const int off = col0 + bj * HALF + n * 16; const f32x4 xo = *(const f32x4*)(s + off); *(f32x4*)(d + off) = xo + gv[bj][n] * acc[ai][bj][m][n]; }
; __device__ __forceinline__ void modpass(const float* xs_main, const float* xs_ctx, const float* mod_l, const float* g, int i, bf16_t* H, int nrows, int gw, int NGW, int lane) {
;     ...
;         float ss = 0.f;
; #pragma unroll
;         for (int j = 0; j < 2; ++j)
; #pragma unroll
;             for (int q = 0; q < 2; ++q) ss += (v[j][q][0] * v[j][q][0] + v[j][q][1] * v[j][q][1]) + (v[j][q][2] * v[j][q][2] + v[j][q][3] * v[j][q][3]);
.LBB0_2337:
	s_cmpk_lt_i32 s26, 0x80
	s_cselect_b32 s17, s63, 0x4800
	s_cmp_gt_i32 s26, 63
	s_cselect_b32 s17, s17, 0
	s_lshl_b32 s17, s17, 2
	s_add_u32 s34, s55, s17
	s_addc_u32 s35, s56, 0
	s_load_dwordx2 s[92:93], s[0:1], 0x30
	s_load_dwordx2 s[76:77], s[0:1], 0xb8
	v_lshl_add_u32 v156, s26, 8, v158
	v_lshl_or_b32 v157, s64, 8, v160
	v_lshlrev_b32_e32 v200, 2, v157
	v_lshl_add_u32 v201, v156, 12, v200
	global_load_dwordx4 v[196:199], v200, s[34:35]
	global_load_dwordx4 v[208:211], v200, s[34:35] offset:64
	global_load_dwordx4 v[212:215], v200, s[34:35] offset:512
	global_load_dwordx4 v[216:219], v200, s[34:35] offset:576
	v_add_u32_e32 v205, 0x10000, v201
	v_add_u32_e32 v207, 0x20000, v201
	v_add_u32_e32 v220, 0x30000, v201
	v_add_u32_e32 v221, 0x80000, v201
	v_add_u32_e32 v222, 0x90000, v201
	v_add_u32_e32 v223, 0xa0000, v201
	v_add_u32_e32 v224, 0xb0000, v201
	global_load_dwordx4 v[128:131], v201, s[8:9]
	global_load_dwordx4 v[132:135], v201, s[8:9] offset:64
	global_load_dwordx4 v[136:139], v201, s[8:9] offset:512
	global_load_dwordx4 v[140:143], v201, s[8:9] offset:576
	global_load_dwordx4 v[164:167], v205, s[8:9]
	global_load_dwordx4 v[168:171], v205, s[8:9] offset:64
	global_load_dwordx4 v[172:175], v205, s[8:9] offset:512
	global_load_dwordx4 v[176:179], v205, s[8:9] offset:576
	global_load_dwordx4 v[180:183], v207, s[8:9]
	global_load_dwordx4 v[184:187], v207, s[8:9] offset:64
	global_load_dwordx4 v[188:191], v207, s[8:9] offset:512
	global_load_dwordx4 v[192:195], v207, s[8:9] offset:576
	s_waitcnt vmcnt(12)
	s_waitcnt vmcnt(11)
	v_pk_fma_f32 v[124:125], v[124:125], v[196:197], v[128:129]
	v_pk_fma_f32 v[126:127], v[126:127], v[198:199], v[130:131]
	v_mul_f32_e32 v225, v124, v124
	v_fmac_f32_e32 v225, v125, v125
	v_fmac_f32_e32 v225, v126, v126
	v_fmac_f32_e32 v225, v127, v127
	s_waitcnt vmcnt(10)
	v_pk_fma_f32 v[120:121], v[120:121], v[208:209], v[132:133]
	v_pk_fma_f32 v[122:123], v[122:123], v[210:211], v[134:135]
	v_fmac_f32_e32 v225, v120, v120
	v_fmac_f32_e32 v225, v121, v121
	v_fmac_f32_e32 v225, v122, v122
	v_fmac_f32_e32 v225, v123, v123
	s_waitcnt vmcnt(9)
	v_pk_fma_f32 v[116:117], v[116:117], v[212:213], v[136:137]
	v_pk_fma_f32 v[118:119], v[118:119], v[214:215], v[138:139]
	v_fmac_f32_e32 v225, v116, v116
	v_fmac_f32_e32 v225, v117, v117
	v_fmac_f32_e32 v225, v118, v118
	v_fmac_f32_e32 v225, v119, v119
	s_waitcnt vmcnt(8)
	v_pk_fma_f32 v[112:113], v[112:113], v[216:217], v[140:141]
	v_pk_fma_f32 v[114:115], v[114:115], v[218:219], v[142:143]
	v_fmac_f32_e32 v225, v112, v112
	v_fmac_f32_e32 v225, v113, v113
	v_fmac_f32_e32 v225, v114, v114
	v_fmac_f32_e32 v225, v115, v115
	global_store_dwordx4 v201, v[124:127], s[8:9]
	global_store_dwordx4 v201, v[120:123], s[8:9] offset:64
	global_store_dwordx4 v201, v[116:119], s[8:9] offset:512
	global_store_dwordx4 v201, v[112:115], s[8:9] offset:576
	global_load_dwordx4 v[128:131], v220, s[8:9]
	global_load_dwordx4 v[132:135], v220, s[8:9] offset:64
	global_load_dwordx4 v[136:139], v220, s[8:9] offset:512
	global_load_dwordx4 v[140:143], v220, s[8:9] offset:576
	s_waitcnt vmcnt(15)
	v_pk_fma_f32 v[108:109], v[108:109], v[196:197], v[164:165]
	v_pk_fma_f32 v[110:111], v[110:111], v[198:199], v[166:167]
	v_mul_f32_e32 v226, v108, v108
	v_fmac_f32_e32 v226, v109, v109
	v_fmac_f32_e32 v226, v110, v110
	v_fmac_f32_e32 v226, v111, v111
	s_waitcnt vmcnt(14)
	v_pk_fma_f32 v[104:105], v[104:105], v[208:209], v[168:169]
	v_pk_fma_f32 v[106:107], v[106:107], v[210:211], v[170:171]
	v_fmac_f32_e32 v226, v104, v104
	v_fmac_f32_e32 v226, v105, v105
	v_fmac_f32_e32 v226, v106, v106
	v_fmac_f32_e32 v226, v107, v107
	s_waitcnt vmcnt(13)
	v_pk_fma_f32 v[100:101], v[100:101], v[212:213], v[172:173]
	v_pk_fma_f32 v[102:103], v[102:103], v[214:215], v[174:175]
	v_fmac_f32_e32 v226, v100, v100
	v_fmac_f32_e32 v226, v101, v101
	v_fmac_f32_e32 v226, v102, v102
	v_fmac_f32_e32 v226, v103, v103
	s_waitcnt vmcnt(12)
	v_pk_fma_f32 v[96:97], v[96:97], v[216:217], v[176:177]
	v_pk_fma_f32 v[98:99], v[98:99], v[218:219], v[178:179]
	v_fmac_f32_e32 v226, v96, v96
	v_fmac_f32_e32 v226, v97, v97
	v_fmac_f32_e32 v226, v98, v98
	v_fmac_f32_e32 v226, v99, v99
	global_store_dwordx4 v205, v[108:111], s[8:9]
	global_store_dwordx4 v205, v[104:107], s[8:9] offset:64
	global_store_dwordx4 v205, v[100:103], s[8:9] offset:512
	global_store_dwordx4 v205, v[96:99], s[8:9] offset:576
	global_load_dwordx4 v[164:167], v221, s[8:9]
	global_load_dwordx4 v[168:171], v221, s[8:9] offset:64
	global_load_dwordx4 v[172:175], v221, s[8:9] offset:512
	global_load_dwordx4 v[176:179], v221, s[8:9] offset:576
	s_waitcnt vmcnt(19)
	v_pk_fma_f32 v[92:93], v[92:93], v[196:197], v[180:181]
	v_pk_fma_f32 v[94:95], v[94:95], v[198:199], v[182:183]
	v_mul_f32_e32 v227, v92, v92
	v_fmac_f32_e32 v227, v93, v93
	v_fmac_f32_e32 v227, v94, v94
	v_fmac_f32_e32 v227, v95, v95
	s_waitcnt vmcnt(18)
	v_pk_fma_f32 v[88:89], v[88:89], v[208:209], v[184:185]
	v_pk_fma_f32 v[90:91], v[90:91], v[210:211], v[186:187]
	v_fmac_f32_e32 v227, v88, v88
	v_fmac_f32_e32 v227, v89, v89
	v_fmac_f32_e32 v227, v90, v90
	v_fmac_f32_e32 v227, v91, v91
	s_waitcnt vmcnt(17)
	v_pk_fma_f32 v[84:85], v[84:85], v[212:213], v[188:189]
	v_pk_fma_f32 v[86:87], v[86:87], v[214:215], v[190:191]
	v_fmac_f32_e32 v227, v84, v84
	v_fmac_f32_e32 v227, v85, v85
	v_fmac_f32_e32 v227, v86, v86
	v_fmac_f32_e32 v227, v87, v87
	s_waitcnt vmcnt(16)
;     __device__ __forceinline__ void operator()(const f32x4 (&acc)[2][2][4][2], const Unit& u, int wr, int wc, int fr, int fq) const {
;     ...
;         for (int ai = 0; ai < 2; ++ai)
; #pragma unroll
;             for (int m = 0; m < 4; ++m) {
;                 const int row = u.pm * BM + ai * HALF + wr * 64 + m * 16 + fr;
;                 const float* s = row < MX_ ? src_main + (size_t)row * D_ : src_ctx + (size_t)(row - MX_) * D_;
;                 float* d = row < MX_ ? dst_main + (size_t)row * D_ : dst_ctx + (size_t)(row - MX_) * D_;
; #pragma unroll
;                 for (int bj = 0; bj < 2; ++bj)
; #pragma unroll
;                     for (int n = 0; n < 2; ++n) { const int off = col0 + bj * HALF + n * 16; const f32x4 xo = *(const f32x4*)(s + off); *(f32x4*)(d + off) = xo + gv[bj][n] * acc[ai][bj][m][n]; }
; __device__ __forceinline__ void modpass(const float* xs_main, const float* xs_ctx, const float* mod_l, const float* g, int i, bf16_t* H, int nrows, int gw, int NGW, int lane) {
;     ...
;         float ss = 0.f;
; #pragma unroll
;         for (int j = 0; j < 2; ++j)
; #pragma unroll
;             for (int q = 0; q < 2; ++q) ss += (v[j][q][0] * v[j][q][0] + v[j][q][1] * v[j][q][1]) + (v[j][q][2] * v[j][q][2] + v[j][q][3] * v[j][q][3]);
	v_pk_fma_f32 v[80:81], v[80:81], v[216:217], v[192:193]
	v_pk_fma_f32 v[82:83], v[82:83], v[218:219], v[194:195]
	v_fmac_f32_e32 v227, v80, v80
	v_fmac_f32_e32 v227, v81, v81
	v_fmac_f32_e32 v227, v82, v82
	v_fmac_f32_e32 v227, v83, v83
	global_store_dwordx4 v207, v[92:95], s[8:9]
	global_store_dwordx4 v207, v[88:91], s[8:9] offset:64
	global_store_dwordx4 v207, v[84:87], s[8:9] offset:512
	global_store_dwordx4 v207, v[80:83], s[8:9] offset:576
	global_load_dwordx4 v[180:183], v222, s[8:9]
	global_load_dwordx4 v[184:187], v222, s[8:9] offset:64
	global_load_dwordx4 v[188:191], v222, s[8:9] offset:512
	global_load_dwordx4 v[192:195], v222, s[8:9] offset:576
	s_waitcnt vmcnt(19)
	v_pk_fma_f32 v[76:77], v[76:77], v[196:197], v[128:129]
	v_pk_fma_f32 v[78:79], v[78:79], v[198:199], v[130:131]
	v_mul_f32_e32 v228, v76, v76
	v_fmac_f32_e32 v228, v77, v77
	v_fmac_f32_e32 v228, v78, v78
	v_fmac_f32_e32 v228, v79, v79
	s_waitcnt vmcnt(18)
	v_pk_fma_f32 v[72:73], v[72:73], v[208:209], v[132:133]
	v_pk_fma_f32 v[74:75], v[74:75], v[210:211], v[134:135]
	v_fmac_f32_e32 v228, v72, v72
	v_fmac_f32_e32 v228, v73, v73
	v_fmac_f32_e32 v228, v74, v74
	v_fmac_f32_e32 v228, v75, v75
	s_waitcnt vmcnt(17)
	v_pk_fma_f32 v[68:69], v[68:69], v[212:213], v[136:137]
	v_pk_fma_f32 v[70:71], v[70:71], v[214:215], v[138:139]
	v_fmac_f32_e32 v228, v68, v68
	v_fmac_f32_e32 v228, v69, v69
	v_fmac_f32_e32 v228, v70, v70
	v_fmac_f32_e32 v228, v71, v71
	s_waitcnt vmcnt(16)
	v_pk_fma_f32 v[64:65], v[64:65], v[216:217], v[140:141]
	v_pk_fma_f32 v[66:67], v[66:67], v[218:219], v[142:143]
	v_fmac_f32_e32 v228, v64, v64
	v_fmac_f32_e32 v228, v65, v65
	v_fmac_f32_e32 v228, v66, v66
	v_fmac_f32_e32 v228, v67, v67
	global_store_dwordx4 v220, v[76:79], s[8:9]
	global_store_dwordx4 v220, v[72:75], s[8:9] offset:64
	global_store_dwordx4 v220, v[68:71], s[8:9] offset:512
	global_store_dwordx4 v220, v[64:67], s[8:9] offset:576
	global_load_dwordx4 v[128:131], v223, s[8:9]
	global_load_dwordx4 v[132:135], v223, s[8:9] offset:64
	global_load_dwordx4 v[136:139], v223, s[8:9] offset:512
	global_load_dwordx4 v[140:143], v223, s[8:9] offset:576
	s_waitcnt vmcnt(19)
	v_pk_fma_f32 v[60:61], v[60:61], v[196:197], v[164:165]
	v_pk_fma_f32 v[62:63], v[62:63], v[198:199], v[166:167]
	v_mul_f32_e32 v229, v60, v60
	v_fmac_f32_e32 v229, v61, v61
	v_fmac_f32_e32 v229, v62, v62
	v_fmac_f32_e32 v229, v63, v63
	s_waitcnt vmcnt(18)
	v_pk_fma_f32 v[56:57], v[56:57], v[208:209], v[168:169]
	v_pk_fma_f32 v[58:59], v[58:59], v[210:211], v[170:171]
	v_fmac_f32_e32 v229, v56, v56
	v_fmac_f32_e32 v229, v57, v57
	v_fmac_f32_e32 v229, v58, v58
	v_fmac_f32_e32 v229, v59, v59
	s_waitcnt vmcnt(17)
	v_pk_fma_f32 v[52:53], v[52:53], v[212:213], v[172:173]
	v_pk_fma_f32 v[54:55], v[54:55], v[214:215], v[174:175]
	v_fmac_f32_e32 v229, v52, v52
	v_fmac_f32_e32 v229, v53, v53
	v_fmac_f32_e32 v229, v54, v54
	v_fmac_f32_e32 v229, v55, v55
	s_waitcnt vmcnt(16)
	v_pk_fma_f32 v[48:49], v[48:49], v[216:217], v[176:177]
	v_pk_fma_f32 v[50:51], v[50:51], v[218:219], v[178:179]
	v_fmac_f32_e32 v229, v48, v48
	v_fmac_f32_e32 v229, v49, v49
	v_fmac_f32_e32 v229, v50, v50
	v_fmac_f32_e32 v229, v51, v51
	global_store_dwordx4 v221, v[60:63], s[8:9]
	global_store_dwordx4 v221, v[56:59], s[8:9] offset:64
	global_store_dwordx4 v221, v[52:55], s[8:9] offset:512
	global_store_dwordx4 v221, v[48:51], s[8:9] offset:576
	global_load_dwordx4 v[164:167], v224, s[8:9]
	global_load_dwordx4 v[168:171], v224, s[8:9] offset:64
	global_load_dwordx4 v[172:175], v224, s[8:9] offset:512
	global_load_dwordx4 v[176:179], v224, s[8:9] offset:576
	s_waitcnt vmcnt(19)
	v_pk_fma_f32 v[44:45], v[44:45], v[196:197], v[180:181]
	v_pk_fma_f32 v[46:47], v[46:47], v[198:199], v[182:183]
	v_mul_f32_e32 v230, v44, v44
	v_fmac_f32_e32 v230, v45, v45
	v_fmac_f32_e32 v230, v46, v46
	v_fmac_f32_e32 v230, v47, v47
	s_waitcnt vmcnt(18)
	v_pk_fma_f32 v[40:41], v[40:41], v[208:209], v[184:185]
	v_pk_fma_f32 v[42:43], v[42:43], v[210:211], v[186:187]
	v_fmac_f32_e32 v230, v40, v40
	v_fmac_f32_e32 v230, v41, v41
	v_fmac_f32_e32 v230, v42, v42
	v_fmac_f32_e32 v230, v43, v43
	s_waitcnt vmcnt(17)
	v_pk_fma_f32 v[36:37], v[36:37], v[212:213], v[188:189]
	v_pk_fma_f32 v[38:39], v[38:39], v[214:215], v[190:191]
	v_fmac_f32_e32 v230, v36, v36
	v_fmac_f32_e32 v230, v37, v37
	v_fmac_f32_e32 v230, v38, v38
	v_fmac_f32_e32 v230, v39, v39
	s_waitcnt vmcnt(16)
	v_pk_fma_f32 v[32:33], v[32:33], v[216:217], v[192:193]
	v_pk_fma_f32 v[34:35], v[34:35], v[218:219], v[194:195]
	v_fmac_f32_e32 v230, v32, v32
	v_fmac_f32_e32 v230, v33, v33
	v_fmac_f32_e32 v230, v34, v34
	v_fmac_f32_e32 v230, v35, v35
	global_store_dwordx4 v222, v[44:47], s[8:9]
	global_store_dwordx4 v222, v[40:43], s[8:9] offset:64
	global_store_dwordx4 v222, v[36:39], s[8:9] offset:512
	global_store_dwordx4 v222, v[32:35], s[8:9] offset:576
	s_waitcnt vmcnt(15)
	v_pk_fma_f32 v[28:29], v[28:29], v[196:197], v[128:129]
	v_pk_fma_f32 v[30:31], v[30:31], v[198:199], v[130:131]
	v_mul_f32_e32 v231, v28, v28
	v_fmac_f32_e32 v231, v29, v29
	v_fmac_f32_e32 v231, v30, v30
	v_fmac_f32_e32 v231, v31, v31
	s_waitcnt vmcnt(14)
;     __device__ __forceinline__ void operator()(const f32x4 (&acc)[2][2][4][2], const Unit& u, int wr, int wc, int fr, int fq) const {
;     ...
;         for (int ai = 0; ai < 2; ++ai)
; #pragma unroll
;             for (int m = 0; m < 4; ++m) {
;                 const int row = u.pm * BM + ai * HALF + wr * 64 + m * 16 + fr;
;                 const float* s = row < MX_ ? src_main + (size_t)row * D_ : src_ctx + (size_t)(row - MX_) * D_;
;                 float* d = row < MX_ ? dst_main + (size_t)row * D_ : dst_ctx + (size_t)(row - MX_) * D_;
; #pragma unroll
;                 for (int bj = 0; bj < 2; ++bj)
; #pragma unroll
;                     for (int n = 0; n < 2; ++n) { const int off = col0 + bj * HALF + n * 16; const f32x4 xo = *(const f32x4*)(s + off); *(f32x4*)(d + off) = xo + gv[bj][n] * acc[ai][bj][m][n]; }
; __device__ __forceinline__ float wave_sum(float v) {
; #pragma unroll
;     for (int o = 1; o < 64; o <<= 1) v += __shfl_xor(v, o);
;     return v;
; }
	v_pk_fma_f32 v[24:25], v[24:25], v[208:209], v[132:133]
	v_pk_fma_f32 v[26:27], v[26:27], v[210:211], v[134:135]
	v_fmac_f32_e32 v231, v24, v24
	v_fmac_f32_e32 v231, v25, v25
	v_fmac_f32_e32 v231, v26, v26
	v_fmac_f32_e32 v231, v27, v27
	s_waitcnt vmcnt(13)
	v_pk_fma_f32 v[20:21], v[20:21], v[212:213], v[136:137]
	v_pk_fma_f32 v[22:23], v[22:23], v[214:215], v[138:139]
	v_fmac_f32_e32 v231, v20, v20
	v_fmac_f32_e32 v231, v21, v21
	v_fmac_f32_e32 v231, v22, v22
	v_fmac_f32_e32 v231, v23, v23
	s_waitcnt vmcnt(12)
	v_pk_fma_f32 v[16:17], v[16:17], v[216:217], v[140:141]
	v_pk_fma_f32 v[18:19], v[18:19], v[218:219], v[142:143]
	v_fmac_f32_e32 v231, v16, v16
	v_fmac_f32_e32 v231, v17, v17
	v_fmac_f32_e32 v231, v18, v18
	v_fmac_f32_e32 v231, v19, v19
	global_store_dwordx4 v223, v[28:31], s[8:9]
	global_store_dwordx4 v223, v[24:27], s[8:9] offset:64
	global_store_dwordx4 v223, v[20:23], s[8:9] offset:512
	global_store_dwordx4 v223, v[16:19], s[8:9] offset:576
	s_waitcnt vmcnt(11)
	v_pk_fma_f32 v[12:13], v[12:13], v[196:197], v[164:165]
	v_pk_fma_f32 v[14:15], v[14:15], v[198:199], v[166:167]
	v_mul_f32_e32 v232, v12, v12
	v_fmac_f32_e32 v232, v13, v13
	v_fmac_f32_e32 v232, v14, v14
	v_fmac_f32_e32 v232, v15, v15
	s_waitcnt vmcnt(10)
	v_pk_fma_f32 v[8:9], v[8:9], v[208:209], v[168:169]
	v_pk_fma_f32 v[10:11], v[10:11], v[210:211], v[170:171]
	v_fmac_f32_e32 v232, v8, v8
	v_fmac_f32_e32 v232, v9, v9
	v_fmac_f32_e32 v232, v10, v10
	v_fmac_f32_e32 v232, v11, v11
	s_waitcnt vmcnt(9)
	v_pk_fma_f32 v[4:5], v[4:5], v[212:213], v[172:173]
	v_pk_fma_f32 v[6:7], v[6:7], v[214:215], v[174:175]
	v_fmac_f32_e32 v232, v4, v4
	v_fmac_f32_e32 v232, v5, v5
	v_fmac_f32_e32 v232, v6, v6
	v_fmac_f32_e32 v232, v7, v7
	s_waitcnt vmcnt(8)
	v_pk_fma_f32 v[0:1], v[0:1], v[216:217], v[176:177]
	v_pk_fma_f32 v[2:3], v[2:3], v[218:219], v[178:179]
	v_fmac_f32_e32 v232, v0, v0
	v_fmac_f32_e32 v232, v1, v1
	v_fmac_f32_e32 v232, v2, v2
	v_fmac_f32_e32 v232, v3, v3
	global_store_dwordx4 v224, v[12:15], s[8:9]
	global_store_dwordx4 v224, v[8:11], s[8:9] offset:64
	global_store_dwordx4 v224, v[4:7], s[8:9] offset:512
	global_store_dwordx4 v224, v[0:3], s[8:9] offset:576
	v_mbcnt_lo_u32_b32 v233, -1, 0
	v_mbcnt_hi_u32_b32 v233, -1, v233
	v_xor_b32_e32 v234, 16, v233
	v_xor_b32_e32 v235, 32, v233
	v_lshlrev_b32_e32 v234, 2, v234
	v_lshlrev_b32_e32 v235, 2, v235
	s_waitcnt lgkmcnt(0)
	ds_bpermute_b32 v128, v234, v225
	ds_bpermute_b32 v129, v234, v226
	ds_bpermute_b32 v130, v234, v227
	ds_bpermute_b32 v131, v234, v228
	ds_bpermute_b32 v132, v234, v229
	ds_bpermute_b32 v133, v234, v230
	ds_bpermute_b32 v134, v234, v231
	ds_bpermute_b32 v135, v234, v232
	s_waitcnt lgkmcnt(7)
	v_add_f32_e32 v225, v225, v128
	s_waitcnt lgkmcnt(6)
	v_add_f32_e32 v226, v226, v129
	s_waitcnt lgkmcnt(5)
	v_add_f32_e32 v227, v227, v130
	s_waitcnt lgkmcnt(4)
	v_add_f32_e32 v228, v228, v131
	s_waitcnt lgkmcnt(3)
	v_add_f32_e32 v229, v229, v132
	s_waitcnt lgkmcnt(2)
	v_add_f32_e32 v230, v230, v133
	s_waitcnt lgkmcnt(1)
	v_add_f32_e32 v231, v231, v134
	s_waitcnt lgkmcnt(0)
	v_add_f32_e32 v232, v232, v135
	ds_bpermute_b32 v128, v235, v225
	ds_bpermute_b32 v129, v235, v226
	ds_bpermute_b32 v130, v235, v227
	ds_bpermute_b32 v131, v235, v228
	ds_bpermute_b32 v132, v235, v229
	ds_bpermute_b32 v133, v235, v230
	ds_bpermute_b32 v134, v235, v231
	ds_bpermute_b32 v135, v235, v232
	s_waitcnt lgkmcnt(7)
	v_add_f32_e32 v225, v225, v128
	s_waitcnt lgkmcnt(6)
	v_add_f32_e32 v226, v226, v129
	s_waitcnt lgkmcnt(5)
	v_add_f32_e32 v227, v227, v130
	s_waitcnt lgkmcnt(4)
	v_add_f32_e32 v228, v228, v131
	s_waitcnt lgkmcnt(3)
	v_add_f32_e32 v229, v229, v132
	s_waitcnt lgkmcnt(2)
	v_add_f32_e32 v230, v230, v133
	s_waitcnt lgkmcnt(1)
	v_add_f32_e32 v231, v231, v134
	s_waitcnt lgkmcnt(0)
	v_add_f32_e32 v232, v232, v135
	v_lshlrev_b32_e32 v236, 2, v156
	s_add_u32 s90, s76, 0x6500000
	s_addc_u32 s91, s77, 0
	s_add_u32 s76, s76, 0x31a8000
	s_addc_u32 s77, s77, 0
	s_lshl_b32 s83, s26, 6
	s_add_u32 s78, s76, s83
	s_addc_u32 s79, s77, 0
	s_add_u32 s78, s78, 0x20000
	s_addc_u32 s79, s79, 0
	s_mov_b64 s[80:81], exec
	s_mov_b64 exec, 0xffff
	global_atomic_add_f32 v236, v225, s[76:77]
	global_atomic_add_f32 v236, v226, s[76:77] offset:64
	global_atomic_add_f32 v236, v227, s[76:77] offset:128
	global_atomic_add_f32 v236, v228, s[76:77] offset:192
	global_atomic_add_f32 v236, v229, s[76:77] offset:512
	global_atomic_add_f32 v236, v230, s[76:77] offset:576
	global_atomic_add_f32 v236, v231, s[76:77] offset:640
	global_atomic_add_f32 v236, v232, s[76:77] offset:704
	s_mov_b64 exec, s[80:81]
	s_add_u32 s86, s34, 0x1000
	s_addc_u32 s87, s35, 0
	s_add_u32 s88, s86, 0x1000
	s_addc_u32 s89, s87, 0
	s_add_u32 s92, s92, 0x5000
	s_addc_u32 s93, s93, 0
	s_mov_b32 s84, 0xffff0000
	s_mov_b32 s85, 0xffff0000
	s_waitcnt vmcnt(0)
	s_barrier
	v_readfirstlane_b32 s83, v206
	v_mov_b32_e32 v237, 0
	v_mov_b32_e32 v238, 1
	s_cmp_lg_u32 s83, 0
	s_cbranch_scc1 .Lfmf_wait_done
	s_mov_b64 exec, 1
	global_atomic_add v237, v238, s[78:79]
	s_mov_b32 s82, 0
.Lfmf_spin:
	global_load_dword v239, v237, s[78:79] sc1
	s_waitcnt vmcnt(0)
	v_readfirstlane_b32 s83, v239
	s_cmp_ge_u32 s83, 4
	s_cbranch_scc1 .Lfmf_spin_done
	s_sleep 1
	s_add_u32 s82, s82, 1
	s_cmp_lt_u32 s82, 0x4000
	s_cbranch_scc1 .Lfmf_spin

; __device__ __forceinline__ unsigned cvtpk_s(float lo, float hi) { f32x2_t v = {lo, hi}; bf16x2_t b = __builtin_convertvector(v, bf16x2_t); return __builtin_bit_cast(unsigned, b); }
; __device__ __forceinline__ u32x4 quad_swap(unsigned lo0, unsigned lo1, unsigned hi0, unsigned hi1, int fq, int& coloff) {
;     const bool odd = fq & 1;
;     const unsigned s0 = odd ? lo0 : hi0, s1 = odd ? lo1 : hi1;
;     const unsigned r0 = (unsigned)__shfl_xor((int)s0, 16), r1 = (unsigned)__shfl_xor((int)s1, 16);
;     coloff = odd ? 16 + 4 * (fq - 1) : 4 * fq;
;     u32x4 o; o.x = odd ? r0 : lo0; o.y = odd ? r1 : lo1; o.z = odd ? hi0 : r0; o.w = odd ? hi1 : r1; return o;
; }
; __device__ __forceinline__ void modpass(const float* xs_main, const float* xs_ctx, const float* mod_l, const float* g, int i, bf16_t* H, int nrows, int gw, int NGW, int lane) {
;     ...
;         if (cond != cur) { cur = cond; const float* shift = mod_l + cond * 9216 + 3 * i * 1024; const float* scale = shift + 1024;
; #pragma unroll
;             for (int j = 0; j < 2; ++j)
; #pragma unroll
;                 for (int q = 0; q < 2; ++q) { const int c = 8 * lane + 512 * j + 4 * q; gm[j][q] = *(const f32x4*)(g + c) * (*(const f32x4*)(scale + c) + 1.0f); sh[j][q] = *(const f32x4*)(shift + c); } }
;         float ss = 0.f;
; #pragma unroll
;         for (int j = 0; j < 2; ++j)
; #pragma unroll
;             for (int q = 0; q < 2; ++q) ss += (v[j][q][0] * v[j][q][0] + v[j][q][1] * v[j][q][1]) + (v[j][q][2] * v[j][q][2] + v[j][q][3] * v[j][q][3]);
;         const float rstd = 1.0f / sqrtf(wave_sum(ss) * (1.0f / D) + EPS);
; #pragma unroll
;         for (int j = 0; j < 2; ++j) {
;             const f32x4 o0 = v[j][0] * rstd * gm[j][0] + sh[j][0], o1 = v[j][1] * rstd * gm[j][1] + sh[j][1];
;             u32x4 w; w.x = cvtpk_s(o0[0], o0[1]); w.y = cvtpk_s(o0[2], o0[3]); w.z = cvtpk_s(o1[0], o1[1]); w.w = cvtpk_s(o1[2], o1[3]);
;             *(u32x4*)(H + (size_t)row * D + 8 * lane + 512 * j) = w;
.Lfmf_wait_done:
	s_barrier
	global_load_dword v132, v236, s[76:77] sc1
	global_load_dword v133, v236, s[76:77] offset:64 sc1
	global_load_dword v134, v236, s[76:77] offset:128 sc1
	global_load_dword v135, v236, s[76:77] offset:192 sc1
	global_load_dword v136, v236, s[76:77] offset:512 sc1
	global_load_dword v137, v236, s[76:77] offset:576 sc1
	global_load_dword v138, v236, s[76:77] offset:640 sc1
	global_load_dword v139, v236, s[76:77] offset:704 sc1
	global_load_dwordx4 v[196:199], v200, s[86:87]
	global_load_dwordx4 v[208:211], v200, s[86:87] offset:64
	global_load_dwordx4 v[212:215], v200, s[86:87] offset:512
	global_load_dwordx4 v[216:219], v200, s[86:87] offset:576
	global_load_dwordx4 v[140:143], v200, s[88:89]
	global_load_dwordx4 v[164:167], v200, s[88:89] offset:64
	global_load_dwordx4 v[168:171], v200, s[88:89] offset:512
	global_load_dwordx4 v[172:175], v200, s[88:89] offset:576
	global_load_dwordx4 v[176:179], v200, s[92:93]
	global_load_dwordx4 v[180:183], v200, s[92:93] offset:64
	global_load_dwordx4 v[184:187], v200, s[92:93] offset:512
	global_load_dwordx4 v[188:191], v200, s[92:93] offset:576
	v_mov_b32_e32 v233, 12
	v_cndmask_b32_e64 v233, 0, v233, s[84:85]
	v_add_u32_e32 v233, v233, v157
	v_lshlrev_b32_e32 v233, 1, v233
	v_lshl_add_u32 v240, v156, 11, v233
	v_mov_b32_e32 v233, 0x358637bd
	s_waitcnt vmcnt(0)
	v_fmamk_f32 v132, v132, 0x3a800000, v233
	v_fmamk_f32 v133, v133, 0x3a800000, v233
	v_fmamk_f32 v134, v134, 0x3a800000, v233
	v_fmamk_f32 v135, v135, 0x3a800000, v233
	v_fmamk_f32 v136, v136, 0x3a800000, v233
	v_fmamk_f32 v137, v137, 0x3a800000, v233
	v_fmamk_f32 v138, v138, 0x3a800000, v233
	v_fmamk_f32 v139, v139, 0x3a800000, v233
	v_rsq_f32_e32 v132, v132
	v_rsq_f32_e32 v133, v133
	v_rsq_f32_e32 v134, v134
	v_rsq_f32_e32 v135, v135
	v_rsq_f32_e32 v136, v136
	v_rsq_f32_e32 v137, v137
	v_rsq_f32_e32 v138, v138
	v_rsq_f32_e32 v139, v139
	v_pk_add_f32 v[140:141], v[140:141], 1.0 op_sel_hi:[1,0]
	v_pk_mul_f32 v[140:141], v[176:177], v[140:141]
	v_pk_add_f32 v[142:143], v[142:143], 1.0 op_sel_hi:[1,0]
	v_pk_mul_f32 v[142:143], v[178:179], v[142:143]
	v_pk_add_f32 v[164:165], v[164:165], 1.0 op_sel_hi:[1,0]
	v_pk_mul_f32 v[164:165], v[180:181], v[164:165]
	v_pk_add_f32 v[166:167], v[166:167], 1.0 op_sel_hi:[1,0]
	v_pk_mul_f32 v[166:167], v[182:183], v[166:167]
	v_pk_add_f32 v[168:169], v[168:169], 1.0 op_sel_hi:[1,0]
	v_pk_mul_f32 v[168:169], v[184:185], v[168:169]
	v_pk_add_f32 v[170:171], v[170:171], 1.0 op_sel_hi:[1,0]
	v_pk_mul_f32 v[170:171], v[186:187], v[170:171]
	v_pk_add_f32 v[172:173], v[172:173], 1.0 op_sel_hi:[1,0]
	v_pk_mul_f32 v[172:173], v[188:189], v[172:173]
	v_pk_add_f32 v[174:175], v[174:175], 1.0 op_sel_hi:[1,0]
	v_pk_mul_f32 v[174:175], v[190:191], v[174:175]
	v_mul_f32_e32 v124, v124, v132
	v_mul_f32_e32 v125, v125, v132
	v_pk_fma_f32 v[124:125], v[140:141], v[124:125], v[196:197]
	v_mul_f32_e32 v126, v126, v132
	v_mul_f32_e32 v127, v127, v132
	v_pk_fma_f32 v[126:127], v[142:143], v[126:127], v[198:199]
	v_cvt_pk_bf16_f32 v184, v124, v125
	v_cvt_pk_bf16_f32 v185, v126, v127
	v_mul_f32_e32 v120, v120, v132
	v_mul_f32_e32 v121, v121, v132
	v_pk_fma_f32 v[120:121], v[164:165], v[120:121], v[208:209]
	v_mul_f32_e32 v122, v122, v132
	v_mul_f32_e32 v123, v123, v132
	v_pk_fma_f32 v[122:123], v[166:167], v[122:123], v[210:211]
	v_cvt_pk_bf16_f32 v186, v120, v121
	v_cvt_pk_bf16_f32 v187, v122, v123
	v_mul_f32_e32 v116, v116, v132
	v_mul_f32_e32 v117, v117, v132
	v_pk_fma_f32 v[116:117], v[168:169], v[116:117], v[212:213]
	v_mul_f32_e32 v118, v118, v132
	v_mul_f32_e32 v119, v119, v132
	v_pk_fma_f32 v[118:119], v[170:171], v[118:119], v[214:215]
	v_cvt_pk_bf16_f32 v188, v116, v117
	v_cvt_pk_bf16_f32 v189, v118, v119
	v_mul_f32_e32 v112, v112, v132
	v_mul_f32_e32 v113, v113, v132
	v_pk_fma_f32 v[112:113], v[172:173], v[112:113], v[216:217]
	v_mul_f32_e32 v114, v114, v132
	v_mul_f32_e32 v115, v115, v132
	v_pk_fma_f32 v[114:115], v[174:175], v[114:115], v[218:219]
	v_cvt_pk_bf16_f32 v190, v112, v113
	v_cvt_pk_bf16_f32 v191, v114, v115
	v_mov_b32_e32 v233, v240
	v_cndmask_b32_e64 v192, v186, v184, s[84:85]
	v_cndmask_b32_e64 v193, v187, v185, s[84:85]
	ds_bpermute_b32 v194, v234, v192
	ds_bpermute_b32 v195, v234, v193
	s_waitcnt lgkmcnt(0)
	v_cndmask_b32_e64 v176, v184, v194, s[84:85]
	v_cndmask_b32_e64 v177, v185, v195, s[84:85]
	v_cndmask_b32_e64 v178, v194, v186, s[84:85]
	v_cndmask_b32_e64 v179, v195, v187, s[84:85]
	global_store_dwordx4 v233, v[176:179], s[90:91]
	v_cndmask_b32_e64 v192, v190, v188, s[84:85]
	v_cndmask_b32_e64 v193, v191, v189, s[84:85]
	ds_bpermute_b32 v194, v234, v192
	ds_bpermute_b32 v195, v234, v193
	s_waitcnt lgkmcnt(0)
	v_cndmask_b32_e64 v180, v188, v194, s[84:85]
	v_cndmask_b32_e64 v181, v189, v195, s[84:85]
	v_cndmask_b32_e64 v182, v194, v190, s[84:85]
	v_cndmask_b32_e64 v183, v195, v191, s[84:85]
	global_store_dwordx4 v233, v[180:183], s[90:91] offset:256
	v_mul_f32_e32 v108, v108, v133
	v_mul_f32_e32 v109, v109, v133
	v_pk_fma_f32 v[108:109], v[140:141], v[108:109], v[196:197]
	v_mul_f32_e32 v110, v110, v133
	v_mul_f32_e32 v111, v111, v133
	v_pk_fma_f32 v[110:111], v[142:143], v[110:111], v[198:199]
	v_cvt_pk_bf16_f32 v184, v108, v109
	v_cvt_pk_bf16_f32 v185, v110, v111
	v_mul_f32_e32 v104, v104, v133
	v_mul_f32_e32 v105, v105, v133
	v_pk_fma_f32 v[104:105], v[164:165], v[104:105], v[208:209]
	v_mul_f32_e32 v106, v106, v133
	v_mul_f32_e32 v107, v107, v133
	v_pk_fma_f32 v[106:107], v[166:167], v[106:107], v[210:211]
	v_cvt_pk_bf16_f32 v186, v104, v105
	v_cvt_pk_bf16_f32 v187, v106, v107
	v_mul_f32_e32 v100, v100, v133
	v_mul_f32_e32 v101, v101, v133
	v_pk_fma_f32 v[100:101], v[168:169], v[100:101], v[212:213]
	v_mul_f32_e32 v102, v102, v133
	v_mul_f32_e32 v103, v103, v133
	v_pk_fma_f32 v[102:103], v[170:171], v[102:103], v[214:215]
	v_cvt_pk_bf16_f32 v188, v100, v101
	v_cvt_pk_bf16_f32 v189, v102, v103
	v_mul_f32_e32 v96, v96, v133
	v_mul_f32_e32 v97, v97, v133
	v_pk_fma_f32 v[96:97], v[172:173], v[96:97], v[216:217]
	v_mul_f32_e32 v98, v98, v133
	v_mul_f32_e32 v99, v99, v133
	v_pk_fma_f32 v[98:99], v[174:175], v[98:99], v[218:219]
	v_cvt_pk_bf16_f32 v190, v96, v97
	v_cvt_pk_bf16_f32 v191, v98, v99
	v_add_u32_e32 v233, 0x8000, v240
	v_cndmask_b32_e64 v192, v186, v184, s[84:85]
	v_cndmask_b32_e64 v193, v187, v185, s[84:85]
	ds_bpermute_b32 v194, v234, v192
	ds_bpermute_b32 v195, v234, v193
	s_waitcnt lgkmcnt(0)
; __device__ __forceinline__ unsigned cvtpk_s(float lo, float hi) { f32x2_t v = {lo, hi}; bf16x2_t b = __builtin_convertvector(v, bf16x2_t); return __builtin_bit_cast(unsigned, b); }
; __device__ __forceinline__ u32x4 quad_swap(unsigned lo0, unsigned lo1, unsigned hi0, unsigned hi1, int fq, int& coloff) {
;     const bool odd = fq & 1;
;     const unsigned s0 = odd ? lo0 : hi0, s1 = odd ? lo1 : hi1;
;     const unsigned r0 = (unsigned)__shfl_xor((int)s0, 16), r1 = (unsigned)__shfl_xor((int)s1, 16);
;     coloff = odd ? 16 + 4 * (fq - 1) : 4 * fq;
;     u32x4 o; o.x = odd ? r0 : lo0; o.y = odd ? r1 : lo1; o.z = odd ? hi0 : r0; o.w = odd ? hi1 : r1; return o;
; }
; __device__ __forceinline__ void modpass(const float* xs_main, const float* xs_ctx, const float* mod_l, const float* g, int i, bf16_t* H, int nrows, int gw, int NGW, int lane) {
;     ...
;         for (int j = 0; j < 2; ++j) {
;             const f32x4 o0 = v[j][0] * rstd * gm[j][0] + sh[j][0], o1 = v[j][1] * rstd * gm[j][1] + sh[j][1];
;             u32x4 w; w.x = cvtpk_s(o0[0], o0[1]); w.y = cvtpk_s(o0[2], o0[3]); w.z = cvtpk_s(o1[0], o1[1]); w.w = cvtpk_s(o1[2], o1[3]);
;             *(u32x4*)(H + (size_t)row * D + 8 * lane + 512 * j) = w;
	v_cndmask_b32_e64 v176, v184, v194, s[84:85]
	v_cndmask_b32_e64 v177, v185, v195, s[84:85]
	v_cndmask_b32_e64 v178, v194, v186, s[84:85]
	v_cndmask_b32_e64 v179, v195, v187, s[84:85]
	global_store_dwordx4 v233, v[176:179], s[90:91]
	v_cndmask_b32_e64 v192, v190, v188, s[84:85]
	v_cndmask_b32_e64 v193, v191, v189, s[84:85]
	ds_bpermute_b32 v194, v234, v192
	ds_bpermute_b32 v195, v234, v193
	s_waitcnt lgkmcnt(0)
	v_cndmask_b32_e64 v180, v188, v194, s[84:85]
	v_cndmask_b32_e64 v181, v189, v195, s[84:85]
	v_cndmask_b32_e64 v182, v194, v190, s[84:85]
	v_cndmask_b32_e64 v183, v195, v191, s[84:85]
	global_store_dwordx4 v233, v[180:183], s[90:91] offset:256
	v_mul_f32_e32 v92, v92, v134
	v_mul_f32_e32 v93, v93, v134
	v_pk_fma_f32 v[92:93], v[140:141], v[92:93], v[196:197]
	v_mul_f32_e32 v94, v94, v134
	v_mul_f32_e32 v95, v95, v134
	v_pk_fma_f32 v[94:95], v[142:143], v[94:95], v[198:199]
	v_cvt_pk_bf16_f32 v184, v92, v93
	v_cvt_pk_bf16_f32 v185, v94, v95
	v_mul_f32_e32 v88, v88, v134
	v_mul_f32_e32 v89, v89, v134
	v_pk_fma_f32 v[88:89], v[164:165], v[88:89], v[208:209]
	v_mul_f32_e32 v90, v90, v134
	v_mul_f32_e32 v91, v91, v134
	v_pk_fma_f32 v[90:91], v[166:167], v[90:91], v[210:211]
	v_cvt_pk_bf16_f32 v186, v88, v89
	v_cvt_pk_bf16_f32 v187, v90, v91
	v_mul_f32_e32 v84, v84, v134
	v_mul_f32_e32 v85, v85, v134
	v_pk_fma_f32 v[84:85], v[168:169], v[84:85], v[212:213]
	v_mul_f32_e32 v86, v86, v134
	v_mul_f32_e32 v87, v87, v134
	v_pk_fma_f32 v[86:87], v[170:171], v[86:87], v[214:215]
	v_cvt_pk_bf16_f32 v188, v84, v85
	v_cvt_pk_bf16_f32 v189, v86, v87
	v_mul_f32_e32 v80, v80, v134
	v_mul_f32_e32 v81, v81, v134
	v_pk_fma_f32 v[80:81], v[172:173], v[80:81], v[216:217]
	v_mul_f32_e32 v82, v82, v134
	v_mul_f32_e32 v83, v83, v134
	v_pk_fma_f32 v[82:83], v[174:175], v[82:83], v[218:219]
	v_cvt_pk_bf16_f32 v190, v80, v81
	v_cvt_pk_bf16_f32 v191, v82, v83
	v_add_u32_e32 v233, 0x10000, v240
	v_cndmask_b32_e64 v192, v186, v184, s[84:85]
	v_cndmask_b32_e64 v193, v187, v185, s[84:85]
	ds_bpermute_b32 v194, v234, v192
	ds_bpermute_b32 v195, v234, v193
	s_waitcnt lgkmcnt(0)
	v_cndmask_b32_e64 v176, v184, v194, s[84:85]
	v_cndmask_b32_e64 v177, v185, v195, s[84:85]
	v_cndmask_b32_e64 v178, v194, v186, s[84:85]
	v_cndmask_b32_e64 v179, v195, v187, s[84:85]
	global_store_dwordx4 v233, v[176:179], s[90:91]
	v_cndmask_b32_e64 v192, v190, v188, s[84:85]
	v_cndmask_b32_e64 v193, v191, v189, s[84:85]
	ds_bpermute_b32 v194, v234, v192
	ds_bpermute_b32 v195, v234, v193
	s_waitcnt lgkmcnt(0)
	v_cndmask_b32_e64 v180, v188, v194, s[84:85]
	v_cndmask_b32_e64 v181, v189, v195, s[84:85]
	v_cndmask_b32_e64 v182, v194, v190, s[84:85]
	v_cndmask_b32_e64 v183, v195, v191, s[84:85]
	global_store_dwordx4 v233, v[180:183], s[90:91] offset:256
	v_mul_f32_e32 v76, v76, v135
	v_mul_f32_e32 v77, v77, v135
	v_pk_fma_f32 v[76:77], v[140:141], v[76:77], v[196:197]
	v_mul_f32_e32 v78, v78, v135
	v_mul_f32_e32 v79, v79, v135
	v_pk_fma_f32 v[78:79], v[142:143], v[78:79], v[198:199]
	v_cvt_pk_bf16_f32 v184, v76, v77
	v_cvt_pk_bf16_f32 v185, v78, v79
	v_mul_f32_e32 v72, v72, v135
	v_mul_f32_e32 v73, v73, v135
	v_pk_fma_f32 v[72:73], v[164:165], v[72:73], v[208:209]
	v_mul_f32_e32 v74, v74, v135
	v_mul_f32_e32 v75, v75, v135
	v_pk_fma_f32 v[74:75], v[166:167], v[74:75], v[210:211]
	v_cvt_pk_bf16_f32 v186, v72, v73
	v_cvt_pk_bf16_f32 v187, v74, v75
	v_mul_f32_e32 v68, v68, v135
	v_mul_f32_e32 v69, v69, v135
	v_pk_fma_f32 v[68:69], v[168:169], v[68:69], v[212:213]
	v_mul_f32_e32 v70, v70, v135
	v_mul_f32_e32 v71, v71, v135
	v_pk_fma_f32 v[70:71], v[170:171], v[70:71], v[214:215]
	v_cvt_pk_bf16_f32 v188, v68, v69
	v_cvt_pk_bf16_f32 v189, v70, v71
	v_mul_f32_e32 v64, v64, v135
	v_mul_f32_e32 v65, v65, v135
	v_pk_fma_f32 v[64:65], v[172:173], v[64:65], v[216:217]
	v_mul_f32_e32 v66, v66, v135
	v_mul_f32_e32 v67, v67, v135
	v_pk_fma_f32 v[66:67], v[174:175], v[66:67], v[218:219]
	v_cvt_pk_bf16_f32 v190, v64, v65
	v_cvt_pk_bf16_f32 v191, v66, v67
	v_add_u32_e32 v233, 0x18000, v240
	v_cndmask_b32_e64 v192, v186, v184, s[84:85]
	v_cndmask_b32_e64 v193, v187, v185, s[84:85]
	ds_bpermute_b32 v194, v234, v192
	ds_bpermute_b32 v195, v234, v193
	s_waitcnt lgkmcnt(0)
	v_cndmask_b32_e64 v176, v184, v194, s[84:85]
	v_cndmask_b32_e64 v177, v185, v195, s[84:85]
	v_cndmask_b32_e64 v178, v194, v186, s[84:85]
	v_cndmask_b32_e64 v179, v195, v187, s[84:85]
	global_store_dwordx4 v233, v[176:179], s[90:91]
	v_cndmask_b32_e64 v192, v190, v188, s[84:85]
	v_cndmask_b32_e64 v193, v191, v189, s[84:85]
	ds_bpermute_b32 v194, v234, v192
	ds_bpermute_b32 v195, v234, v193
	s_waitcnt lgkmcnt(0)
	v_cndmask_b32_e64 v180, v188, v194, s[84:85]
	v_cndmask_b32_e64 v181, v189, v195, s[84:85]
	v_cndmask_b32_e64 v182, v194, v190, s[84:85]
	v_cndmask_b32_e64 v183, v195, v191, s[84:85]
	global_store_dwordx4 v233, v[180:183], s[90:91] offset:256
	v_mul_f32_e32 v60, v60, v136
	v_mul_f32_e32 v61, v61, v136
	v_pk_fma_f32 v[60:61], v[140:141], v[60:61], v[196:197]
	v_mul_f32_e32 v62, v62, v136
	v_mul_f32_e32 v63, v63, v136
	v_pk_fma_f32 v[62:63], v[142:143], v[62:63], v[198:199]
	v_cvt_pk_bf16_f32 v184, v60, v61
	v_cvt_pk_bf16_f32 v185, v62, v63
	v_mul_f32_e32 v56, v56, v136
	v_mul_f32_e32 v57, v57, v136
	v_pk_fma_f32 v[56:57], v[164:165], v[56:57], v[208:209]
	v_mul_f32_e32 v58, v58, v136
	v_mul_f32_e32 v59, v59, v136
	v_pk_fma_f32 v[58:59], v[166:167], v[58:59], v[210:211]
	v_cvt_pk_bf16_f32 v186, v56, v57
	v_cvt_pk_bf16_f32 v187, v58, v59
	v_mul_f32_e32 v52, v52, v136
	v_mul_f32_e32 v53, v53, v136
	v_pk_fma_f32 v[52:53], v[168:169], v[52:53], v[212:213]
	v_mul_f32_e32 v54, v54, v136
	v_mul_f32_e32 v55, v55, v136
	v_pk_fma_f32 v[54:55], v[170:171], v[54:55], v[214:215]
	v_cvt_pk_bf16_f32 v188, v52, v53
	v_cvt_pk_bf16_f32 v189, v54, v55
	v_mul_f32_e32 v48, v48, v136
	v_mul_f32_e32 v49, v49, v136
	v_pk_fma_f32 v[48:49], v[172:173], v[48:49], v[216:217]
	v_mul_f32_e32 v50, v50, v136
	v_mul_f32_e32 v51, v51, v136
	v_pk_fma_f32 v[50:51], v[174:175], v[50:51], v[218:219]
	v_cvt_pk_bf16_f32 v190, v48, v49
	v_cvt_pk_bf16_f32 v191, v50, v51
	v_add_u32_e32 v233, 0x40000, v240
	v_cndmask_b32_e64 v192, v186, v184, s[84:85]
	v_cndmask_b32_e64 v193, v187, v185, s[84:85]
	ds_bpermute_b32 v194, v234, v192
	ds_bpermute_b32 v195, v234, v193
	s_waitcnt lgkmcnt(0)
; __device__ __forceinline__ unsigned cvtpk_s(float lo, float hi) { f32x2_t v = {lo, hi}; bf16x2_t b = __builtin_convertvector(v, bf16x2_t); return __builtin_bit_cast(unsigned, b); }
; __device__ __forceinline__ u32x4 quad_swap(unsigned lo0, unsigned lo1, unsigned hi0, unsigned hi1, int fq, int& coloff) {
;     const bool odd = fq & 1;
;     const unsigned s0 = odd ? lo0 : hi0, s1 = odd ? lo1 : hi1;
;     const unsigned r0 = (unsigned)__shfl_xor((int)s0, 16), r1 = (unsigned)__shfl_xor((int)s1, 16);
;     coloff = odd ? 16 + 4 * (fq - 1) : 4 * fq;
;     u32x4 o; o.x = odd ? r0 : lo0; o.y = odd ? r1 : lo1; o.z = odd ? hi0 : r0; o.w = odd ? hi1 : r1; return o;
; }
; __device__ __forceinline__ void modpass(const float* xs_main, const float* xs_ctx, const float* mod_l, const float* g, int i, bf16_t* H, int nrows, int gw, int NGW, int lane) {
;     ...
;         for (int j = 0; j < 2; ++j) {
;             const f32x4 o0 = v[j][0] * rstd * gm[j][0] + sh[j][0], o1 = v[j][1] * rstd * gm[j][1] + sh[j][1];
;             u32x4 w; w.x = cvtpk_s(o0[0], o0[1]); w.y = cvtpk_s(o0[2], o0[3]); w.z = cvtpk_s(o1[0], o1[1]); w.w = cvtpk_s(o1[2], o1[3]);
;             *(u32x4*)(H + (size_t)row * D + 8 * lane + 512 * j) = w;
	v_cndmask_b32_e64 v176, v184, v194, s[84:85]
	v_cndmask_b32_e64 v177, v185, v195, s[84:85]
	v_cndmask_b32_e64 v178, v194, v186, s[84:85]
	v_cndmask_b32_e64 v179, v195, v187, s[84:85]
	global_store_dwordx4 v233, v[176:179], s[90:91]
	v_cndmask_b32_e64 v192, v190, v188, s[84:85]
	v_cndmask_b32_e64 v193, v191, v189, s[84:85]
	ds_bpermute_b32 v194, v234, v192
	ds_bpermute_b32 v195, v234, v193
	s_waitcnt lgkmcnt(0)
	v_cndmask_b32_e64 v180, v188, v194, s[84:85]
	v_cndmask_b32_e64 v181, v189, v195, s[84:85]
	v_cndmask_b32_e64 v182, v194, v190, s[84:85]
	v_cndmask_b32_e64 v183, v195, v191, s[84:85]
	global_store_dwordx4 v233, v[180:183], s[90:91] offset:256
	v_mul_f32_e32 v44, v44, v137
	v_mul_f32_e32 v45, v45, v137
	v_pk_fma_f32 v[44:45], v[140:141], v[44:45], v[196:197]
	v_mul_f32_e32 v46, v46, v137
	v_mul_f32_e32 v47, v47, v137
	v_pk_fma_f32 v[46:47], v[142:143], v[46:47], v[198:199]
	v_cvt_pk_bf16_f32 v184, v44, v45
	v_cvt_pk_bf16_f32 v185, v46, v47
	v_mul_f32_e32 v40, v40, v137
	v_mul_f32_e32 v41, v41, v137
	v_pk_fma_f32 v[40:41], v[164:165], v[40:41], v[208:209]
	v_mul_f32_e32 v42, v42, v137
	v_mul_f32_e32 v43, v43, v137
	v_pk_fma_f32 v[42:43], v[166:167], v[42:43], v[210:211]
	v_cvt_pk_bf16_f32 v186, v40, v41
	v_cvt_pk_bf16_f32 v187, v42, v43
	v_mul_f32_e32 v36, v36, v137
	v_mul_f32_e32 v37, v37, v137
	v_pk_fma_f32 v[36:37], v[168:169], v[36:37], v[212:213]
	v_mul_f32_e32 v38, v38, v137
	v_mul_f32_e32 v39, v39, v137
	v_pk_fma_f32 v[38:39], v[170:171], v[38:39], v[214:215]
	v_cvt_pk_bf16_f32 v188, v36, v37
	v_cvt_pk_bf16_f32 v189, v38, v39
	v_mul_f32_e32 v32, v32, v137
	v_mul_f32_e32 v33, v33, v137
	v_pk_fma_f32 v[32:33], v[172:173], v[32:33], v[216:217]
	v_mul_f32_e32 v34, v34, v137
	v_mul_f32_e32 v35, v35, v137
	v_pk_fma_f32 v[34:35], v[174:175], v[34:35], v[218:219]
	v_cvt_pk_bf16_f32 v190, v32, v33
	v_cvt_pk_bf16_f32 v191, v34, v35
	v_add_u32_e32 v233, 0x48000, v240
	v_cndmask_b32_e64 v192, v186, v184, s[84:85]
	v_cndmask_b32_e64 v193, v187, v185, s[84:85]
	ds_bpermute_b32 v194, v234, v192
	ds_bpermute_b32 v195, v234, v193
	s_waitcnt lgkmcnt(0)
	v_cndmask_b32_e64 v176, v184, v194, s[84:85]
	v_cndmask_b32_e64 v177, v185, v195, s[84:85]
	v_cndmask_b32_e64 v178, v194, v186, s[84:85]
	v_cndmask_b32_e64 v179, v195, v187, s[84:85]
	global_store_dwordx4 v233, v[176:179], s[90:91]
	v_cndmask_b32_e64 v192, v190, v188, s[84:85]
	v_cndmask_b32_e64 v193, v191, v189, s[84:85]
	ds_bpermute_b32 v194, v234, v192
	ds_bpermute_b32 v195, v234, v193
	s_waitcnt lgkmcnt(0)
	v_cndmask_b32_e64 v180, v188, v194, s[84:85]
	v_cndmask_b32_e64 v181, v189, v195, s[84:85]
	v_cndmask_b32_e64 v182, v194, v190, s[84:85]
	v_cndmask_b32_e64 v183, v195, v191, s[84:85]
	global_store_dwordx4 v233, v[180:183], s[90:91] offset:256
	v_mul_f32_e32 v28, v28, v138
	v_mul_f32_e32 v29, v29, v138
	v_pk_fma_f32 v[28:29], v[140:141], v[28:29], v[196:197]
	v_mul_f32_e32 v30, v30, v138
	v_mul_f32_e32 v31, v31, v138
	v_pk_fma_f32 v[30:31], v[142:143], v[30:31], v[198:199]
	v_cvt_pk_bf16_f32 v184, v28, v29
	v_cvt_pk_bf16_f32 v185, v30, v31
	v_mul_f32_e32 v24, v24, v138
	v_mul_f32_e32 v25, v25, v138
	v_pk_fma_f32 v[24:25], v[164:165], v[24:25], v[208:209]
	v_mul_f32_e32 v26, v26, v138
	v_mul_f32_e32 v27, v27, v138
	v_pk_fma_f32 v[26:27], v[166:167], v[26:27], v[210:211]
	v_cvt_pk_bf16_f32 v186, v24, v25
	v_cvt_pk_bf16_f32 v187, v26, v27
	v_mul_f32_e32 v20, v20, v138
	v_mul_f32_e32 v21, v21, v138
	v_pk_fma_f32 v[20:21], v[168:169], v[20:21], v[212:213]
	v_mul_f32_e32 v22, v22, v138
	v_mul_f32_e32 v23, v23, v138
	v_pk_fma_f32 v[22:23], v[170:171], v[22:23], v[214:215]
	v_cvt_pk_bf16_f32 v188, v20, v21
	v_cvt_pk_bf16_f32 v189, v22, v23
	v_mul_f32_e32 v16, v16, v138
	v_mul_f32_e32 v17, v17, v138
	v_pk_fma_f32 v[16:17], v[172:173], v[16:17], v[216:217]
	v_mul_f32_e32 v18, v18, v138
	v_mul_f32_e32 v19, v19, v138
	v_pk_fma_f32 v[18:19], v[174:175], v[18:19], v[218:219]
	v_cvt_pk_bf16_f32 v190, v16, v17
	v_cvt_pk_bf16_f32 v191, v18, v19
	v_add_u32_e32 v233, 0x50000, v240
	v_cndmask_b32_e64 v192, v186, v184, s[84:85]
	v_cndmask_b32_e64 v193, v187, v185, s[84:85]
	ds_bpermute_b32 v194, v234, v192
	ds_bpermute_b32 v195, v234, v193
	s_waitcnt lgkmcnt(0)
	v_cndmask_b32_e64 v176, v184, v194, s[84:85]
	v_cndmask_b32_e64 v177, v185, v195, s[84:85]
	v_cndmask_b32_e64 v178, v194, v186, s[84:85]
	v_cndmask_b32_e64 v179, v195, v187, s[84:85]
	global_store_dwordx4 v233, v[176:179], s[90:91]
	v_cndmask_b32_e64 v192, v190, v188, s[84:85]
	v_cndmask_b32_e64 v193, v191, v189, s[84:85]
	ds_bpermute_b32 v194, v234, v192
	ds_bpermute_b32 v195, v234, v193
	s_waitcnt lgkmcnt(0)
	v_cndmask_b32_e64 v180, v188, v194, s[84:85]
	v_cndmask_b32_e64 v181, v189, v195, s[84:85]
	v_cndmask_b32_e64 v182, v194, v190, s[84:85]
	v_cndmask_b32_e64 v183, v195, v191, s[84:85]
	global_store_dwordx4 v233, v[180:183], s[90:91] offset:256
	v_mul_f32_e32 v12, v12, v139
	v_mul_f32_e32 v13, v13, v139
	v_pk_fma_f32 v[12:13], v[140:141], v[12:13], v[196:197]
	v_mul_f32_e32 v14, v14, v139
	v_mul_f32_e32 v15, v15, v139
	v_pk_fma_f32 v[14:15], v[142:143], v[14:15], v[198:199]
	v_cvt_pk_bf16_f32 v184, v12, v13
	v_cvt_pk_bf16_f32 v185, v14, v15
	v_mul_f32_e32 v8, v8, v139
	v_mul_f32_e32 v9, v9, v139
	v_pk_fma_f32 v[8:9], v[164:165], v[8:9], v[208:209]
	v_mul_f32_e32 v10, v10, v139
	v_mul_f32_e32 v11, v11, v139
	v_pk_fma_f32 v[10:11], v[166:167], v[10:11], v[210:211]
	v_cvt_pk_bf16_f32 v186, v8, v9
	v_cvt_pk_bf16_f32 v187, v10, v11
	v_mul_f32_e32 v4, v4, v139
	v_mul_f32_e32 v5, v5, v139
	v_pk_fma_f32 v[4:5], v[168:169], v[4:5], v[212:213]
	v_mul_f32_e32 v6, v6, v139
	v_mul_f32_e32 v7, v7, v139
	v_pk_fma_f32 v[6:7], v[170:171], v[6:7], v[214:215]
	v_cvt_pk_bf16_f32 v188, v4, v5
	v_cvt_pk_bf16_f32 v189, v6, v7
	v_mul_f32_e32 v0, v0, v139
	v_mul_f32_e32 v1, v1, v139
	v_pk_fma_f32 v[0:1], v[172:173], v[0:1], v[216:217]
	v_mul_f32_e32 v2, v2, v139
	v_mul_f32_e32 v3, v3, v139
	v_pk_fma_f32 v[2:3], v[174:175], v[2:3], v[218:219]
	v_cvt_pk_bf16_f32 v190, v0, v1
	v_cvt_pk_bf16_f32 v191, v2, v3
	v_add_u32_e32 v233, 0x58000, v240
	v_cndmask_b32_e64 v192, v186, v184, s[84:85]
	v_cndmask_b32_e64 v193, v187, v185, s[84:85]
	ds_bpermute_b32 v194, v234, v192
	ds_bpermute_b32 v195, v234, v193
	s_waitcnt lgkmcnt(0)
	v_cndmask_b32_e64 v176, v184, v194, s[84:85]
	v_cndmask_b32_e64 v177, v185, v195, s[84:85]
	v_cndmask_b32_e64 v178, v194, v186, s[84:85]
	v_cndmask_b32_e64 v179, v195, v187, s[84:85]
	global_store_dwordx4 v233, v[176:179], s[90:91]
	v_cndmask_b32_e64 v192, v190, v188, s[84:85]
	v_cndmask_b32_e64 v193, v191, v189, s[84:85]
	ds_bpermute_b32 v194, v234, v192
	ds_bpermute_b32 v195, v234, v193
	s_waitcnt lgkmcnt(0)
	v_cndmask_b32_e64 v180, v188, v194, s[84:85]
	v_cndmask_b32_e64 v181, v189, v195, s[84:85]
	v_cndmask_b32_e64 v182, v194, v190, s[84:85]
	v_cndmask_b32_e64 v183, v195, v191, s[84:85]
	global_store_dwordx4 v233, v[180:183], s[90:91] offset:256
	s_andn2_b64 vcc, exec, s[6:7]
	s_mov_b64 s[6:7], -1
	s_cbranch_vccnz .LBB0_2326
	s_andn2_b64 vcc, exec, s[10:11]
	s_cbranch_vccnz .LBB0_2325
	s_barrier
	s_branch .LBB0_2325

; __device__ __forceinline__ unsigned xb_ld(unsigned* p)              { return __hip_atomic_load(p, __ATOMIC_RELAXED, __HIP_MEMORY_SCOPE_AGENT); }
; __device__ __forceinline__ unsigned xb_add(unsigned* p, unsigned v) { return __hip_atomic_fetch_add(p, v, __ATOMIC_RELAXED, __HIP_MEMORY_SCOPE_AGENT); }
; #define XB_SPIN(cond, bar) do { unsigned _sp = 0; while (cond) { __builtin_amdgcn_s_sleep(1); \
;     if ((++_sp & 255u) == 0u) { if (xb_ld(&(bar)[XB_TMO])) break; if (_sp > XB_SPIN_CAP) { atomicAdd(&(bar)[XB_TMO], 1u); break; } } } } while (0)
; __device__ __forceinline__ void xcd_barrier(const XcdBarrier& b) {
;     asm volatile("s_waitcnt vmcnt(0)" ::: "memory");
;     __syncthreads();
;     if (threadIdx.x == 0) {
;         unsigned* bar = b.bar;
;         __builtin_amdgcn_s_waitcnt(0);
;         unsigned nloc = b.st[0], nx = b.st[1];
;         if (nloc == 0u) { xcd_barrier_complete(bar, b.x, nloc, nx); b.st[0] = nloc; b.st[1] = nx; }
;         const unsigned old = xb_add(&bar[XB_XSUB(b.x)], 1u);
;         const unsigned gen = old / nloc;
;         if (old + 1u == (gen + 1u) * nloc) {
;             __builtin_amdgcn_fence(__ATOMIC_RELEASE, "agent");
;             asm volatile("s_waitcnt vmcnt(0)" ::: "memory");
;             const unsigned og = xb_add(&bar[XB_TOP], 1u);
;             const unsigned tg = og / nx;
;             if (og + 1u == (tg + 1u) * nx) xb_add(&bar[XB_TOPGEN], 1u);
;             else XB_SPIN(xb_ld(&bar[XB_TOPGEN]) == tg, bar);
;             __builtin_amdgcn_fence(__ATOMIC_ACQUIRE, "agent");
;             xb_add(&bar[XB_XGEN(b.x)], 1u);
;             asm volatile("s_waitcnt vmcnt(0)" ::: "memory");
;         } else {
;             XB_SPIN(xb_ld(&bar[XB_XGEN(b.x)]) == gen, bar);
;             __builtin_amdgcn_fence(__ATOMIC_ACQUIRE, "agent");
;             asm volatile("s_waitcnt vmcnt(0)" ::: "memory");
;         }
;     }
;     __syncthreads();
; }
.LBB0_2341:
.LBB0_2400:
	s_mov_b64 s[8:9], s[0:1]
	s_getreg_b32 s10, hwreg(HW_REG_XCC_ID, 0, 4)
	s_waitcnt vmcnt(0)
	s_barrier
	s_and_saveexec_b64 s[6:7], s[24:25]
	s_cbranch_execz .LBB0_2452
	s_add_i32 s11, 0, 0x27fc0
	v_mov_b32_e32 v0, s11
	s_load_dwordx2 s[8:9], s[8:9], 0xb8
	s_waitcnt vmcnt(0) expcnt(0) lgkmcnt(0)
	ds_read_b32 v2, v0
	s_add_i32 s11, 0, 0x27fc4
	v_mov_b32_e32 v0, s11
	ds_read_b32 v0, v0
	s_and_b32 s29, s10, 15
	s_waitcnt lgkmcnt(1)
	v_cmp_ne_u32_e32 vcc, 0, v2
	s_cbranch_vccnz .LBB0_2416
	v_readlane_b32 s10, v252, 0
	v_readlane_b32 s11, v252, 1
	s_load_dword s10, s[10:11], 0x14
	s_mov_b32 s34, 1
	v_mov_b32_e32 v16, 0
	s_waitcnt lgkmcnt(0)
	s_lshr_b32 s12, s10, 16
	s_and_b32 s10, s10, 0xffff
	s_cmp_lg_u32 s10, 0
	s_cselect_b64 s[10:11], -1, 0
	s_cmp_lg_u64 s[10:11], 0
	s_addc_u32 s10, s31, 0
	s_cmp_lg_u32 s12, 0
	s_mul_i32 s35, s10, s30
	s_cselect_b64 s[10:11], -1, 0
	s_cmp_lg_u64 s[10:11], 0
	s_addc_u32 s10, s72, 0
	s_mul_i32 s35, s35, s10
	s_add_u32 s10, s8, 0xc8200
	s_addc_u32 s11, s9, 0
	s_add_u32 s12, s8, 0xc8400
	s_addc_u32 s13, s9, 0
	s_add_u32 s14, s8, 0xc8500
	s_addc_u32 s15, s9, 0
	s_add_u32 s16, s8, 0xc8600
	s_addc_u32 s17, s9, 0
	s_add_u32 s18, s8, 0xc8700
	s_addc_u32 s19, s9, 0
	s_add_u32 s20, s8, 0xc8800
	s_addc_u32 s21, s9, 0
	s_add_u32 s22, s8, 0xc8900
	s_addc_u32 s23, s9, 0
	s_add_u32 s26, s8, 0xc8a00
	s_addc_u32 s27, s9, 0
	s_add_u32 s36, s8, 0xc8b00
	s_addc_u32 s37, s9, 0
	s_add_u32 s38, s8, 0xc8c00
	s_addc_u32 s39, s9, 0
	s_add_u32 s40, s8, 0xc8d00
	s_addc_u32 s41, s9, 0
	s_add_u32 s42, s8, 0xc8e00
	s_addc_u32 s43, s9, 0
	s_add_u32 s44, s8, 0xc8f00
	s_addc_u32 s45, s9, 0
	s_add_u32 s46, s8, 0xc9000
	s_addc_u32 s47, s9, 0
	s_add_u32 s48, s8, 0xc9100
	s_addc_u32 s49, s9, 0
	s_add_u32 s50, s8, 0xc9200
	s_addc_u32 s51, s9, 0
	s_add_u32 s52, s8, 0xc9300
	s_addc_u32 s53, s9, 0
	s_branch .LBB0_2404

; #define LAS __attribute__((address_space(3)))
; __device__ __forceinline__ kptr_t kargs() { kptr_t p = (kptr_t)__builtin_amdgcn_kernarg_segment_ptr(); asm volatile("" : "+s"(p)); return p; }
; #define KIN(i) KPTR(const float, i)
; #define KOUT() KPTR(float, 22)
; #define PH_BEGIN() const kptr_t kp = kargs(); unsigned char* const ws = KWS(); (void)ws; int tid_ = threadIdx.x; asm volatile("" : "+v"(tid_)); const int lane = tid_ & 63, wave = __builtin_amdgcn_readfirstlane(tid_ >> 6); \
;     const int gw = blockIdx.x * NWAVES + wave, NGW = gridDim.x * NWAVES; (void)lane; (void)gw; (void)NGW
; __global__ void __launch_bounds__(NTHREADS, 2) mega_fwd(Args a) {
;     extern __shared__ __attribute__((aligned(16))) unsigned char lds_raw[];
;     cg::grid_group grid = cg::this_grid();
;     LAS unsigned char* lds = (LAS unsigned char*)lds_raw;
;     if (threadIdx.x < 2) ((volatile LAS unsigned*)(lds + LDS_BARST))[threadIdx.x] = 0u;
;     __syncthreads();
;     { const kptr_t kp = kargs(); (void)xcd_barrier_post((unsigned*)(KPTR(unsigned char, 23) + CTL_XBAR), (volatile LAS unsigned*)(lds + LDS_BARST)); }
;     { PH_BEGIN(); prologue(kp, (LAS float*)(lds + wave * 16384), gw, NGW, lane); }
;     if (gridDim.y == 0x7fffffffu) grid.sync();
;     xbar(lds);
;     layer_fwd<0>(grid, lds);
;     layer_fwd<1>(grid, lds);
;     { PH_BEGIN(); final_norm(KOUT(), KIN(21), gw, NGW, lane); }
; }
	.amdhsa_kernel _Z8mega_fwd4Args
		.amdhsa_group_segment_fixed_size 0
		.amdhsa_private_segment_fixed_size 0
		.amdhsa_kernarg_size 448
		.amdhsa_user_sgpr_count 2
		.amdhsa_user_sgpr_dispatch_ptr 0
		.amdhsa_user_sgpr_queue_ptr 0
		.amdhsa_user_sgpr_kernarg_segment_ptr 1
		.amdhsa_user_sgpr_dispatch_id 0
		.amdhsa_user_sgpr_kernarg_preload_length 0
		.amdhsa_user_sgpr_kernarg_preload_offset 0
		.amdhsa_user_sgpr_private_segment_size 0
		.amdhsa_uses_dynamic_stack 0
		.amdhsa_enable_private_segment 0
		.amdhsa_system_sgpr_workgroup_id_x 1
		.amdhsa_system_sgpr_workgroup_id_y 0
		.amdhsa_system_sgpr_workgroup_id_z 0
		.amdhsa_system_sgpr_workgroup_info 0
		.amdhsa_system_vgpr_workitem_id 2
		.amdhsa_next_free_vgpr 253
		.amdhsa_next_free_sgpr 102
		.amdhsa_accum_offset 256
		.amdhsa_reserve_vcc 1
		.amdhsa_float_round_mode_32 0
		.amdhsa_float_round_mode_16_64 0
		.amdhsa_float_denorm_mode_32 3
		.amdhsa_float_denorm_mode_16_64 3
		.amdhsa_dx10_clamp 1
		.amdhsa_ieee_mode 1
		.amdhsa_fp16_overflow 0
		.amdhsa_tg_split 0
		.amdhsa_exception_fp_ieee_invalid_op 0
		.amdhsa_exception_fp_denorm_src 0
		.amdhsa_exception_fp_ieee_div_zero 0
		.amdhsa_exception_fp_ieee_overflow 0
		.amdhsa_exception_fp_ieee_underflow 0
		.amdhsa_exception_fp_ieee_inexact 0
		.amdhsa_exception_int_div_zero 0
	.end_amdhsa_kernel

; #define LAS __attribute__((address_space(3)))
; __device__ __forceinline__ kptr_t kargs() { kptr_t p = (kptr_t)__builtin_amdgcn_kernarg_segment_ptr(); asm volatile("" : "+s"(p)); return p; }
; #define KIN(i) KPTR(const float, i)
; #define KOUT() KPTR(float, 22)
; #define PH_BEGIN() const kptr_t kp = kargs(); unsigned char* const ws = KWS(); (void)ws; int tid_ = threadIdx.x; asm volatile("" : "+v"(tid_)); const int lane = tid_ & 63, wave = __builtin_amdgcn_readfirstlane(tid_ >> 6); \
;     const int gw = blockIdx.x * NWAVES + wave, NGW = gridDim.x * NWAVES; (void)lane; (void)gw; (void)NGW
; __global__ void __launch_bounds__(NTHREADS, 2) mega_fwd(Args a) {
;     extern __shared__ __attribute__((aligned(16))) unsigned char lds_raw[];
;     cg::grid_group grid = cg::this_grid();
;     LAS unsigned char* lds = (LAS unsigned char*)lds_raw;
;     if (threadIdx.x < 2) ((volatile LAS unsigned*)(lds + LDS_BARST))[threadIdx.x] = 0u;
;     __syncthreads();
;     { const kptr_t kp = kargs(); (void)xcd_barrier_post((unsigned*)(KPTR(unsigned char, 23) + CTL_XBAR), (volatile LAS unsigned*)(lds + LDS_BARST)); }
;     { PH_BEGIN(); prologue(kp, (LAS float*)(lds + wave * 16384), gw, NGW, lane); }
;     if (gridDim.y == 0x7fffffffu) grid.sync();
;     xbar(lds);
;     layer_fwd<0>(grid, lds);
;     layer_fwd<1>(grid, lds);
;     { PH_BEGIN(); final_norm(KOUT(), KIN(21), gw, NGW, lane); }
; }
amdhsa.kernels:
  - .agpr_count:     0
    .args:
      - .offset:         0
        .size:           192
        .value_kind:     by_value
      - .offset:         192
        .size:           4
        .value_kind:     hidden_block_count_x
      - .offset:         196
        .size:           4
        .value_kind:     hidden_block_count_y
      - .offset:         200
        .size:           4
        .value_kind:     hidden_block_count_z
      - .offset:         204
        .size:           2
        .value_kind:     hidden_group_size_x
      - .offset:         206
        .size:           2
        .value_kind:     hidden_group_size_y
      - .offset:         208
        .size:           2
        .value_kind:     hidden_group_size_z
      - .offset:         210
        .size:           2
        .value_kind:     hidden_remainder_x
      - .offset:         212
        .size:           2
        .value_kind:     hidden_remainder_y
      - .offset:         214
        .size:           2
        .value_kind:     hidden_remainder_z
      - .offset:         232
        .size:           8
        .value_kind:     hidden_global_offset_x
      - .offset:         240
        .size:           8
        .value_kind:     hidden_global_offset_y
      - .offset:         248
        .size:           8
        .value_kind:     hidden_global_offset_z
      - .offset:         256
        .size:           2
        .value_kind:     hidden_grid_dims
      - .offset:         280
        .size:           8
        .value_kind:     hidden_multigrid_sync_arg
      - .offset:         312
        .size:           4
        .value_kind:     hidden_dynamic_lds_size
    .group_segment_fixed_size: 0
    .kernarg_segment_align: 8
    .kernarg_segment_size: 448
    .language:       OpenCL C
    .language_version:
      - 2
      - 0
    .max_flat_workgroup_size: 512
    .name:           _Z8mega_fwd4Args
    .private_segment_fixed_size: 0
    .sgpr_count:     108
    .sgpr_spill_count: 9
    .symbol:         _Z8mega_fwd4Args.kd
    .uniform_work_group_size: 1
    .uses_dynamic_stack: false
    .vgpr_count:     253
    .vgpr_spill_count: 0
    .wavefront_size: 64
